# same as previous version but with every s_setprio flip deleted (A/B of the compiler's per-phase priority flips)
# speedup vs baseline: 1.0585x; 1.0010x over previous
.LBB0_292:
	ds_read_b128 v[152:155], v149
	ds_read_b128 v[156:159], v149 offset:1024
	ds_read_b128 v[160:163], v149 offset:2048
	ds_read_b128 v[164:167], v149 offset:3072
	ds_read_b128 v[168:171], v150
	ds_read_b128 v[172:175], v150 offset:1024
	ds_read_b128 v[176:179], v150 offset:2048
	ds_read_b128 v[180:183], v150 offset:3072
	s_add_u32 s74, s56, 0xfffc0080
	s_addc_u32 s75, s57, -1
	s_cmp_eq_u32 s89, 12
	s_cselect_b32 s87, s21, s75
	s_cselect_b32 s86, s81, s74
	s_cselect_b32 s75, s15, s88
	s_cselect_b32 s74, s82, s83
	v_lshl_add_u64 v[144:145], s[56:57], 0, v[136:137]
	s_add_i32 m0, s55, 0xc000
	ds_read_b128 v[184:187], v151
	ds_read_b128 v[188:191], v151 offset:1024
	ds_read_b128 v[192:195], v151 offset:2048
	ds_read_b128 v[196:199], v151 offset:3072
	ds_read_b128 v[200:203], v151 offset:4096
	ds_read_b128 v[204:207], v151 offset:5120
	ds_read_b128 v[208:211], v151 offset:6144
	ds_read_b128 v[212:215], v151 offset:7168
	global_load_lds_dwordx4 v[144:145], off
	v_lshl_add_u64 v[144:145], s[56:57], 0, v[138:139]
	s_add_i32 m0, s55, 0xe000
	s_nop 0
	global_load_lds_dwordx4 v[144:145], off
	s_waitcnt vmcnt(8)
	s_waitcnt lgkmcnt(0)
	s_barrier
	s_waitcnt lgkmcnt(0)
	v_mfma_f32_16x16x32_bf16 v[124:127], v[152:155], v[184:187], v[124:127]
	v_mfma_f32_16x16x32_bf16 v[120:123], v[160:163], v[184:187], v[120:123]
	v_mfma_f32_16x16x32_bf16 v[112:115], v[152:155], v[192:195], v[112:115]
	v_mfma_f32_16x16x32_bf16 v[104:107], v[160:163], v[192:195], v[104:107]
	v_mfma_f32_16x16x32_bf16 v[96:99], v[152:155], v[200:203], v[96:99]
	v_mfma_f32_16x16x32_bf16 v[88:91], v[160:163], v[200:203], v[88:91]
	v_mfma_f32_16x16x32_bf16 v[80:83], v[152:155], v[208:211], v[80:83]
	v_mfma_f32_16x16x32_bf16 v[72:75], v[160:163], v[208:211], v[72:75]
	v_mfma_f32_16x16x32_bf16 v[124:127], v[156:159], v[188:191], v[124:127]
	v_mfma_f32_16x16x32_bf16 v[120:123], v[164:167], v[188:191], v[120:123]
	v_mfma_f32_16x16x32_bf16 v[112:115], v[156:159], v[196:199], v[112:115]
	v_mfma_f32_16x16x32_bf16 v[104:107], v[164:167], v[196:199], v[104:107]
	v_mfma_f32_16x16x32_bf16 v[96:99], v[156:159], v[204:207], v[96:99]
	v_mfma_f32_16x16x32_bf16 v[88:91], v[164:167], v[204:207], v[88:91]
	v_mfma_f32_16x16x32_bf16 v[80:83], v[156:159], v[212:215], v[80:83]
	v_mfma_f32_16x16x32_bf16 v[72:75], v[164:167], v[212:215], v[72:75]
	v_mfma_f32_16x16x32_bf16 v[116:119], v[168:171], v[184:187], v[116:119]
	v_mfma_f32_16x16x32_bf16 v[108:111], v[176:179], v[184:187], v[108:111]
	v_mfma_f32_16x16x32_bf16 v[100:103], v[168:171], v[192:195], v[100:103]
	v_mfma_f32_16x16x32_bf16 v[92:95], v[176:179], v[192:195], v[92:95]
	v_mfma_f32_16x16x32_bf16 v[84:87], v[168:171], v[200:203], v[84:87]
	v_mfma_f32_16x16x32_bf16 v[76:79], v[176:179], v[200:203], v[76:79]
	v_mfma_f32_16x16x32_bf16 v[68:71], v[168:171], v[208:211], v[68:71]
	v_mfma_f32_16x16x32_bf16 v[64:67], v[176:179], v[208:211], v[64:67]
	v_mfma_f32_16x16x32_bf16 v[116:119], v[172:175], v[188:191], v[116:119]
	v_mfma_f32_16x16x32_bf16 v[108:111], v[180:183], v[188:191], v[108:111]
	v_mfma_f32_16x16x32_bf16 v[100:103], v[172:175], v[196:199], v[100:103]
	v_mfma_f32_16x16x32_bf16 v[92:95], v[180:183], v[196:199], v[92:95]
	v_mfma_f32_16x16x32_bf16 v[84:87], v[172:175], v[204:207], v[84:87]
	v_mfma_f32_16x16x32_bf16 v[76:79], v[180:183], v[204:207], v[76:79]
	v_mfma_f32_16x16x32_bf16 v[68:71], v[172:175], v[212:215], v[68:71]
	v_mfma_f32_16x16x32_bf16 v[64:67], v[180:183], v[212:215], v[64:67]
	s_barrier
	s_add_i32 s90, s77, s52
	v_lshl_add_u64 v[144:145], s[74:75], 0, v[132:133]
	s_mov_b32 m0, s90
	ds_read_b128 v[184:187], v151 offset:16384
	ds_read_b128 v[188:191], v151 offset:17408
	ds_read_b128 v[192:195], v151 offset:18432
	ds_read_b128 v[196:199], v151 offset:19456
	ds_read_b128 v[200:203], v151 offset:20480
	ds_read_b128 v[204:207], v151 offset:21504
	ds_read_b128 v[208:211], v151 offset:22528
	ds_read_b128 v[212:215], v151 offset:23552
	global_load_lds_dwordx4 v[144:145], off
	s_add_i32 m0, s90, 0x2000
	s_add_u32 s90, s74, 0x40000
	v_lshl_add_u64 v[216:217], s[74:75], 0, v[128:129]
	s_addc_u32 s91, s75, 0
	s_add_i32 s92, s78, s52
	global_load_lds_dwordx4 v[216:217], off
	v_lshl_add_u64 v[218:219], s[90:91], 0, v[132:133]
	s_mov_b32 m0, s92
	v_lshl_add_u64 v[220:221], s[86:87], 0, v[130:131]
	global_load_lds_dwordx4 v[218:219], off
	v_lshl_add_u64 v[218:219], s[90:91], 0, v[128:129]
	s_add_i32 m0, s92, 0x2000
	s_nop 0
	global_load_lds_dwordx4 v[218:219], off
	v_lshl_add_u64 v[218:219], s[86:87], 0, v[134:135]
	s_mov_b32 m0, s55
	s_nop 0
	global_load_lds_dwordx4 v[218:219], off
	s_mov_b32 m0, s61
	s_nop 0
	global_load_lds_dwordx4 v[220:221], off
	s_waitcnt vmcnt(8)
	s_waitcnt lgkmcnt(0)
	s_barrier
	s_waitcnt lgkmcnt(0)
	v_mfma_f32_16x16x32_bf16 v[60:63], v[152:155], v[184:187], v[60:63]
	v_mfma_f32_16x16x32_bf16 v[56:59], v[160:163], v[184:187], v[56:59]
	v_mfma_f32_16x16x32_bf16 v[48:51], v[152:155], v[192:195], v[48:51]
	v_mfma_f32_16x16x32_bf16 v[40:43], v[160:163], v[192:195], v[40:43]
	v_mfma_f32_16x16x32_bf16 v[32:35], v[152:155], v[200:203], v[32:35]
	v_mfma_f32_16x16x32_bf16 v[24:27], v[160:163], v[200:203], v[24:27]
	v_mfma_f32_16x16x32_bf16 v[16:19], v[152:155], v[208:211], v[16:19]
	v_mfma_f32_16x16x32_bf16 v[8:11], v[160:163], v[208:211], v[8:11]
	v_mfma_f32_16x16x32_bf16 v[60:63], v[156:159], v[188:191], v[60:63]
	v_mfma_f32_16x16x32_bf16 v[56:59], v[164:167], v[188:191], v[56:59]
	v_mfma_f32_16x16x32_bf16 v[48:51], v[156:159], v[196:199], v[48:51]
	v_mfma_f32_16x16x32_bf16 v[40:43], v[164:167], v[196:199], v[40:43]
	v_mfma_f32_16x16x32_bf16 v[32:35], v[156:159], v[204:207], v[32:35]
	v_mfma_f32_16x16x32_bf16 v[24:27], v[164:167], v[204:207], v[24:27]
	v_mfma_f32_16x16x32_bf16 v[16:19], v[156:159], v[212:215], v[16:19]
	v_mfma_f32_16x16x32_bf16 v[8:11], v[164:167], v[212:215], v[8:11]
	v_mfma_f32_16x16x32_bf16 v[52:55], v[168:171], v[184:187], v[52:55]
	v_mfma_f32_16x16x32_bf16 v[44:47], v[176:179], v[184:187], v[44:47]
	v_mfma_f32_16x16x32_bf16 v[36:39], v[168:171], v[192:195], v[36:39]
	v_mfma_f32_16x16x32_bf16 v[28:31], v[176:179], v[192:195], v[28:31]
	v_mfma_f32_16x16x32_bf16 v[20:23], v[168:171], v[200:203], v[20:23]
	v_mfma_f32_16x16x32_bf16 v[12:15], v[176:179], v[200:203], v[12:15]
	v_mfma_f32_16x16x32_bf16 v[4:7], v[168:171], v[208:211], v[4:7]
	v_mfma_f32_16x16x32_bf16 v[0:3], v[176:179], v[208:211], v[0:3]
	v_mfma_f32_16x16x32_bf16 v[52:55], v[172:175], v[188:191], v[52:55]
	v_mfma_f32_16x16x32_bf16 v[44:47], v[180:183], v[188:191], v[44:47]
	v_mfma_f32_16x16x32_bf16 v[36:39], v[172:175], v[196:199], v[36:39]
	v_mfma_f32_16x16x32_bf16 v[28:31], v[180:183], v[196:199], v[28:31]
	v_mfma_f32_16x16x32_bf16 v[20:23], v[172:175], v[204:207], v[20:23]
	v_mfma_f32_16x16x32_bf16 v[12:15], v[180:183], v[204:207], v[12:15]
	v_mfma_f32_16x16x32_bf16 v[4:7], v[172:175], v[212:215], v[4:7]
	v_mfma_f32_16x16x32_bf16 v[0:3], v[180:183], v[212:215], v[0:3]
	s_barrier
	s_add_i32 s90, 0, 0x18000
	s_add_i32 s91, 0, 0x1c000
	v_add_u32_e32 v164, s90, v147
	v_add_u32_e32 v180, s91, v147
	ds_read_b128 v[152:155], v164
	ds_read_b128 v[156:159], v164 offset:1024
	ds_read_b128 v[160:163], v164 offset:2048
	ds_read_b128 v[164:167], v164 offset:3072
	ds_read_b128 v[168:171], v180
	ds_read_b128 v[172:175], v180 offset:1024
	ds_read_b128 v[176:179], v180 offset:2048
	ds_read_b128 v[180:183], v180 offset:3072
	s_add_u32 s86, s86, 0x40000
	s_addc_u32 s87, s87, 0
	s_mov_b32 m0, s62
	v_lshl_add_u64 v[222:223], s[86:87], 0, v[134:135]
	ds_read_b128 v[184:187], v151 offset:32768
	ds_read_b128 v[188:191], v151 offset:33792
	ds_read_b128 v[192:195], v151 offset:34816
	ds_read_b128 v[196:199], v151 offset:35840
	ds_read_b128 v[200:203], v151 offset:36864
	ds_read_b128 v[204:207], v151 offset:37888
	ds_read_b128 v[208:211], v151 offset:38912
	ds_read_b128 v[212:215], v151 offset:39936
	global_load_lds_dwordx4 v[222:223], off
	v_lshl_add_u64 v[222:223], s[86:87], 0, v[130:131]
	s_mov_b32 m0, s63
	s_nop 0
	global_load_lds_dwordx4 v[222:223], off
	s_waitcnt vmcnt(8)
	s_waitcnt lgkmcnt(0)
	s_barrier
	s_waitcnt lgkmcnt(0)
	v_mfma_f32_16x16x32_bf16 v[124:127], v[152:155], v[184:187], v[124:127]
	v_mfma_f32_16x16x32_bf16 v[120:123], v[160:163], v[184:187], v[120:123]
	v_mfma_f32_16x16x32_bf16 v[112:115], v[152:155], v[192:195], v[112:115]
	v_mfma_f32_16x16x32_bf16 v[104:107], v[160:163], v[192:195], v[104:107]
	v_mfma_f32_16x16x32_bf16 v[96:99], v[152:155], v[200:203], v[96:99]
	v_mfma_f32_16x16x32_bf16 v[88:91], v[160:163], v[200:203], v[88:91]
	v_mfma_f32_16x16x32_bf16 v[80:83], v[152:155], v[208:211], v[80:83]
	v_mfma_f32_16x16x32_bf16 v[72:75], v[160:163], v[208:211], v[72:75]
	v_mfma_f32_16x16x32_bf16 v[124:127], v[156:159], v[188:191], v[124:127]
	v_mfma_f32_16x16x32_bf16 v[120:123], v[164:167], v[188:191], v[120:123]
	v_mfma_f32_16x16x32_bf16 v[112:115], v[156:159], v[196:199], v[112:115]
	v_mfma_f32_16x16x32_bf16 v[104:107], v[164:167], v[196:199], v[104:107]
	v_mfma_f32_16x16x32_bf16 v[96:99], v[156:159], v[204:207], v[96:99]
	v_mfma_f32_16x16x32_bf16 v[88:91], v[164:167], v[204:207], v[88:91]
	v_mfma_f32_16x16x32_bf16 v[80:83], v[156:159], v[212:215], v[80:83]
	v_mfma_f32_16x16x32_bf16 v[72:75], v[164:167], v[212:215], v[72:75]
	v_mfma_f32_16x16x32_bf16 v[116:119], v[168:171], v[184:187], v[116:119]
	v_mfma_f32_16x16x32_bf16 v[108:111], v[176:179], v[184:187], v[108:111]
	v_mfma_f32_16x16x32_bf16 v[100:103], v[168:171], v[192:195], v[100:103]
	v_mfma_f32_16x16x32_bf16 v[92:95], v[176:179], v[192:195], v[92:95]
	v_mfma_f32_16x16x32_bf16 v[84:87], v[168:171], v[200:203], v[84:87]
	v_mfma_f32_16x16x32_bf16 v[76:79], v[176:179], v[200:203], v[76:79]
	v_mfma_f32_16x16x32_bf16 v[68:71], v[168:171], v[208:211], v[68:71]
	v_mfma_f32_16x16x32_bf16 v[64:67], v[176:179], v[208:211], v[64:67]
	v_mfma_f32_16x16x32_bf16 v[116:119], v[172:175], v[188:191], v[116:119]
	v_mfma_f32_16x16x32_bf16 v[108:111], v[180:183], v[188:191], v[108:111]
	v_mfma_f32_16x16x32_bf16 v[100:103], v[172:175], v[196:199], v[100:103]
	v_mfma_f32_16x16x32_bf16 v[92:95], v[180:183], v[196:199], v[92:95]
	v_mfma_f32_16x16x32_bf16 v[84:87], v[172:175], v[204:207], v[84:87]
	v_mfma_f32_16x16x32_bf16 v[76:79], v[180:183], v[204:207], v[76:79]
	v_mfma_f32_16x16x32_bf16 v[68:71], v[172:175], v[212:215], v[68:71]
	v_mfma_f32_16x16x32_bf16 v[64:67], v[180:183], v[212:215], v[64:67]
	s_barrier
	s_add_i32 s86, s90, s52
	v_lshl_add_u64 v[144:145], v[144:145], 0, s[10:11]
	s_mov_b32 m0, s86
	ds_read_b128 v[184:187], v151 offset:49152
	ds_read_b128 v[188:191], v151 offset:50176
	ds_read_b128 v[192:195], v151 offset:51200
	ds_read_b128 v[196:199], v151 offset:52224
	ds_read_b128 v[200:203], v151 offset:53248
	ds_read_b128 v[204:207], v151 offset:54272
	ds_read_b128 v[208:211], v151 offset:55296
	ds_read_b128 v[212:215], v151 offset:56320
	global_load_lds_dwordx4 v[144:145], off
	s_add_i32 m0, s86, 0x2000
	s_add_u32 s74, s74, 0x40080
	v_lshl_add_u64 v[144:145], v[216:217], 0, s[10:11]
	s_addc_u32 s75, s75, 0
	s_add_i32 s86, s91, s52
	global_load_lds_dwordx4 v[144:145], off
	v_lshl_add_u64 v[144:145], s[74:75], 0, v[132:133]
	s_mov_b32 m0, s86
	s_nop 0
	global_load_lds_dwordx4 v[144:145], off
	v_lshl_add_u64 v[144:145], s[74:75], 0, v[128:129]
	s_add_i32 m0, s86, 0x2000
	s_nop 0
	global_load_lds_dwordx4 v[144:145], off
	v_lshl_add_u64 v[144:145], v[218:219], 0, s[10:11]
	s_mov_b32 m0, s66
	s_nop 0
	global_load_lds_dwordx4 v[144:145], off
	v_lshl_add_u64 v[144:145], v[220:221], 0, s[10:11]
	s_mov_b32 m0, s67
	s_nop 0
	global_load_lds_dwordx4 v[144:145], off
	s_waitcnt vmcnt(8)
	s_waitcnt lgkmcnt(0)
	s_barrier
	s_waitcnt lgkmcnt(0)
	v_mfma_f32_16x16x32_bf16 v[60:63], v[152:155], v[184:187], v[60:63]
	v_mfma_f32_16x16x32_bf16 v[56:59], v[160:163], v[184:187], v[56:59]
	v_mfma_f32_16x16x32_bf16 v[48:51], v[152:155], v[192:195], v[48:51]
	v_mfma_f32_16x16x32_bf16 v[40:43], v[160:163], v[192:195], v[40:43]
	v_mfma_f32_16x16x32_bf16 v[32:35], v[152:155], v[200:203], v[32:35]
	v_mfma_f32_16x16x32_bf16 v[24:27], v[160:163], v[200:203], v[24:27]
	v_mfma_f32_16x16x32_bf16 v[16:19], v[152:155], v[208:211], v[16:19]
	v_mfma_f32_16x16x32_bf16 v[8:11], v[160:163], v[208:211], v[8:11]
	v_mfma_f32_16x16x32_bf16 v[60:63], v[156:159], v[188:191], v[60:63]
	v_mfma_f32_16x16x32_bf16 v[56:59], v[164:167], v[188:191], v[56:59]
	v_mfma_f32_16x16x32_bf16 v[48:51], v[156:159], v[196:199], v[48:51]
	v_mfma_f32_16x16x32_bf16 v[40:43], v[164:167], v[196:199], v[40:43]
	v_mfma_f32_16x16x32_bf16 v[32:35], v[156:159], v[204:207], v[32:35]
	v_mfma_f32_16x16x32_bf16 v[24:27], v[164:167], v[204:207], v[24:27]
	v_mfma_f32_16x16x32_bf16 v[16:19], v[156:159], v[212:215], v[16:19]
	v_mfma_f32_16x16x32_bf16 v[8:11], v[164:167], v[212:215], v[8:11]
	v_mfma_f32_16x16x32_bf16 v[52:55], v[168:171], v[184:187], v[52:55]
	v_mfma_f32_16x16x32_bf16 v[44:47], v[176:179], v[184:187], v[44:47]
	v_mfma_f32_16x16x32_bf16 v[36:39], v[168:171], v[192:195], v[36:39]
	v_mfma_f32_16x16x32_bf16 v[28:31], v[176:179], v[192:195], v[28:31]
	v_mfma_f32_16x16x32_bf16 v[20:23], v[168:171], v[200:203], v[20:23]
	v_mfma_f32_16x16x32_bf16 v[12:15], v[176:179], v[200:203], v[12:15]
	v_mfma_f32_16x16x32_bf16 v[4:7], v[168:171], v[208:211], v[4:7]
	v_mfma_f32_16x16x32_bf16 v[0:3], v[176:179], v[208:211], v[0:3]
	v_mfma_f32_16x16x32_bf16 v[52:55], v[172:175], v[188:191], v[52:55]
	v_mfma_f32_16x16x32_bf16 v[44:47], v[180:183], v[188:191], v[44:47]
	v_mfma_f32_16x16x32_bf16 v[36:39], v[172:175], v[196:199], v[36:39]
	v_mfma_f32_16x16x32_bf16 v[28:31], v[180:183], v[196:199], v[28:31]
	v_mfma_f32_16x16x32_bf16 v[20:23], v[172:175], v[204:207], v[20:23]
	v_mfma_f32_16x16x32_bf16 v[12:15], v[180:183], v[204:207], v[12:15]
	v_mfma_f32_16x16x32_bf16 v[4:7], v[172:175], v[212:215], v[4:7]
	v_mfma_f32_16x16x32_bf16 v[0:3], v[180:183], v[212:215], v[0:3]
	s_barrier
	s_add_i32 s89, s89, 2
	s_add_u32 s56, s56, 0x100
	s_addc_u32 s57, s57, 0
	s_add_u32 s83, s83, 0x100
	s_addc_u32 s88, s88, 0
	s_cmp_gt_u32 s89, 13
	s_cbranch_scc0 .LBB0_292
	s_and_b64 vcc, exec, s[12:13]
	s_cbranch_vccz .LBB0_295
	s_barrier

.LBB0_737:
	v_add_u32_e32 v176, s95, v178
	ds_read_b128 v[172:175], v176
	ds_read_b128 v[182:185], v176 offset:1024
	ds_read_b128 v[186:189], v176 offset:2048
	ds_read_b128 v[190:193], v176 offset:3072
	v_add_u32_e32 v176, s96, v178
	ds_read_b128 v[194:197], v176
	ds_read_b128 v[198:201], v176 offset:1024
	ds_read_b128 v[202:205], v176 offset:2048
	ds_read_b128 v[206:209], v176 offset:3072
	s_add_u32 s79, s86, 0xfffc0080
	s_addc_u32 s88, s87, -1
	s_cmp_eq_u32 s78, 12
	s_cselect_b32 s91, s8, s88
	s_cselect_b32 s90, s35, s79
	s_cselect_b32 s89, s31, s77
	s_cselect_b32 s88, s75, s76
	v_lshl_add_u64 v[176:177], s[86:87], 0, v[164:165]
	s_add_i32 m0, s59, 0xc000
	ds_read_b128 v[210:213], v180
	ds_read_b128 v[214:217], v180 offset:1024
	ds_read_b128 v[218:221], v180 offset:2048
	ds_read_b128 v[222:225], v180 offset:3072
	ds_read_b128 v[226:229], v180 offset:4096
	ds_read_b128 v[232:235], v180 offset:5120
	ds_read_b128 v[236:239], v180 offset:6144
	ds_read_b128 v[240:243], v180 offset:7168
	global_load_lds_dwordx4 v[176:177], off
	v_lshl_add_u64 v[176:177], s[86:87], 0, v[166:167]
	s_add_i32 m0, s59, 0xe000
	s_nop 0
	global_load_lds_dwordx4 v[176:177], off
	s_waitcnt vmcnt(8)
	s_waitcnt lgkmcnt(0)
	s_barrier
	s_waitcnt lgkmcnt(0)
	v_mfma_f32_16x16x32_bf16 v[124:127], v[172:175], v[210:213], v[124:127]
	v_mfma_f32_16x16x32_bf16 v[120:123], v[186:189], v[210:213], v[120:123]
	v_mfma_f32_16x16x32_bf16 v[108:111], v[172:175], v[218:221], v[108:111]
	v_mfma_f32_16x16x32_bf16 v[104:107], v[186:189], v[218:221], v[104:107]
	v_mfma_f32_16x16x32_bf16 v[92:95], v[172:175], v[226:229], v[92:95]
	v_mfma_f32_16x16x32_bf16 v[88:91], v[186:189], v[226:229], v[88:91]
	v_mfma_f32_16x16x32_bf16 v[76:79], v[172:175], v[236:239], v[76:79]
	v_mfma_f32_16x16x32_bf16 v[72:75], v[186:189], v[236:239], v[72:75]
	v_mfma_f32_16x16x32_bf16 v[124:127], v[182:185], v[214:217], v[124:127]
	v_mfma_f32_16x16x32_bf16 v[120:123], v[190:193], v[214:217], v[120:123]
	v_mfma_f32_16x16x32_bf16 v[108:111], v[182:185], v[222:225], v[108:111]
	v_mfma_f32_16x16x32_bf16 v[104:107], v[190:193], v[222:225], v[104:107]
	v_mfma_f32_16x16x32_bf16 v[92:95], v[182:185], v[232:235], v[92:95]
	v_mfma_f32_16x16x32_bf16 v[88:91], v[190:193], v[232:235], v[88:91]
	v_mfma_f32_16x16x32_bf16 v[76:79], v[182:185], v[240:243], v[76:79]
	v_mfma_f32_16x16x32_bf16 v[72:75], v[190:193], v[240:243], v[72:75]
	v_mfma_f32_16x16x32_bf16 v[116:119], v[194:197], v[210:213], v[116:119]
	v_mfma_f32_16x16x32_bf16 v[112:115], v[202:205], v[210:213], v[112:115]
	v_mfma_f32_16x16x32_bf16 v[100:103], v[194:197], v[218:221], v[100:103]
	v_mfma_f32_16x16x32_bf16 v[96:99], v[202:205], v[218:221], v[96:99]
	v_mfma_f32_16x16x32_bf16 v[84:87], v[194:197], v[226:229], v[84:87]
	v_mfma_f32_16x16x32_bf16 v[80:83], v[202:205], v[226:229], v[80:83]
	v_mfma_f32_16x16x32_bf16 v[68:71], v[194:197], v[236:239], v[68:71]
	v_mfma_f32_16x16x32_bf16 v[64:67], v[202:205], v[236:239], v[64:67]
	v_mfma_f32_16x16x32_bf16 v[116:119], v[198:201], v[214:217], v[116:119]
	v_mfma_f32_16x16x32_bf16 v[112:115], v[206:209], v[214:217], v[112:115]
	v_mfma_f32_16x16x32_bf16 v[100:103], v[198:201], v[222:225], v[100:103]
	v_mfma_f32_16x16x32_bf16 v[96:99], v[206:209], v[222:225], v[96:99]
	v_mfma_f32_16x16x32_bf16 v[84:87], v[198:201], v[232:235], v[84:87]
	v_mfma_f32_16x16x32_bf16 v[80:83], v[206:209], v[232:235], v[80:83]
	v_mfma_f32_16x16x32_bf16 v[68:71], v[198:201], v[240:243], v[68:71]
	v_mfma_f32_16x16x32_bf16 v[64:67], v[206:209], v[240:243], v[64:67]
	s_barrier
	s_add_i32 s79, s95, s52
	v_lshl_add_u64 v[176:177], s[88:89], 0, v[128:129]
	s_mov_b32 m0, s79
	ds_read_b128 v[210:213], v180 offset:16384
	ds_read_b128 v[214:217], v180 offset:17408
	ds_read_b128 v[218:221], v180 offset:18432
	ds_read_b128 v[222:225], v180 offset:19456
	ds_read_b128 v[226:229], v180 offset:20480
	ds_read_b128 v[232:235], v180 offset:21504
	ds_read_b128 v[236:239], v180 offset:22528
	ds_read_b128 v[240:243], v180 offset:23552
	global_load_lds_dwordx4 v[176:177], off
	s_add_i32 m0, s79, 0x2000
	s_add_u32 vcc_lo, s88, 0x40000
	v_lshl_add_u64 v[244:245], s[88:89], 0, v[130:131]
	s_addc_u32 vcc_hi, s89, 0
	s_add_i32 s79, s96, s52
	global_load_lds_dwordx4 v[244:245], off
	v_lshl_add_u64 v[246:247], vcc, 0, v[128:129]
	s_mov_b32 m0, s79
	v_lshl_add_u64 v[248:249], s[90:91], 0, v[130:131]
	global_load_lds_dwordx4 v[246:247], off
	v_lshl_add_u64 v[246:247], vcc, 0, v[130:131]
	s_add_i32 m0, s79, 0x2000
	s_nop 0
	global_load_lds_dwordx4 v[246:247], off
	v_lshl_add_u64 v[246:247], s[90:91], 0, v[128:129]
	s_mov_b32 m0, s59
	s_nop 0
	global_load_lds_dwordx4 v[246:247], off
	s_mov_b32 m0, s60
	s_nop 0
	global_load_lds_dwordx4 v[248:249], off
	s_waitcnt vmcnt(8)
	s_waitcnt lgkmcnt(0)
	s_barrier
	s_waitcnt lgkmcnt(0)
	v_mfma_f32_16x16x32_bf16 v[60:63], v[172:175], v[210:213], v[60:63]
	v_mfma_f32_16x16x32_bf16 v[56:59], v[186:189], v[210:213], v[56:59]
	v_mfma_f32_16x16x32_bf16 v[44:47], v[172:175], v[218:221], v[44:47]
	v_mfma_f32_16x16x32_bf16 v[40:43], v[186:189], v[218:221], v[40:43]
	v_mfma_f32_16x16x32_bf16 v[28:31], v[172:175], v[226:229], v[28:31]
	v_mfma_f32_16x16x32_bf16 v[24:27], v[186:189], v[226:229], v[24:27]
	v_mfma_f32_16x16x32_bf16 v[12:15], v[172:175], v[236:239], v[12:15]
	v_mfma_f32_16x16x32_bf16 v[8:11], v[186:189], v[236:239], v[8:11]
	v_mfma_f32_16x16x32_bf16 v[60:63], v[182:185], v[214:217], v[60:63]
	v_mfma_f32_16x16x32_bf16 v[56:59], v[190:193], v[214:217], v[56:59]
	v_mfma_f32_16x16x32_bf16 v[44:47], v[182:185], v[222:225], v[44:47]
	v_mfma_f32_16x16x32_bf16 v[40:43], v[190:193], v[222:225], v[40:43]
	v_mfma_f32_16x16x32_bf16 v[28:31], v[182:185], v[232:235], v[28:31]
	v_mfma_f32_16x16x32_bf16 v[24:27], v[190:193], v[232:235], v[24:27]
	v_mfma_f32_16x16x32_bf16 v[12:15], v[182:185], v[240:243], v[12:15]
	v_mfma_f32_16x16x32_bf16 v[8:11], v[190:193], v[240:243], v[8:11]
	v_mfma_f32_16x16x32_bf16 v[52:55], v[194:197], v[210:213], v[52:55]
	v_mfma_f32_16x16x32_bf16 v[48:51], v[202:205], v[210:213], v[48:51]
	v_mfma_f32_16x16x32_bf16 v[36:39], v[194:197], v[218:221], v[36:39]
	v_mfma_f32_16x16x32_bf16 v[32:35], v[202:205], v[218:221], v[32:35]
	v_mfma_f32_16x16x32_bf16 v[20:23], v[194:197], v[226:229], v[20:23]
	v_mfma_f32_16x16x32_bf16 v[16:19], v[202:205], v[226:229], v[16:19]
	v_mfma_f32_16x16x32_bf16 v[4:7], v[194:197], v[236:239], v[4:7]
	v_mfma_f32_16x16x32_bf16 v[0:3], v[202:205], v[236:239], v[0:3]
	v_mfma_f32_16x16x32_bf16 v[52:55], v[198:201], v[214:217], v[52:55]
	v_mfma_f32_16x16x32_bf16 v[48:51], v[206:209], v[214:217], v[48:51]
	v_mfma_f32_16x16x32_bf16 v[36:39], v[198:201], v[222:225], v[36:39]
	v_mfma_f32_16x16x32_bf16 v[32:35], v[206:209], v[222:225], v[32:35]
	v_mfma_f32_16x16x32_bf16 v[20:23], v[198:201], v[232:235], v[20:23]
	v_mfma_f32_16x16x32_bf16 v[16:19], v[206:209], v[232:235], v[16:19]
	v_mfma_f32_16x16x32_bf16 v[4:7], v[198:201], v[240:243], v[4:7]
	v_mfma_f32_16x16x32_bf16 v[0:3], v[206:209], v[240:243], v[0:3]
	s_barrier
	s_add_i32 s79, 0, 0x18000
	s_add_i32 vcc_lo, 0, 0x1c000
	v_add_u32_e32 v190, s79, v178
	v_add_u32_e32 v206, vcc_lo, v178
	ds_read_b128 v[172:175], v190
	ds_read_b128 v[182:185], v190 offset:1024
	ds_read_b128 v[186:189], v190 offset:2048
	ds_read_b128 v[190:193], v190 offset:3072
	ds_read_b128 v[194:197], v206
	ds_read_b128 v[198:201], v206 offset:1024
	ds_read_b128 v[202:205], v206 offset:2048
	ds_read_b128 v[206:209], v206 offset:3072
	s_add_u32 s90, s90, 0x40000
	s_addc_u32 s91, s91, 0
	s_mov_b32 m0, s61
	v_lshl_add_u64 v[250:251], s[90:91], 0, v[128:129]
	ds_read_b128 v[210:213], v180 offset:32768
	ds_read_b128 v[214:217], v180 offset:33792
	ds_read_b128 v[218:221], v180 offset:34816
	ds_read_b128 v[222:225], v180 offset:35840
	ds_read_b128 v[226:229], v180 offset:36864
	ds_read_b128 v[232:235], v180 offset:37888
	ds_read_b128 v[236:239], v180 offset:38912
	ds_read_b128 v[240:243], v180 offset:39936
	global_load_lds_dwordx4 v[250:251], off
	v_lshl_add_u64 v[250:251], s[90:91], 0, v[130:131]
	s_mov_b32 m0, s62
	s_nop 0
	global_load_lds_dwordx4 v[250:251], off
	s_waitcnt vmcnt(8)
	s_waitcnt lgkmcnt(0)
	s_barrier
	s_waitcnt lgkmcnt(0)
	v_mfma_f32_16x16x32_bf16 v[124:127], v[172:175], v[210:213], v[124:127]
	v_mfma_f32_16x16x32_bf16 v[120:123], v[186:189], v[210:213], v[120:123]
	v_mfma_f32_16x16x32_bf16 v[108:111], v[172:175], v[218:221], v[108:111]
	v_mfma_f32_16x16x32_bf16 v[104:107], v[186:189], v[218:221], v[104:107]
	v_mfma_f32_16x16x32_bf16 v[92:95], v[172:175], v[226:229], v[92:95]
	v_mfma_f32_16x16x32_bf16 v[88:91], v[186:189], v[226:229], v[88:91]
	v_mfma_f32_16x16x32_bf16 v[76:79], v[172:175], v[236:239], v[76:79]
	v_mfma_f32_16x16x32_bf16 v[72:75], v[186:189], v[236:239], v[72:75]
	v_mfma_f32_16x16x32_bf16 v[124:127], v[182:185], v[214:217], v[124:127]
	v_mfma_f32_16x16x32_bf16 v[120:123], v[190:193], v[214:217], v[120:123]
	v_mfma_f32_16x16x32_bf16 v[108:111], v[182:185], v[222:225], v[108:111]
	v_mfma_f32_16x16x32_bf16 v[104:107], v[190:193], v[222:225], v[104:107]
	v_mfma_f32_16x16x32_bf16 v[92:95], v[182:185], v[232:235], v[92:95]
	v_mfma_f32_16x16x32_bf16 v[88:91], v[190:193], v[232:235], v[88:91]
	v_mfma_f32_16x16x32_bf16 v[76:79], v[182:185], v[240:243], v[76:79]
	v_mfma_f32_16x16x32_bf16 v[72:75], v[190:193], v[240:243], v[72:75]
	v_mfma_f32_16x16x32_bf16 v[116:119], v[194:197], v[210:213], v[116:119]
	v_mfma_f32_16x16x32_bf16 v[112:115], v[202:205], v[210:213], v[112:115]
	v_mfma_f32_16x16x32_bf16 v[100:103], v[194:197], v[218:221], v[100:103]
	v_mfma_f32_16x16x32_bf16 v[96:99], v[202:205], v[218:221], v[96:99]
	v_mfma_f32_16x16x32_bf16 v[84:87], v[194:197], v[226:229], v[84:87]
	v_mfma_f32_16x16x32_bf16 v[80:83], v[202:205], v[226:229], v[80:83]
	v_mfma_f32_16x16x32_bf16 v[68:71], v[194:197], v[236:239], v[68:71]
	v_mfma_f32_16x16x32_bf16 v[64:67], v[202:205], v[236:239], v[64:67]
	v_mfma_f32_16x16x32_bf16 v[116:119], v[198:201], v[214:217], v[116:119]
	v_mfma_f32_16x16x32_bf16 v[112:115], v[206:209], v[214:217], v[112:115]
	v_mfma_f32_16x16x32_bf16 v[100:103], v[198:201], v[222:225], v[100:103]
	v_mfma_f32_16x16x32_bf16 v[96:99], v[206:209], v[222:225], v[96:99]
	v_mfma_f32_16x16x32_bf16 v[84:87], v[198:201], v[232:235], v[84:87]
	v_mfma_f32_16x16x32_bf16 v[80:83], v[206:209], v[232:235], v[80:83]
	v_mfma_f32_16x16x32_bf16 v[68:71], v[198:201], v[240:243], v[68:71]
	v_mfma_f32_16x16x32_bf16 v[64:67], v[206:209], v[240:243], v[64:67]
	s_barrier
	s_add_i32 s79, s79, s52
	v_lshl_add_u64 v[176:177], v[176:177], 0, s[14:15]
	s_mov_b32 m0, s79
	ds_read_b128 v[210:213], v180 offset:49152
	ds_read_b128 v[214:217], v180 offset:50176
	ds_read_b128 v[218:221], v180 offset:51200
	ds_read_b128 v[222:225], v180 offset:52224
	ds_read_b128 v[226:229], v180 offset:53248
	ds_read_b128 v[232:235], v180 offset:54272
	ds_read_b128 v[236:239], v180 offset:55296
	ds_read_b128 v[240:243], v180 offset:56320
	global_load_lds_dwordx4 v[176:177], off
	s_add_i32 m0, s79, 0x2000
	s_add_u32 s88, s88, 0x40080
	v_lshl_add_u64 v[176:177], v[244:245], 0, s[14:15]
	s_addc_u32 s89, s89, 0
	s_add_i32 s79, vcc_lo, s52
	global_load_lds_dwordx4 v[176:177], off
	v_lshl_add_u64 v[176:177], s[88:89], 0, v[128:129]
	s_mov_b32 m0, s79
	s_nop 0
	global_load_lds_dwordx4 v[176:177], off
	v_lshl_add_u64 v[176:177], s[88:89], 0, v[130:131]
	s_add_i32 m0, s79, 0x2000
	s_nop 0
	global_load_lds_dwordx4 v[176:177], off
	v_lshl_add_u64 v[176:177], v[246:247], 0, s[14:15]
	s_mov_b32 m0, s81
	s_nop 0
	global_load_lds_dwordx4 v[176:177], off
	v_lshl_add_u64 v[176:177], v[248:249], 0, s[14:15]
	s_mov_b32 m0, s82
	s_nop 0
	global_load_lds_dwordx4 v[176:177], off
	s_waitcnt vmcnt(8)
	s_waitcnt lgkmcnt(0)
	s_barrier
	s_waitcnt lgkmcnt(0)
	v_mfma_f32_16x16x32_bf16 v[60:63], v[172:175], v[210:213], v[60:63]
	v_mfma_f32_16x16x32_bf16 v[56:59], v[186:189], v[210:213], v[56:59]
	v_mfma_f32_16x16x32_bf16 v[44:47], v[172:175], v[218:221], v[44:47]
	v_mfma_f32_16x16x32_bf16 v[40:43], v[186:189], v[218:221], v[40:43]
	v_mfma_f32_16x16x32_bf16 v[28:31], v[172:175], v[226:229], v[28:31]
	v_mfma_f32_16x16x32_bf16 v[24:27], v[186:189], v[226:229], v[24:27]
	v_mfma_f32_16x16x32_bf16 v[12:15], v[172:175], v[236:239], v[12:15]
	v_mfma_f32_16x16x32_bf16 v[8:11], v[186:189], v[236:239], v[8:11]
	v_mfma_f32_16x16x32_bf16 v[60:63], v[182:185], v[214:217], v[60:63]
	v_mfma_f32_16x16x32_bf16 v[56:59], v[190:193], v[214:217], v[56:59]
	v_mfma_f32_16x16x32_bf16 v[44:47], v[182:185], v[222:225], v[44:47]
	v_mfma_f32_16x16x32_bf16 v[40:43], v[190:193], v[222:225], v[40:43]
	v_mfma_f32_16x16x32_bf16 v[28:31], v[182:185], v[232:235], v[28:31]
	v_mfma_f32_16x16x32_bf16 v[24:27], v[190:193], v[232:235], v[24:27]
	v_mfma_f32_16x16x32_bf16 v[12:15], v[182:185], v[240:243], v[12:15]
	v_mfma_f32_16x16x32_bf16 v[8:11], v[190:193], v[240:243], v[8:11]
	v_mfma_f32_16x16x32_bf16 v[52:55], v[194:197], v[210:213], v[52:55]
	v_mfma_f32_16x16x32_bf16 v[48:51], v[202:205], v[210:213], v[48:51]
	v_mfma_f32_16x16x32_bf16 v[36:39], v[194:197], v[218:221], v[36:39]
	v_mfma_f32_16x16x32_bf16 v[32:35], v[202:205], v[218:221], v[32:35]
	v_mfma_f32_16x16x32_bf16 v[20:23], v[194:197], v[226:229], v[20:23]
	v_mfma_f32_16x16x32_bf16 v[16:19], v[202:205], v[226:229], v[16:19]
	v_mfma_f32_16x16x32_bf16 v[4:7], v[194:197], v[236:239], v[4:7]
	v_mfma_f32_16x16x32_bf16 v[0:3], v[202:205], v[236:239], v[0:3]
	v_mfma_f32_16x16x32_bf16 v[52:55], v[198:201], v[214:217], v[52:55]
	v_mfma_f32_16x16x32_bf16 v[48:51], v[206:209], v[214:217], v[48:51]
	v_mfma_f32_16x16x32_bf16 v[36:39], v[198:201], v[222:225], v[36:39]
	v_mfma_f32_16x16x32_bf16 v[32:35], v[206:209], v[222:225], v[32:35]
	v_mfma_f32_16x16x32_bf16 v[20:23], v[198:201], v[232:235], v[20:23]
	v_mfma_f32_16x16x32_bf16 v[16:19], v[206:209], v[232:235], v[16:19]
	v_mfma_f32_16x16x32_bf16 v[4:7], v[198:201], v[240:243], v[4:7]
	v_mfma_f32_16x16x32_bf16 v[0:3], v[206:209], v[240:243], v[0:3]
	s_barrier
	s_add_i32 s78, s78, 2
	s_add_u32 s86, s86, 0x100
	s_addc_u32 s87, s87, 0
	s_add_u32 s76, s76, 0x100
	s_addc_u32 s77, s77, 0
	s_cmp_gt_u32 s78, 13
	s_cbranch_scc0 .LBB0_737
	s_and_b64 vcc, exec, s[12:13]
	s_cbranch_vccz .LBB0_740
	s_barrier

.LBB0_828:
	ds_read_b128 v[116:119], v173
	ds_read_b128 v[124:127], v173 offset:1024
	ds_read_b128 v[128:131], v173 offset:2048
	ds_read_b128 v[132:135], v173 offset:3072
	ds_read_b128 v[160:163], v174
	ds_read_b128 v[164:167], v174 offset:1024
	ds_read_b128 v[178:181], v174 offset:2048
	ds_read_b128 v[182:185], v174 offset:3072
	s_add_u32 s78, s90, 0xfffc0080
	s_addc_u32 s79, s91, -1
	s_cmp_eq_u32 s77, 12
	s_cselect_b32 s95, s4, s79
	s_cselect_b32 s94, s5, s78
	s_cselect_b32 s93, s55, s76
	s_cselect_b32 s92, s57, s67
	v_lshl_add_u64 v[168:169], s[90:91], 0, v[152:153]
	s_add_i32 m0, s31, 0xc000
	ds_read_b128 v[186:189], v175
	ds_read_b128 v[190:193], v175 offset:1024
	ds_read_b128 v[194:197], v175 offset:2048
	ds_read_b128 v[198:201], v175 offset:3072
	ds_read_b128 v[202:205], v175 offset:4096
	ds_read_b128 v[206:209], v175 offset:5120
	ds_read_b128 v[210:213], v175 offset:6144
	ds_read_b128 v[214:217], v175 offset:7168
	global_load_lds_dwordx4 v[168:169], off
	v_lshl_add_u64 v[168:169], s[90:91], 0, v[154:155]
	s_add_i32 m0, s31, 0xe000
	s_nop 0
	global_load_lds_dwordx4 v[168:169], off
	s_waitcnt vmcnt(8)
	s_waitcnt lgkmcnt(0)
	s_barrier
	s_waitcnt lgkmcnt(0)
	v_mfma_f32_16x16x32_bf16 v[140:143], v[116:119], v[186:189], v[140:143]
	v_mfma_f32_16x16x32_bf16 v[136:139], v[128:131], v[186:189], v[136:139]
	v_mfma_f32_16x16x32_bf16 v[108:111], v[116:119], v[194:197], v[108:111]
	v_mfma_f32_16x16x32_bf16 v[104:107], v[128:131], v[194:197], v[104:107]
	v_mfma_f32_16x16x32_bf16 v[92:95], v[116:119], v[202:205], v[92:95]
	v_mfma_f32_16x16x32_bf16 v[88:91], v[128:131], v[202:205], v[88:91]
	v_mfma_f32_16x16x32_bf16 v[76:79], v[116:119], v[210:213], v[76:79]
	v_mfma_f32_16x16x32_bf16 v[72:75], v[128:131], v[210:213], v[72:75]
	v_mfma_f32_16x16x32_bf16 v[140:143], v[124:127], v[190:193], v[140:143]
	v_mfma_f32_16x16x32_bf16 v[136:139], v[132:135], v[190:193], v[136:139]
	v_mfma_f32_16x16x32_bf16 v[108:111], v[124:127], v[198:201], v[108:111]
	v_mfma_f32_16x16x32_bf16 v[104:107], v[132:135], v[198:201], v[104:107]
	v_mfma_f32_16x16x32_bf16 v[92:95], v[124:127], v[206:209], v[92:95]
	v_mfma_f32_16x16x32_bf16 v[88:91], v[132:135], v[206:209], v[88:91]
	v_mfma_f32_16x16x32_bf16 v[76:79], v[124:127], v[214:217], v[76:79]
	v_mfma_f32_16x16x32_bf16 v[72:75], v[132:135], v[214:217], v[72:75]
	v_mfma_f32_16x16x32_bf16 v[120:123], v[160:163], v[186:189], v[120:123]
	v_mfma_f32_16x16x32_bf16 v[112:115], v[178:181], v[186:189], v[112:115]
	v_mfma_f32_16x16x32_bf16 v[100:103], v[160:163], v[194:197], v[100:103]
	v_mfma_f32_16x16x32_bf16 v[96:99], v[178:181], v[194:197], v[96:99]
	v_mfma_f32_16x16x32_bf16 v[84:87], v[160:163], v[202:205], v[84:87]
	v_mfma_f32_16x16x32_bf16 v[80:83], v[178:181], v[202:205], v[80:83]
	v_mfma_f32_16x16x32_bf16 v[68:71], v[160:163], v[210:213], v[68:71]
	v_mfma_f32_16x16x32_bf16 v[64:67], v[178:181], v[210:213], v[64:67]
	v_mfma_f32_16x16x32_bf16 v[120:123], v[164:167], v[190:193], v[120:123]
	v_mfma_f32_16x16x32_bf16 v[112:115], v[182:185], v[190:193], v[112:115]
	v_mfma_f32_16x16x32_bf16 v[100:103], v[164:167], v[198:201], v[100:103]
	v_mfma_f32_16x16x32_bf16 v[96:99], v[182:185], v[198:201], v[96:99]
	v_mfma_f32_16x16x32_bf16 v[84:87], v[164:167], v[206:209], v[84:87]
	v_mfma_f32_16x16x32_bf16 v[80:83], v[182:185], v[206:209], v[80:83]
	v_mfma_f32_16x16x32_bf16 v[68:71], v[164:167], v[214:217], v[68:71]
	v_mfma_f32_16x16x32_bf16 v[64:67], v[182:185], v[214:217], v[64:67]
	s_barrier
	s_add_i32 s78, s62, s21
	v_lshl_add_u64 v[168:169], s[92:93], 0, v[148:149]
	s_mov_b32 m0, s78
	ds_read_b128 v[186:189], v175 offset:16384
	ds_read_b128 v[190:193], v175 offset:17408
	ds_read_b128 v[194:197], v175 offset:18432
	ds_read_b128 v[198:201], v175 offset:19456
	ds_read_b128 v[202:205], v175 offset:20480
	ds_read_b128 v[206:209], v175 offset:21504
	ds_read_b128 v[210:213], v175 offset:22528
	ds_read_b128 v[214:217], v175 offset:23552
	global_load_lds_dwordx4 v[168:169], off
	s_add_i32 m0, s78, 0x2000
	s_add_u32 s78, s92, 0x580000
	v_lshl_add_u64 v[218:219], s[92:93], 0, v[144:145]
	s_addc_u32 s79, s93, 0
	s_add_i32 s80, s63, s21
	global_load_lds_dwordx4 v[218:219], off
	v_lshl_add_u64 v[220:221], s[78:79], 0, v[148:149]
	s_mov_b32 m0, s80
	v_lshl_add_u64 v[222:223], s[94:95], 0, v[146:147]
	global_load_lds_dwordx4 v[220:221], off
	v_lshl_add_u64 v[220:221], s[78:79], 0, v[144:145]
	s_add_i32 m0, s80, 0x2000
	s_nop 0
	global_load_lds_dwordx4 v[220:221], off
	v_lshl_add_u64 v[220:221], s[94:95], 0, v[150:151]
	s_mov_b32 m0, s31
	s_nop 0
	global_load_lds_dwordx4 v[220:221], off
	s_mov_b32 m0, s52
	s_nop 0
	global_load_lds_dwordx4 v[222:223], off
	s_waitcnt vmcnt(8)
	s_waitcnt lgkmcnt(0)
	s_barrier
	s_waitcnt lgkmcnt(0)
	v_mfma_f32_16x16x32_bf16 v[60:63], v[116:119], v[186:189], v[60:63]
	v_mfma_f32_16x16x32_bf16 v[56:59], v[128:131], v[186:189], v[56:59]
	v_mfma_f32_16x16x32_bf16 v[44:47], v[116:119], v[194:197], v[44:47]
	v_mfma_f32_16x16x32_bf16 v[40:43], v[128:131], v[194:197], v[40:43]
	v_mfma_f32_16x16x32_bf16 v[28:31], v[116:119], v[202:205], v[28:31]
	v_mfma_f32_16x16x32_bf16 v[24:27], v[128:131], v[202:205], v[24:27]
	v_mfma_f32_16x16x32_bf16 v[12:15], v[116:119], v[210:213], v[12:15]
	v_mfma_f32_16x16x32_bf16 v[8:11], v[128:131], v[210:213], v[8:11]
	v_mfma_f32_16x16x32_bf16 v[60:63], v[124:127], v[190:193], v[60:63]
	v_mfma_f32_16x16x32_bf16 v[56:59], v[132:135], v[190:193], v[56:59]
	v_mfma_f32_16x16x32_bf16 v[44:47], v[124:127], v[198:201], v[44:47]
	v_mfma_f32_16x16x32_bf16 v[40:43], v[132:135], v[198:201], v[40:43]
	v_mfma_f32_16x16x32_bf16 v[28:31], v[124:127], v[206:209], v[28:31]
	v_mfma_f32_16x16x32_bf16 v[24:27], v[132:135], v[206:209], v[24:27]
	v_mfma_f32_16x16x32_bf16 v[12:15], v[124:127], v[214:217], v[12:15]
	v_mfma_f32_16x16x32_bf16 v[8:11], v[132:135], v[214:217], v[8:11]
	v_mfma_f32_16x16x32_bf16 v[52:55], v[160:163], v[186:189], v[52:55]
	v_mfma_f32_16x16x32_bf16 v[48:51], v[178:181], v[186:189], v[48:51]
	v_mfma_f32_16x16x32_bf16 v[36:39], v[160:163], v[194:197], v[36:39]
	v_mfma_f32_16x16x32_bf16 v[32:35], v[178:181], v[194:197], v[32:35]
	v_mfma_f32_16x16x32_bf16 v[20:23], v[160:163], v[202:205], v[20:23]
	v_mfma_f32_16x16x32_bf16 v[16:19], v[178:181], v[202:205], v[16:19]
	v_mfma_f32_16x16x32_bf16 v[4:7], v[160:163], v[210:213], v[4:7]
	v_mfma_f32_16x16x32_bf16 v[0:3], v[178:181], v[210:213], v[0:3]
	v_mfma_f32_16x16x32_bf16 v[52:55], v[164:167], v[190:193], v[52:55]
	v_mfma_f32_16x16x32_bf16 v[48:51], v[182:185], v[190:193], v[48:51]
	v_mfma_f32_16x16x32_bf16 v[36:39], v[164:167], v[198:201], v[36:39]
	v_mfma_f32_16x16x32_bf16 v[32:35], v[182:185], v[198:201], v[32:35]
	v_mfma_f32_16x16x32_bf16 v[20:23], v[164:167], v[206:209], v[20:23]
	v_mfma_f32_16x16x32_bf16 v[16:19], v[182:185], v[206:209], v[16:19]
	v_mfma_f32_16x16x32_bf16 v[4:7], v[164:167], v[214:217], v[4:7]
	v_mfma_f32_16x16x32_bf16 v[0:3], v[182:185], v[214:217], v[0:3]
	s_barrier
	s_add_i32 s80, 0, 0x18000
	s_add_i32 s81, 0, 0x1c000
	v_add_u32_e32 v132, s80, v171
	v_add_u32_e32 v177, s81, v171
	ds_read_b128 v[116:119], v132
	ds_read_b128 v[124:127], v132 offset:1024
	ds_read_b128 v[128:131], v132 offset:2048
	ds_read_b128 v[132:135], v132 offset:3072
	ds_read_b128 v[160:163], v177
	ds_read_b128 v[164:167], v177 offset:1024
	ds_read_b128 v[178:181], v177 offset:2048
	ds_read_b128 v[182:185], v177 offset:3072
	s_add_u32 s78, s94, 0x40000
	s_addc_u32 s79, s95, 0
	s_mov_b32 m0, s53
	v_lshl_add_u64 v[224:225], s[78:79], 0, v[150:151]
	ds_read_b128 v[186:189], v175 offset:32768
	ds_read_b128 v[190:193], v175 offset:33792
	ds_read_b128 v[194:197], v175 offset:34816
	ds_read_b128 v[198:201], v175 offset:35840
	ds_read_b128 v[202:205], v175 offset:36864
	ds_read_b128 v[206:209], v175 offset:37888
	ds_read_b128 v[210:213], v175 offset:38912
	ds_read_b128 v[214:217], v175 offset:39936
	global_load_lds_dwordx4 v[224:225], off
	v_lshl_add_u64 v[224:225], s[78:79], 0, v[146:147]
	s_mov_b32 m0, s58
	s_nop 0
	global_load_lds_dwordx4 v[224:225], off
	s_waitcnt vmcnt(8)
	s_waitcnt lgkmcnt(0)
	s_barrier
	s_waitcnt lgkmcnt(0)
	v_mfma_f32_16x16x32_bf16 v[140:143], v[116:119], v[186:189], v[140:143]
	v_mfma_f32_16x16x32_bf16 v[136:139], v[128:131], v[186:189], v[136:139]
	v_mfma_f32_16x16x32_bf16 v[108:111], v[116:119], v[194:197], v[108:111]
	v_mfma_f32_16x16x32_bf16 v[104:107], v[128:131], v[194:197], v[104:107]
	v_mfma_f32_16x16x32_bf16 v[92:95], v[116:119], v[202:205], v[92:95]
	v_mfma_f32_16x16x32_bf16 v[88:91], v[128:131], v[202:205], v[88:91]
	v_mfma_f32_16x16x32_bf16 v[76:79], v[116:119], v[210:213], v[76:79]
	v_mfma_f32_16x16x32_bf16 v[72:75], v[128:131], v[210:213], v[72:75]
	v_mfma_f32_16x16x32_bf16 v[140:143], v[124:127], v[190:193], v[140:143]
	v_mfma_f32_16x16x32_bf16 v[136:139], v[132:135], v[190:193], v[136:139]
	v_mfma_f32_16x16x32_bf16 v[108:111], v[124:127], v[198:201], v[108:111]
	v_mfma_f32_16x16x32_bf16 v[104:107], v[132:135], v[198:201], v[104:107]
	v_mfma_f32_16x16x32_bf16 v[92:95], v[124:127], v[206:209], v[92:95]
	v_mfma_f32_16x16x32_bf16 v[88:91], v[132:135], v[206:209], v[88:91]
	v_mfma_f32_16x16x32_bf16 v[76:79], v[124:127], v[214:217], v[76:79]
	v_mfma_f32_16x16x32_bf16 v[72:75], v[132:135], v[214:217], v[72:75]
	v_mfma_f32_16x16x32_bf16 v[120:123], v[160:163], v[186:189], v[120:123]
	v_mfma_f32_16x16x32_bf16 v[112:115], v[178:181], v[186:189], v[112:115]
	v_mfma_f32_16x16x32_bf16 v[100:103], v[160:163], v[194:197], v[100:103]
	v_mfma_f32_16x16x32_bf16 v[96:99], v[178:181], v[194:197], v[96:99]
	v_mfma_f32_16x16x32_bf16 v[84:87], v[160:163], v[202:205], v[84:87]
	v_mfma_f32_16x16x32_bf16 v[80:83], v[178:181], v[202:205], v[80:83]
	v_mfma_f32_16x16x32_bf16 v[68:71], v[160:163], v[210:213], v[68:71]
	v_mfma_f32_16x16x32_bf16 v[64:67], v[178:181], v[210:213], v[64:67]
	v_mfma_f32_16x16x32_bf16 v[120:123], v[164:167], v[190:193], v[120:123]
	v_mfma_f32_16x16x32_bf16 v[112:115], v[182:185], v[190:193], v[112:115]
	v_mfma_f32_16x16x32_bf16 v[100:103], v[164:167], v[198:201], v[100:103]
	v_mfma_f32_16x16x32_bf16 v[96:99], v[182:185], v[198:201], v[96:99]
	v_mfma_f32_16x16x32_bf16 v[84:87], v[164:167], v[206:209], v[84:87]
	v_mfma_f32_16x16x32_bf16 v[80:83], v[182:185], v[206:209], v[80:83]
	v_mfma_f32_16x16x32_bf16 v[68:71], v[164:167], v[214:217], v[68:71]
	v_mfma_f32_16x16x32_bf16 v[64:67], v[182:185], v[214:217], v[64:67]
	s_barrier
	s_add_i32 s78, s80, s21
	v_lshl_add_u64 v[168:169], v[168:169], 0, s[16:17]
	s_mov_b32 m0, s78
	ds_read_b128 v[186:189], v175 offset:49152
	ds_read_b128 v[190:193], v175 offset:50176
	ds_read_b128 v[194:197], v175 offset:51200
	ds_read_b128 v[198:201], v175 offset:52224
	ds_read_b128 v[202:205], v175 offset:53248
	ds_read_b128 v[206:209], v175 offset:54272
	ds_read_b128 v[210:213], v175 offset:55296
	ds_read_b128 v[214:217], v175 offset:56320
	global_load_lds_dwordx4 v[168:169], off
	s_add_i32 m0, s78, 0x2000
	s_add_u32 s78, s92, 0x580080
	v_lshl_add_u64 v[168:169], v[218:219], 0, s[16:17]
	s_addc_u32 s79, s93, 0
	s_add_i32 s80, s81, s21
	global_load_lds_dwordx4 v[168:169], off
	v_lshl_add_u64 v[168:169], s[78:79], 0, v[148:149]
	s_mov_b32 m0, s80
	s_nop 0
	global_load_lds_dwordx4 v[168:169], off
	v_lshl_add_u64 v[168:169], s[78:79], 0, v[144:145]
	s_add_i32 m0, s80, 0x2000
	s_nop 0
	global_load_lds_dwordx4 v[168:169], off
	v_lshl_add_u64 v[168:169], v[220:221], 0, s[16:17]
	s_mov_b32 m0, s60
	s_nop 0
	global_load_lds_dwordx4 v[168:169], off
	v_lshl_add_u64 v[168:169], v[222:223], 0, s[16:17]
	s_mov_b32 m0, s61
	s_nop 0
	global_load_lds_dwordx4 v[168:169], off
	s_waitcnt vmcnt(8)
	s_waitcnt lgkmcnt(0)
	s_barrier
	s_waitcnt lgkmcnt(0)
	v_mfma_f32_16x16x32_bf16 v[60:63], v[116:119], v[186:189], v[60:63]
	v_mfma_f32_16x16x32_bf16 v[56:59], v[128:131], v[186:189], v[56:59]
	v_mfma_f32_16x16x32_bf16 v[44:47], v[116:119], v[194:197], v[44:47]
	v_mfma_f32_16x16x32_bf16 v[40:43], v[128:131], v[194:197], v[40:43]
	v_mfma_f32_16x16x32_bf16 v[28:31], v[116:119], v[202:205], v[28:31]
	v_mfma_f32_16x16x32_bf16 v[24:27], v[128:131], v[202:205], v[24:27]
	v_mfma_f32_16x16x32_bf16 v[12:15], v[116:119], v[210:213], v[12:15]
	v_mfma_f32_16x16x32_bf16 v[8:11], v[128:131], v[210:213], v[8:11]
	v_mfma_f32_16x16x32_bf16 v[60:63], v[124:127], v[190:193], v[60:63]
	v_mfma_f32_16x16x32_bf16 v[56:59], v[132:135], v[190:193], v[56:59]
	v_mfma_f32_16x16x32_bf16 v[44:47], v[124:127], v[198:201], v[44:47]
	v_mfma_f32_16x16x32_bf16 v[40:43], v[132:135], v[198:201], v[40:43]
	v_mfma_f32_16x16x32_bf16 v[28:31], v[124:127], v[206:209], v[28:31]
	v_mfma_f32_16x16x32_bf16 v[24:27], v[132:135], v[206:209], v[24:27]
	v_mfma_f32_16x16x32_bf16 v[12:15], v[124:127], v[214:217], v[12:15]
	v_mfma_f32_16x16x32_bf16 v[8:11], v[132:135], v[214:217], v[8:11]
	v_mfma_f32_16x16x32_bf16 v[52:55], v[160:163], v[186:189], v[52:55]
	v_mfma_f32_16x16x32_bf16 v[48:51], v[178:181], v[186:189], v[48:51]
	v_mfma_f32_16x16x32_bf16 v[36:39], v[160:163], v[194:197], v[36:39]
	v_mfma_f32_16x16x32_bf16 v[32:35], v[178:181], v[194:197], v[32:35]
	v_mfma_f32_16x16x32_bf16 v[20:23], v[160:163], v[202:205], v[20:23]
	v_mfma_f32_16x16x32_bf16 v[16:19], v[178:181], v[202:205], v[16:19]
	v_mfma_f32_16x16x32_bf16 v[4:7], v[160:163], v[210:213], v[4:7]
	v_mfma_f32_16x16x32_bf16 v[0:3], v[178:181], v[210:213], v[0:3]
	v_mfma_f32_16x16x32_bf16 v[52:55], v[164:167], v[190:193], v[52:55]
	v_mfma_f32_16x16x32_bf16 v[48:51], v[182:185], v[190:193], v[48:51]
	v_mfma_f32_16x16x32_bf16 v[36:39], v[164:167], v[198:201], v[36:39]
	v_mfma_f32_16x16x32_bf16 v[32:35], v[182:185], v[198:201], v[32:35]
	v_mfma_f32_16x16x32_bf16 v[20:23], v[164:167], v[206:209], v[20:23]
	v_mfma_f32_16x16x32_bf16 v[16:19], v[182:185], v[206:209], v[16:19]
	v_mfma_f32_16x16x32_bf16 v[4:7], v[164:167], v[214:217], v[4:7]
	v_mfma_f32_16x16x32_bf16 v[0:3], v[182:185], v[214:217], v[0:3]
	s_barrier
	s_add_i32 s77, s77, 2
	s_add_u32 s90, s90, 0x100
	s_addc_u32 s91, s91, 0
	s_add_u32 s67, s67, 0x100
	s_addc_u32 s76, s76, 0
	s_cmp_gt_u32 s77, 13
	s_cbranch_scc0 .LBB0_828
	s_and_b64 vcc, exec, s[34:35]
	s_cbranch_vccz .LBB0_831
	s_barrier

.LBB0_967:
	ds_read_b128 v[116:119], v173
	ds_read_b128 v[124:127], v173 offset:1024
	ds_read_b128 v[128:131], v173 offset:2048
	ds_read_b128 v[132:135], v173 offset:3072
	ds_read_b128 v[160:163], v174
	ds_read_b128 v[164:167], v174 offset:1024
	ds_read_b128 v[178:181], v174 offset:2048
	ds_read_b128 v[182:185], v174 offset:3072
	s_add_u32 s78, s90, 0xfffc0080
	s_addc_u32 s79, s91, -1
	s_cmp_eq_u32 s77, 12
	s_cselect_b32 s95, s4, s79
	s_cselect_b32 s94, s5, s78
	s_cselect_b32 s93, s55, s76
	s_cselect_b32 s92, s57, s67
	v_lshl_add_u64 v[168:169], s[90:91], 0, v[152:153]
	s_add_i32 m0, s31, 0xc000
	ds_read_b128 v[186:189], v175
	ds_read_b128 v[190:193], v175 offset:1024
	ds_read_b128 v[194:197], v175 offset:2048
	ds_read_b128 v[198:201], v175 offset:3072
	ds_read_b128 v[202:205], v175 offset:4096
	ds_read_b128 v[206:209], v175 offset:5120
	ds_read_b128 v[210:213], v175 offset:6144
	ds_read_b128 v[214:217], v175 offset:7168
	global_load_lds_dwordx4 v[168:169], off
	v_lshl_add_u64 v[168:169], s[90:91], 0, v[154:155]
	s_add_i32 m0, s31, 0xe000
	s_nop 0
	global_load_lds_dwordx4 v[168:169], off
	s_waitcnt vmcnt(8)
	s_waitcnt lgkmcnt(0)
	s_barrier
	s_waitcnt lgkmcnt(0)
	v_mfma_f32_16x16x32_bf16 v[140:143], v[116:119], v[186:189], v[140:143]
	v_mfma_f32_16x16x32_bf16 v[136:139], v[128:131], v[186:189], v[136:139]
	v_mfma_f32_16x16x32_bf16 v[108:111], v[116:119], v[194:197], v[108:111]
	v_mfma_f32_16x16x32_bf16 v[104:107], v[128:131], v[194:197], v[104:107]
	v_mfma_f32_16x16x32_bf16 v[92:95], v[116:119], v[202:205], v[92:95]
	v_mfma_f32_16x16x32_bf16 v[88:91], v[128:131], v[202:205], v[88:91]
	v_mfma_f32_16x16x32_bf16 v[76:79], v[116:119], v[210:213], v[76:79]
	v_mfma_f32_16x16x32_bf16 v[72:75], v[128:131], v[210:213], v[72:75]
	v_mfma_f32_16x16x32_bf16 v[140:143], v[124:127], v[190:193], v[140:143]
	v_mfma_f32_16x16x32_bf16 v[136:139], v[132:135], v[190:193], v[136:139]
	v_mfma_f32_16x16x32_bf16 v[108:111], v[124:127], v[198:201], v[108:111]
	v_mfma_f32_16x16x32_bf16 v[104:107], v[132:135], v[198:201], v[104:107]
	v_mfma_f32_16x16x32_bf16 v[92:95], v[124:127], v[206:209], v[92:95]
	v_mfma_f32_16x16x32_bf16 v[88:91], v[132:135], v[206:209], v[88:91]
	v_mfma_f32_16x16x32_bf16 v[76:79], v[124:127], v[214:217], v[76:79]
	v_mfma_f32_16x16x32_bf16 v[72:75], v[132:135], v[214:217], v[72:75]
	v_mfma_f32_16x16x32_bf16 v[120:123], v[160:163], v[186:189], v[120:123]
	v_mfma_f32_16x16x32_bf16 v[112:115], v[178:181], v[186:189], v[112:115]
	v_mfma_f32_16x16x32_bf16 v[100:103], v[160:163], v[194:197], v[100:103]
	v_mfma_f32_16x16x32_bf16 v[96:99], v[178:181], v[194:197], v[96:99]
	v_mfma_f32_16x16x32_bf16 v[84:87], v[160:163], v[202:205], v[84:87]
	v_mfma_f32_16x16x32_bf16 v[80:83], v[178:181], v[202:205], v[80:83]
	v_mfma_f32_16x16x32_bf16 v[68:71], v[160:163], v[210:213], v[68:71]
	v_mfma_f32_16x16x32_bf16 v[64:67], v[178:181], v[210:213], v[64:67]
	v_mfma_f32_16x16x32_bf16 v[120:123], v[164:167], v[190:193], v[120:123]
	v_mfma_f32_16x16x32_bf16 v[112:115], v[182:185], v[190:193], v[112:115]
	v_mfma_f32_16x16x32_bf16 v[100:103], v[164:167], v[198:201], v[100:103]
	v_mfma_f32_16x16x32_bf16 v[96:99], v[182:185], v[198:201], v[96:99]
	v_mfma_f32_16x16x32_bf16 v[84:87], v[164:167], v[206:209], v[84:87]
	v_mfma_f32_16x16x32_bf16 v[80:83], v[182:185], v[206:209], v[80:83]
	v_mfma_f32_16x16x32_bf16 v[68:71], v[164:167], v[214:217], v[68:71]
	v_mfma_f32_16x16x32_bf16 v[64:67], v[182:185], v[214:217], v[64:67]
	s_barrier
	s_add_i32 s78, s62, s21
	v_lshl_add_u64 v[168:169], s[92:93], 0, v[148:149]
	s_mov_b32 m0, s78
	ds_read_b128 v[186:189], v175 offset:16384
	ds_read_b128 v[190:193], v175 offset:17408
	ds_read_b128 v[194:197], v175 offset:18432
	ds_read_b128 v[198:201], v175 offset:19456
	ds_read_b128 v[202:205], v175 offset:20480
	ds_read_b128 v[206:209], v175 offset:21504
	ds_read_b128 v[210:213], v175 offset:22528
	ds_read_b128 v[214:217], v175 offset:23552
	global_load_lds_dwordx4 v[168:169], off
	s_add_i32 m0, s78, 0x2000
	s_add_u32 s78, s92, 0x580000
	v_lshl_add_u64 v[218:219], s[92:93], 0, v[144:145]
	s_addc_u32 s79, s93, 0
	s_add_i32 s80, s63, s21
	global_load_lds_dwordx4 v[218:219], off
	v_lshl_add_u64 v[220:221], s[78:79], 0, v[148:149]
	s_mov_b32 m0, s80
	v_lshl_add_u64 v[222:223], s[94:95], 0, v[146:147]
	global_load_lds_dwordx4 v[220:221], off
	v_lshl_add_u64 v[220:221], s[78:79], 0, v[144:145]
	s_add_i32 m0, s80, 0x2000
	s_nop 0
	global_load_lds_dwordx4 v[220:221], off
	v_lshl_add_u64 v[220:221], s[94:95], 0, v[150:151]
	s_mov_b32 m0, s31
	s_nop 0
	global_load_lds_dwordx4 v[220:221], off
	s_mov_b32 m0, s52
	s_nop 0
	global_load_lds_dwordx4 v[222:223], off
	s_waitcnt vmcnt(8)
	s_waitcnt lgkmcnt(0)
	s_barrier
	s_waitcnt lgkmcnt(0)
	v_mfma_f32_16x16x32_bf16 v[60:63], v[116:119], v[186:189], v[60:63]
	v_mfma_f32_16x16x32_bf16 v[56:59], v[128:131], v[186:189], v[56:59]
	v_mfma_f32_16x16x32_bf16 v[44:47], v[116:119], v[194:197], v[44:47]
	v_mfma_f32_16x16x32_bf16 v[40:43], v[128:131], v[194:197], v[40:43]
	v_mfma_f32_16x16x32_bf16 v[28:31], v[116:119], v[202:205], v[28:31]
	v_mfma_f32_16x16x32_bf16 v[24:27], v[128:131], v[202:205], v[24:27]
	v_mfma_f32_16x16x32_bf16 v[12:15], v[116:119], v[210:213], v[12:15]
	v_mfma_f32_16x16x32_bf16 v[8:11], v[128:131], v[210:213], v[8:11]
	v_mfma_f32_16x16x32_bf16 v[60:63], v[124:127], v[190:193], v[60:63]
	v_mfma_f32_16x16x32_bf16 v[56:59], v[132:135], v[190:193], v[56:59]
	v_mfma_f32_16x16x32_bf16 v[44:47], v[124:127], v[198:201], v[44:47]
	v_mfma_f32_16x16x32_bf16 v[40:43], v[132:135], v[198:201], v[40:43]
	v_mfma_f32_16x16x32_bf16 v[28:31], v[124:127], v[206:209], v[28:31]
	v_mfma_f32_16x16x32_bf16 v[24:27], v[132:135], v[206:209], v[24:27]
	v_mfma_f32_16x16x32_bf16 v[12:15], v[124:127], v[214:217], v[12:15]
	v_mfma_f32_16x16x32_bf16 v[8:11], v[132:135], v[214:217], v[8:11]
	v_mfma_f32_16x16x32_bf16 v[52:55], v[160:163], v[186:189], v[52:55]
	v_mfma_f32_16x16x32_bf16 v[48:51], v[178:181], v[186:189], v[48:51]
	v_mfma_f32_16x16x32_bf16 v[36:39], v[160:163], v[194:197], v[36:39]
	v_mfma_f32_16x16x32_bf16 v[32:35], v[178:181], v[194:197], v[32:35]
	v_mfma_f32_16x16x32_bf16 v[20:23], v[160:163], v[202:205], v[20:23]
	v_mfma_f32_16x16x32_bf16 v[16:19], v[178:181], v[202:205], v[16:19]
	v_mfma_f32_16x16x32_bf16 v[4:7], v[160:163], v[210:213], v[4:7]
	v_mfma_f32_16x16x32_bf16 v[0:3], v[178:181], v[210:213], v[0:3]
	v_mfma_f32_16x16x32_bf16 v[52:55], v[164:167], v[190:193], v[52:55]
	v_mfma_f32_16x16x32_bf16 v[48:51], v[182:185], v[190:193], v[48:51]
	v_mfma_f32_16x16x32_bf16 v[36:39], v[164:167], v[198:201], v[36:39]
	v_mfma_f32_16x16x32_bf16 v[32:35], v[182:185], v[198:201], v[32:35]
	v_mfma_f32_16x16x32_bf16 v[20:23], v[164:167], v[206:209], v[20:23]
	v_mfma_f32_16x16x32_bf16 v[16:19], v[182:185], v[206:209], v[16:19]
	v_mfma_f32_16x16x32_bf16 v[4:7], v[164:167], v[214:217], v[4:7]
	v_mfma_f32_16x16x32_bf16 v[0:3], v[182:185], v[214:217], v[0:3]
	s_barrier
	s_add_i32 s80, 0, 0x18000
	s_add_i32 s81, 0, 0x1c000
	v_add_u32_e32 v132, s80, v171
	v_add_u32_e32 v177, s81, v171
	ds_read_b128 v[116:119], v132
	ds_read_b128 v[124:127], v132 offset:1024
	ds_read_b128 v[128:131], v132 offset:2048
	ds_read_b128 v[132:135], v132 offset:3072
	ds_read_b128 v[160:163], v177
	ds_read_b128 v[164:167], v177 offset:1024
	ds_read_b128 v[178:181], v177 offset:2048
	ds_read_b128 v[182:185], v177 offset:3072
	s_add_u32 s78, s94, 0x40000
	s_addc_u32 s79, s95, 0
	s_mov_b32 m0, s53
	v_lshl_add_u64 v[224:225], s[78:79], 0, v[150:151]
	ds_read_b128 v[186:189], v175 offset:32768
	ds_read_b128 v[190:193], v175 offset:33792
	ds_read_b128 v[194:197], v175 offset:34816
	ds_read_b128 v[198:201], v175 offset:35840
	ds_read_b128 v[202:205], v175 offset:36864
	ds_read_b128 v[206:209], v175 offset:37888
	ds_read_b128 v[210:213], v175 offset:38912
	ds_read_b128 v[214:217], v175 offset:39936
	global_load_lds_dwordx4 v[224:225], off
	v_lshl_add_u64 v[224:225], s[78:79], 0, v[146:147]
	s_mov_b32 m0, s58
	s_nop 0
	global_load_lds_dwordx4 v[224:225], off
	s_waitcnt vmcnt(8)
	s_waitcnt lgkmcnt(0)
	s_barrier
	s_waitcnt lgkmcnt(0)
	v_mfma_f32_16x16x32_bf16 v[140:143], v[116:119], v[186:189], v[140:143]
	v_mfma_f32_16x16x32_bf16 v[136:139], v[128:131], v[186:189], v[136:139]
	v_mfma_f32_16x16x32_bf16 v[108:111], v[116:119], v[194:197], v[108:111]
	v_mfma_f32_16x16x32_bf16 v[104:107], v[128:131], v[194:197], v[104:107]
	v_mfma_f32_16x16x32_bf16 v[92:95], v[116:119], v[202:205], v[92:95]
	v_mfma_f32_16x16x32_bf16 v[88:91], v[128:131], v[202:205], v[88:91]
	v_mfma_f32_16x16x32_bf16 v[76:79], v[116:119], v[210:213], v[76:79]
	v_mfma_f32_16x16x32_bf16 v[72:75], v[128:131], v[210:213], v[72:75]
	v_mfma_f32_16x16x32_bf16 v[140:143], v[124:127], v[190:193], v[140:143]
	v_mfma_f32_16x16x32_bf16 v[136:139], v[132:135], v[190:193], v[136:139]
	v_mfma_f32_16x16x32_bf16 v[108:111], v[124:127], v[198:201], v[108:111]
	v_mfma_f32_16x16x32_bf16 v[104:107], v[132:135], v[198:201], v[104:107]
	v_mfma_f32_16x16x32_bf16 v[92:95], v[124:127], v[206:209], v[92:95]
	v_mfma_f32_16x16x32_bf16 v[88:91], v[132:135], v[206:209], v[88:91]
	v_mfma_f32_16x16x32_bf16 v[76:79], v[124:127], v[214:217], v[76:79]
	v_mfma_f32_16x16x32_bf16 v[72:75], v[132:135], v[214:217], v[72:75]
	v_mfma_f32_16x16x32_bf16 v[120:123], v[160:163], v[186:189], v[120:123]
	v_mfma_f32_16x16x32_bf16 v[112:115], v[178:181], v[186:189], v[112:115]
	v_mfma_f32_16x16x32_bf16 v[100:103], v[160:163], v[194:197], v[100:103]
	v_mfma_f32_16x16x32_bf16 v[96:99], v[178:181], v[194:197], v[96:99]
	v_mfma_f32_16x16x32_bf16 v[84:87], v[160:163], v[202:205], v[84:87]
	v_mfma_f32_16x16x32_bf16 v[80:83], v[178:181], v[202:205], v[80:83]
	v_mfma_f32_16x16x32_bf16 v[68:71], v[160:163], v[210:213], v[68:71]
	v_mfma_f32_16x16x32_bf16 v[64:67], v[178:181], v[210:213], v[64:67]
	v_mfma_f32_16x16x32_bf16 v[120:123], v[164:167], v[190:193], v[120:123]
	v_mfma_f32_16x16x32_bf16 v[112:115], v[182:185], v[190:193], v[112:115]
	v_mfma_f32_16x16x32_bf16 v[100:103], v[164:167], v[198:201], v[100:103]
	v_mfma_f32_16x16x32_bf16 v[96:99], v[182:185], v[198:201], v[96:99]
	v_mfma_f32_16x16x32_bf16 v[84:87], v[164:167], v[206:209], v[84:87]
	v_mfma_f32_16x16x32_bf16 v[80:83], v[182:185], v[206:209], v[80:83]
	v_mfma_f32_16x16x32_bf16 v[68:71], v[164:167], v[214:217], v[68:71]
	v_mfma_f32_16x16x32_bf16 v[64:67], v[182:185], v[214:217], v[64:67]
	s_barrier
	s_add_i32 s78, s80, s21
	v_lshl_add_u64 v[168:169], v[168:169], 0, s[16:17]
	s_mov_b32 m0, s78
	ds_read_b128 v[186:189], v175 offset:49152
	ds_read_b128 v[190:193], v175 offset:50176
	ds_read_b128 v[194:197], v175 offset:51200
	ds_read_b128 v[198:201], v175 offset:52224
	ds_read_b128 v[202:205], v175 offset:53248
	ds_read_b128 v[206:209], v175 offset:54272
	ds_read_b128 v[210:213], v175 offset:55296
	ds_read_b128 v[214:217], v175 offset:56320
	global_load_lds_dwordx4 v[168:169], off
	s_add_i32 m0, s78, 0x2000
	s_add_u32 s78, s92, 0x580080
	v_lshl_add_u64 v[168:169], v[218:219], 0, s[16:17]
	s_addc_u32 s79, s93, 0
	s_add_i32 s80, s81, s21
	global_load_lds_dwordx4 v[168:169], off
	v_lshl_add_u64 v[168:169], s[78:79], 0, v[148:149]
	s_mov_b32 m0, s80
	s_nop 0
	global_load_lds_dwordx4 v[168:169], off
	v_lshl_add_u64 v[168:169], s[78:79], 0, v[144:145]
	s_add_i32 m0, s80, 0x2000
	s_nop 0
	global_load_lds_dwordx4 v[168:169], off
	v_lshl_add_u64 v[168:169], v[220:221], 0, s[16:17]
	s_mov_b32 m0, s60
	s_nop 0
	global_load_lds_dwordx4 v[168:169], off
	v_lshl_add_u64 v[168:169], v[222:223], 0, s[16:17]
	s_mov_b32 m0, s61
	s_nop 0
	global_load_lds_dwordx4 v[168:169], off
	s_waitcnt vmcnt(8)
	s_waitcnt lgkmcnt(0)
	s_barrier
	s_waitcnt lgkmcnt(0)
	v_mfma_f32_16x16x32_bf16 v[60:63], v[116:119], v[186:189], v[60:63]
	v_mfma_f32_16x16x32_bf16 v[56:59], v[128:131], v[186:189], v[56:59]
	v_mfma_f32_16x16x32_bf16 v[44:47], v[116:119], v[194:197], v[44:47]
	v_mfma_f32_16x16x32_bf16 v[40:43], v[128:131], v[194:197], v[40:43]
	v_mfma_f32_16x16x32_bf16 v[28:31], v[116:119], v[202:205], v[28:31]
	v_mfma_f32_16x16x32_bf16 v[24:27], v[128:131], v[202:205], v[24:27]
	v_mfma_f32_16x16x32_bf16 v[12:15], v[116:119], v[210:213], v[12:15]
	v_mfma_f32_16x16x32_bf16 v[8:11], v[128:131], v[210:213], v[8:11]
	v_mfma_f32_16x16x32_bf16 v[60:63], v[124:127], v[190:193], v[60:63]
	v_mfma_f32_16x16x32_bf16 v[56:59], v[132:135], v[190:193], v[56:59]
	v_mfma_f32_16x16x32_bf16 v[44:47], v[124:127], v[198:201], v[44:47]
	v_mfma_f32_16x16x32_bf16 v[40:43], v[132:135], v[198:201], v[40:43]
	v_mfma_f32_16x16x32_bf16 v[28:31], v[124:127], v[206:209], v[28:31]
	v_mfma_f32_16x16x32_bf16 v[24:27], v[132:135], v[206:209], v[24:27]
	v_mfma_f32_16x16x32_bf16 v[12:15], v[124:127], v[214:217], v[12:15]
	v_mfma_f32_16x16x32_bf16 v[8:11], v[132:135], v[214:217], v[8:11]
	v_mfma_f32_16x16x32_bf16 v[52:55], v[160:163], v[186:189], v[52:55]
	v_mfma_f32_16x16x32_bf16 v[48:51], v[178:181], v[186:189], v[48:51]
	v_mfma_f32_16x16x32_bf16 v[36:39], v[160:163], v[194:197], v[36:39]
	v_mfma_f32_16x16x32_bf16 v[32:35], v[178:181], v[194:197], v[32:35]
	v_mfma_f32_16x16x32_bf16 v[20:23], v[160:163], v[202:205], v[20:23]
	v_mfma_f32_16x16x32_bf16 v[16:19], v[178:181], v[202:205], v[16:19]
	v_mfma_f32_16x16x32_bf16 v[4:7], v[160:163], v[210:213], v[4:7]
	v_mfma_f32_16x16x32_bf16 v[0:3], v[178:181], v[210:213], v[0:3]
	v_mfma_f32_16x16x32_bf16 v[52:55], v[164:167], v[190:193], v[52:55]
	v_mfma_f32_16x16x32_bf16 v[48:51], v[182:185], v[190:193], v[48:51]
	v_mfma_f32_16x16x32_bf16 v[36:39], v[164:167], v[198:201], v[36:39]
	v_mfma_f32_16x16x32_bf16 v[32:35], v[182:185], v[198:201], v[32:35]
	v_mfma_f32_16x16x32_bf16 v[20:23], v[164:167], v[206:209], v[20:23]
	v_mfma_f32_16x16x32_bf16 v[16:19], v[182:185], v[206:209], v[16:19]
	v_mfma_f32_16x16x32_bf16 v[4:7], v[164:167], v[214:217], v[4:7]
	v_mfma_f32_16x16x32_bf16 v[0:3], v[182:185], v[214:217], v[0:3]
	s_barrier
	s_add_i32 s77, s77, 2
	s_add_u32 s90, s90, 0x100
	s_addc_u32 s91, s91, 0
	s_add_u32 s67, s67, 0x100
	s_addc_u32 s76, s76, 0
	s_cmp_lt_u32 s77, 14
	s_cbranch_scc1 .LBB0_967
	s_andn2_b64 vcc, exec, s[34:35]
	s_cbranch_vccnz .LBB0_970
	s_barrier

.LBB0_1121:
	v_add_u32_e32 v176, s91, v178
	ds_read_b128 v[172:175], v176
	ds_read_b128 v[182:185], v176 offset:1024
	ds_read_b128 v[186:189], v176 offset:2048
	ds_read_b128 v[190:193], v176 offset:3072
	v_add_u32_e32 v176, s92, v178
	ds_read_b128 v[194:197], v176
	ds_read_b128 v[198:201], v176 offset:1024
	ds_read_b128 v[202:205], v176 offset:2048
	ds_read_b128 v[206:209], v176 offset:3072
	s_add_u32 s76, s74, 0x100
	s_addc_u32 s77, s75, 0
	s_cmp_eq_u32 s16, 40
	s_cselect_b32 s89, s11, s77
	s_cselect_b32 s88, s10, s76
	s_cselect_b32 s87, s57, s5
	s_cselect_b32 s86, s56, s4
	v_lshl_add_u64 v[176:177], s[74:75], 0, v[164:165]
	s_add_i32 m0, s61, 0xc000
	ds_read_b128 v[210:213], v180
	ds_read_b128 v[214:217], v180 offset:1024
	ds_read_b128 v[218:221], v180 offset:2048
	ds_read_b128 v[222:225], v180 offset:3072
	ds_read_b128 v[226:229], v180 offset:4096
	ds_read_b128 v[232:235], v180 offset:5120
	ds_read_b128 v[236:239], v180 offset:6144
	ds_read_b128 v[240:243], v180 offset:7168
	global_load_lds_dwordx4 v[176:177], off
	v_lshl_add_u64 v[176:177], s[74:75], 0, v[166:167]
	s_add_i32 m0, s61, 0xe000
	s_nop 0
	global_load_lds_dwordx4 v[176:177], off
	s_waitcnt vmcnt(8)
	s_waitcnt lgkmcnt(0)
	s_barrier
	s_waitcnt lgkmcnt(0)
	v_mfma_f32_16x16x32_bf16 v[124:127], v[172:175], v[210:213], v[124:127]
	v_mfma_f32_16x16x32_bf16 v[120:123], v[186:189], v[210:213], v[120:123]
	v_mfma_f32_16x16x32_bf16 v[108:111], v[172:175], v[218:221], v[108:111]
	v_mfma_f32_16x16x32_bf16 v[104:107], v[186:189], v[218:221], v[104:107]
	v_mfma_f32_16x16x32_bf16 v[92:95], v[172:175], v[226:229], v[92:95]
	v_mfma_f32_16x16x32_bf16 v[88:91], v[186:189], v[226:229], v[88:91]
	v_mfma_f32_16x16x32_bf16 v[76:79], v[172:175], v[236:239], v[76:79]
	v_mfma_f32_16x16x32_bf16 v[72:75], v[186:189], v[236:239], v[72:75]
	v_mfma_f32_16x16x32_bf16 v[124:127], v[182:185], v[214:217], v[124:127]
	v_mfma_f32_16x16x32_bf16 v[120:123], v[190:193], v[214:217], v[120:123]
	v_mfma_f32_16x16x32_bf16 v[108:111], v[182:185], v[222:225], v[108:111]
	v_mfma_f32_16x16x32_bf16 v[104:107], v[190:193], v[222:225], v[104:107]
	v_mfma_f32_16x16x32_bf16 v[92:95], v[182:185], v[232:235], v[92:95]
	v_mfma_f32_16x16x32_bf16 v[88:91], v[190:193], v[232:235], v[88:91]
	v_mfma_f32_16x16x32_bf16 v[76:79], v[182:185], v[240:243], v[76:79]
	v_mfma_f32_16x16x32_bf16 v[72:75], v[190:193], v[240:243], v[72:75]
	v_mfma_f32_16x16x32_bf16 v[116:119], v[194:197], v[210:213], v[116:119]
	v_mfma_f32_16x16x32_bf16 v[112:115], v[202:205], v[210:213], v[112:115]
	v_mfma_f32_16x16x32_bf16 v[100:103], v[194:197], v[218:221], v[100:103]
	v_mfma_f32_16x16x32_bf16 v[96:99], v[202:205], v[218:221], v[96:99]
	v_mfma_f32_16x16x32_bf16 v[84:87], v[194:197], v[226:229], v[84:87]
	v_mfma_f32_16x16x32_bf16 v[80:83], v[202:205], v[226:229], v[80:83]
	v_mfma_f32_16x16x32_bf16 v[68:71], v[194:197], v[236:239], v[68:71]
	v_mfma_f32_16x16x32_bf16 v[64:67], v[202:205], v[236:239], v[64:67]
	v_mfma_f32_16x16x32_bf16 v[116:119], v[198:201], v[214:217], v[116:119]
	v_mfma_f32_16x16x32_bf16 v[112:115], v[206:209], v[214:217], v[112:115]
	v_mfma_f32_16x16x32_bf16 v[100:103], v[198:201], v[222:225], v[100:103]
	v_mfma_f32_16x16x32_bf16 v[96:99], v[206:209], v[222:225], v[96:99]
	v_mfma_f32_16x16x32_bf16 v[84:87], v[198:201], v[232:235], v[84:87]
	v_mfma_f32_16x16x32_bf16 v[80:83], v[206:209], v[232:235], v[80:83]
	v_mfma_f32_16x16x32_bf16 v[68:71], v[198:201], v[240:243], v[68:71]
	v_mfma_f32_16x16x32_bf16 v[64:67], v[206:209], v[240:243], v[64:67]
	s_barrier
	s_add_i32 s20, s91, s60
	v_lshl_add_u64 v[176:177], s[86:87], 0, v[128:129]
	s_mov_b32 m0, s20
	ds_read_b128 v[210:213], v180 offset:16384
	ds_read_b128 v[214:217], v180 offset:17408
	ds_read_b128 v[218:221], v180 offset:18432
	ds_read_b128 v[222:225], v180 offset:19456
	ds_read_b128 v[226:229], v180 offset:20480
	ds_read_b128 v[232:235], v180 offset:21504
	ds_read_b128 v[236:239], v180 offset:22528
	ds_read_b128 v[240:243], v180 offset:23552
	global_load_lds_dwordx4 v[176:177], off
	s_add_i32 m0, s20, 0x2000
	s_add_u32 s20, s86, 0xb0000
	v_lshl_add_u64 v[244:245], s[86:87], 0, v[130:131]
	s_addc_u32 s21, s87, 0
	s_add_i32 s30, s92, s60
	global_load_lds_dwordx4 v[244:245], off
	v_lshl_add_u64 v[246:247], s[20:21], 0, v[128:129]
	s_mov_b32 m0, s30
	v_lshl_add_u64 v[248:249], s[88:89], 0, v[130:131]
	global_load_lds_dwordx4 v[246:247], off
	v_lshl_add_u64 v[246:247], s[20:21], 0, v[130:131]
	s_add_i32 m0, s30, 0x2000
	s_nop 0
	global_load_lds_dwordx4 v[246:247], off
	v_lshl_add_u64 v[246:247], s[88:89], 0, v[128:129]
	s_mov_b32 m0, s61
	s_nop 0
	global_load_lds_dwordx4 v[246:247], off
	s_mov_b32 m0, s62
	s_nop 0
	global_load_lds_dwordx4 v[248:249], off
	s_waitcnt vmcnt(8)
	s_waitcnt lgkmcnt(0)
	s_barrier
	s_waitcnt lgkmcnt(0)
	v_mfma_f32_16x16x32_bf16 v[60:63], v[172:175], v[210:213], v[60:63]
	v_mfma_f32_16x16x32_bf16 v[56:59], v[186:189], v[210:213], v[56:59]
	v_mfma_f32_16x16x32_bf16 v[44:47], v[172:175], v[218:221], v[44:47]
	v_mfma_f32_16x16x32_bf16 v[40:43], v[186:189], v[218:221], v[40:43]
	v_mfma_f32_16x16x32_bf16 v[28:31], v[172:175], v[226:229], v[28:31]
	v_mfma_f32_16x16x32_bf16 v[24:27], v[186:189], v[226:229], v[24:27]
	v_mfma_f32_16x16x32_bf16 v[12:15], v[172:175], v[236:239], v[12:15]
	v_mfma_f32_16x16x32_bf16 v[8:11], v[186:189], v[236:239], v[8:11]
	v_mfma_f32_16x16x32_bf16 v[60:63], v[182:185], v[214:217], v[60:63]
	v_mfma_f32_16x16x32_bf16 v[56:59], v[190:193], v[214:217], v[56:59]
	v_mfma_f32_16x16x32_bf16 v[44:47], v[182:185], v[222:225], v[44:47]
	v_mfma_f32_16x16x32_bf16 v[40:43], v[190:193], v[222:225], v[40:43]
	v_mfma_f32_16x16x32_bf16 v[28:31], v[182:185], v[232:235], v[28:31]
	v_mfma_f32_16x16x32_bf16 v[24:27], v[190:193], v[232:235], v[24:27]
	v_mfma_f32_16x16x32_bf16 v[12:15], v[182:185], v[240:243], v[12:15]
	v_mfma_f32_16x16x32_bf16 v[8:11], v[190:193], v[240:243], v[8:11]
	v_mfma_f32_16x16x32_bf16 v[52:55], v[194:197], v[210:213], v[52:55]
	v_mfma_f32_16x16x32_bf16 v[48:51], v[202:205], v[210:213], v[48:51]
	v_mfma_f32_16x16x32_bf16 v[36:39], v[194:197], v[218:221], v[36:39]
	v_mfma_f32_16x16x32_bf16 v[32:35], v[202:205], v[218:221], v[32:35]
	v_mfma_f32_16x16x32_bf16 v[20:23], v[194:197], v[226:229], v[20:23]
	v_mfma_f32_16x16x32_bf16 v[16:19], v[202:205], v[226:229], v[16:19]
	v_mfma_f32_16x16x32_bf16 v[4:7], v[194:197], v[236:239], v[4:7]
	v_mfma_f32_16x16x32_bf16 v[0:3], v[202:205], v[236:239], v[0:3]
	v_mfma_f32_16x16x32_bf16 v[52:55], v[198:201], v[214:217], v[52:55]
	v_mfma_f32_16x16x32_bf16 v[48:51], v[206:209], v[214:217], v[48:51]
	v_mfma_f32_16x16x32_bf16 v[36:39], v[198:201], v[222:225], v[36:39]
	v_mfma_f32_16x16x32_bf16 v[32:35], v[206:209], v[222:225], v[32:35]
	v_mfma_f32_16x16x32_bf16 v[20:23], v[198:201], v[232:235], v[20:23]
	v_mfma_f32_16x16x32_bf16 v[16:19], v[206:209], v[232:235], v[16:19]
	v_mfma_f32_16x16x32_bf16 v[4:7], v[198:201], v[240:243], v[4:7]
	v_mfma_f32_16x16x32_bf16 v[0:3], v[206:209], v[240:243], v[0:3]
	s_barrier
	s_add_i32 s30, 0, 0x18000
	s_add_i32 s31, 0, 0x1c000
	v_add_u32_e32 v190, s30, v178
	v_add_u32_e32 v206, s31, v178
	ds_read_b128 v[172:175], v190
	ds_read_b128 v[182:185], v190 offset:1024
	ds_read_b128 v[186:189], v190 offset:2048
	ds_read_b128 v[190:193], v190 offset:3072
	ds_read_b128 v[194:197], v206
	ds_read_b128 v[198:201], v206 offset:1024
	ds_read_b128 v[202:205], v206 offset:2048
	ds_read_b128 v[206:209], v206 offset:3072
	s_add_u32 s20, s88, 0xb0000
	s_addc_u32 s21, s89, 0
	s_mov_b32 m0, s63
	v_lshl_add_u64 v[250:251], s[20:21], 0, v[128:129]
	ds_read_b128 v[210:213], v180 offset:32768
	ds_read_b128 v[214:217], v180 offset:33792
	ds_read_b128 v[218:221], v180 offset:34816
	ds_read_b128 v[222:225], v180 offset:35840
	ds_read_b128 v[226:229], v180 offset:36864
	ds_read_b128 v[232:235], v180 offset:37888
	ds_read_b128 v[236:239], v180 offset:38912
	ds_read_b128 v[240:243], v180 offset:39936
	global_load_lds_dwordx4 v[250:251], off
	v_lshl_add_u64 v[250:251], s[20:21], 0, v[130:131]
	s_mov_b32 m0, s64
	s_nop 0
	global_load_lds_dwordx4 v[250:251], off
	s_waitcnt vmcnt(8)
	s_waitcnt lgkmcnt(0)
	s_barrier
	s_waitcnt lgkmcnt(0)
	v_mfma_f32_16x16x32_bf16 v[124:127], v[172:175], v[210:213], v[124:127]
	v_mfma_f32_16x16x32_bf16 v[120:123], v[186:189], v[210:213], v[120:123]
	v_mfma_f32_16x16x32_bf16 v[108:111], v[172:175], v[218:221], v[108:111]
	v_mfma_f32_16x16x32_bf16 v[104:107], v[186:189], v[218:221], v[104:107]
	v_mfma_f32_16x16x32_bf16 v[92:95], v[172:175], v[226:229], v[92:95]
	v_mfma_f32_16x16x32_bf16 v[88:91], v[186:189], v[226:229], v[88:91]
	v_mfma_f32_16x16x32_bf16 v[76:79], v[172:175], v[236:239], v[76:79]
	v_mfma_f32_16x16x32_bf16 v[72:75], v[186:189], v[236:239], v[72:75]
	v_mfma_f32_16x16x32_bf16 v[124:127], v[182:185], v[214:217], v[124:127]
	v_mfma_f32_16x16x32_bf16 v[120:123], v[190:193], v[214:217], v[120:123]
	v_mfma_f32_16x16x32_bf16 v[108:111], v[182:185], v[222:225], v[108:111]
	v_mfma_f32_16x16x32_bf16 v[104:107], v[190:193], v[222:225], v[104:107]
	v_mfma_f32_16x16x32_bf16 v[92:95], v[182:185], v[232:235], v[92:95]
	v_mfma_f32_16x16x32_bf16 v[88:91], v[190:193], v[232:235], v[88:91]
	v_mfma_f32_16x16x32_bf16 v[76:79], v[182:185], v[240:243], v[76:79]
	v_mfma_f32_16x16x32_bf16 v[72:75], v[190:193], v[240:243], v[72:75]
	v_mfma_f32_16x16x32_bf16 v[116:119], v[194:197], v[210:213], v[116:119]
	v_mfma_f32_16x16x32_bf16 v[112:115], v[202:205], v[210:213], v[112:115]
	v_mfma_f32_16x16x32_bf16 v[100:103], v[194:197], v[218:221], v[100:103]
	v_mfma_f32_16x16x32_bf16 v[96:99], v[202:205], v[218:221], v[96:99]
	v_mfma_f32_16x16x32_bf16 v[84:87], v[194:197], v[226:229], v[84:87]
	v_mfma_f32_16x16x32_bf16 v[80:83], v[202:205], v[226:229], v[80:83]
	v_mfma_f32_16x16x32_bf16 v[68:71], v[194:197], v[236:239], v[68:71]
	v_mfma_f32_16x16x32_bf16 v[64:67], v[202:205], v[236:239], v[64:67]
	v_mfma_f32_16x16x32_bf16 v[116:119], v[198:201], v[214:217], v[116:119]
	v_mfma_f32_16x16x32_bf16 v[112:115], v[206:209], v[214:217], v[112:115]
	v_mfma_f32_16x16x32_bf16 v[100:103], v[198:201], v[222:225], v[100:103]
	v_mfma_f32_16x16x32_bf16 v[96:99], v[206:209], v[222:225], v[96:99]
	v_mfma_f32_16x16x32_bf16 v[84:87], v[198:201], v[232:235], v[84:87]
	v_mfma_f32_16x16x32_bf16 v[80:83], v[206:209], v[232:235], v[80:83]
	v_mfma_f32_16x16x32_bf16 v[68:71], v[198:201], v[240:243], v[68:71]
	v_mfma_f32_16x16x32_bf16 v[64:67], v[206:209], v[240:243], v[64:67]
	s_barrier
	s_add_i32 s20, s30, s60
	v_lshl_add_u64 v[176:177], v[176:177], 0, s[52:53]
	s_mov_b32 m0, s20
	ds_read_b128 v[210:213], v180 offset:49152
	ds_read_b128 v[214:217], v180 offset:50176
	ds_read_b128 v[218:221], v180 offset:51200
	ds_read_b128 v[222:225], v180 offset:52224
	ds_read_b128 v[226:229], v180 offset:53248
	ds_read_b128 v[232:235], v180 offset:54272
	ds_read_b128 v[236:239], v180 offset:55296
	ds_read_b128 v[240:243], v180 offset:56320
	global_load_lds_dwordx4 v[176:177], off
	s_add_i32 m0, s20, 0x2000
	s_add_u32 s20, s86, 0xb0080
	v_lshl_add_u64 v[176:177], v[244:245], 0, s[52:53]
	s_addc_u32 s21, s87, 0
	s_add_i32 s30, s31, s60
	global_load_lds_dwordx4 v[176:177], off
	v_lshl_add_u64 v[176:177], s[20:21], 0, v[128:129]
	s_mov_b32 m0, s30
	s_nop 0
	global_load_lds_dwordx4 v[176:177], off
	v_lshl_add_u64 v[176:177], s[20:21], 0, v[130:131]
	s_add_i32 m0, s30, 0x2000
	s_nop 0
	global_load_lds_dwordx4 v[176:177], off
	v_lshl_add_u64 v[176:177], v[246:247], 0, s[52:53]
	s_mov_b32 m0, s83
	s_nop 0
	global_load_lds_dwordx4 v[176:177], off
	v_lshl_add_u64 v[176:177], v[248:249], 0, s[52:53]
	s_mov_b32 m0, s90
	s_nop 0
	global_load_lds_dwordx4 v[176:177], off
	s_waitcnt vmcnt(8)
	s_waitcnt lgkmcnt(0)
	s_barrier
	s_waitcnt lgkmcnt(0)
	v_mfma_f32_16x16x32_bf16 v[60:63], v[172:175], v[210:213], v[60:63]
	v_mfma_f32_16x16x32_bf16 v[56:59], v[186:189], v[210:213], v[56:59]
	v_mfma_f32_16x16x32_bf16 v[44:47], v[172:175], v[218:221], v[44:47]
	v_mfma_f32_16x16x32_bf16 v[40:43], v[186:189], v[218:221], v[40:43]
	v_mfma_f32_16x16x32_bf16 v[28:31], v[172:175], v[226:229], v[28:31]
	v_mfma_f32_16x16x32_bf16 v[24:27], v[186:189], v[226:229], v[24:27]
	v_mfma_f32_16x16x32_bf16 v[12:15], v[172:175], v[236:239], v[12:15]
	v_mfma_f32_16x16x32_bf16 v[8:11], v[186:189], v[236:239], v[8:11]
	v_mfma_f32_16x16x32_bf16 v[60:63], v[182:185], v[214:217], v[60:63]
	v_mfma_f32_16x16x32_bf16 v[56:59], v[190:193], v[214:217], v[56:59]
	v_mfma_f32_16x16x32_bf16 v[44:47], v[182:185], v[222:225], v[44:47]
	v_mfma_f32_16x16x32_bf16 v[40:43], v[190:193], v[222:225], v[40:43]
	v_mfma_f32_16x16x32_bf16 v[28:31], v[182:185], v[232:235], v[28:31]
	v_mfma_f32_16x16x32_bf16 v[24:27], v[190:193], v[232:235], v[24:27]
	v_mfma_f32_16x16x32_bf16 v[12:15], v[182:185], v[240:243], v[12:15]
	v_mfma_f32_16x16x32_bf16 v[8:11], v[190:193], v[240:243], v[8:11]
	v_mfma_f32_16x16x32_bf16 v[52:55], v[194:197], v[210:213], v[52:55]
	v_mfma_f32_16x16x32_bf16 v[48:51], v[202:205], v[210:213], v[48:51]
	v_mfma_f32_16x16x32_bf16 v[36:39], v[194:197], v[218:221], v[36:39]
	v_mfma_f32_16x16x32_bf16 v[32:35], v[202:205], v[218:221], v[32:35]
	v_mfma_f32_16x16x32_bf16 v[20:23], v[194:197], v[226:229], v[20:23]
	v_mfma_f32_16x16x32_bf16 v[16:19], v[202:205], v[226:229], v[16:19]
	v_mfma_f32_16x16x32_bf16 v[4:7], v[194:197], v[236:239], v[4:7]
	v_mfma_f32_16x16x32_bf16 v[0:3], v[202:205], v[236:239], v[0:3]
	v_mfma_f32_16x16x32_bf16 v[52:55], v[198:201], v[214:217], v[52:55]
	v_mfma_f32_16x16x32_bf16 v[48:51], v[206:209], v[214:217], v[48:51]
	v_mfma_f32_16x16x32_bf16 v[36:39], v[198:201], v[222:225], v[36:39]
	v_mfma_f32_16x16x32_bf16 v[32:35], v[206:209], v[222:225], v[32:35]
	v_mfma_f32_16x16x32_bf16 v[20:23], v[198:201], v[232:235], v[20:23]
	v_mfma_f32_16x16x32_bf16 v[16:19], v[206:209], v[232:235], v[16:19]
	v_mfma_f32_16x16x32_bf16 v[4:7], v[198:201], v[240:243], v[4:7]
	v_mfma_f32_16x16x32_bf16 v[0:3], v[206:209], v[240:243], v[0:3]
	s_barrier
	s_add_i32 s16, s16, 2
	s_add_u32 s4, s4, 0x100
	s_addc_u32 s5, s5, 0
	s_cmp_gt_u32 s16, 41
	s_mov_b64 s[74:75], s[76:77]
	s_cbranch_scc0 .LBB0_1121
	s_and_b64 vcc, exec, s[54:55]
	s_cbranch_vccz .LBB0_1124
	s_barrier

.LBB0_1209:
	ds_read_b128 v[116:119], v173
	ds_read_b128 v[124:127], v173 offset:1024
	ds_read_b128 v[128:131], v173 offset:2048
	ds_read_b128 v[132:135], v173 offset:3072
	ds_read_b128 v[160:163], v174
	ds_read_b128 v[164:167], v174 offset:1024
	ds_read_b128 v[178:181], v174 offset:2048
	ds_read_b128 v[182:185], v174 offset:3072
	s_add_u32 s76, s74, 0xfffc0080
	s_addc_u32 s77, s75, -1
	s_cmp_eq_u32 s89, 12
	s_cselect_b32 s87, s4, s77
	s_cselect_b32 s86, s5, s76
	s_cselect_b32 s77, s49, s88
	s_cselect_b32 s76, s53, s83
	v_lshl_add_u64 v[168:169], s[74:75], 0, v[152:153]
	s_add_i32 m0, s59, 0xc000
	ds_read_b128 v[186:189], v175
	ds_read_b128 v[190:193], v175 offset:1024
	ds_read_b128 v[194:197], v175 offset:2048
	ds_read_b128 v[198:201], v175 offset:3072
	ds_read_b128 v[202:205], v175 offset:4096
	ds_read_b128 v[206:209], v175 offset:5120
	ds_read_b128 v[210:213], v175 offset:6144
	ds_read_b128 v[214:217], v175 offset:7168
	global_load_lds_dwordx4 v[168:169], off
	v_lshl_add_u64 v[168:169], s[74:75], 0, v[154:155]
	s_add_i32 m0, s59, 0xe000
	s_nop 0
	global_load_lds_dwordx4 v[168:169], off
	s_waitcnt vmcnt(8)
	s_waitcnt lgkmcnt(0)
	s_barrier
	s_waitcnt lgkmcnt(0)
	v_mfma_f32_16x16x32_bf16 v[140:143], v[116:119], v[186:189], v[140:143]
	v_mfma_f32_16x16x32_bf16 v[136:139], v[128:131], v[186:189], v[136:139]
	v_mfma_f32_16x16x32_bf16 v[108:111], v[116:119], v[194:197], v[108:111]
	v_mfma_f32_16x16x32_bf16 v[104:107], v[128:131], v[194:197], v[104:107]
	v_mfma_f32_16x16x32_bf16 v[92:95], v[116:119], v[202:205], v[92:95]
	v_mfma_f32_16x16x32_bf16 v[88:91], v[128:131], v[202:205], v[88:91]
	v_mfma_f32_16x16x32_bf16 v[76:79], v[116:119], v[210:213], v[76:79]
	v_mfma_f32_16x16x32_bf16 v[72:75], v[128:131], v[210:213], v[72:75]
	v_mfma_f32_16x16x32_bf16 v[140:143], v[124:127], v[190:193], v[140:143]
	v_mfma_f32_16x16x32_bf16 v[136:139], v[132:135], v[190:193], v[136:139]
	v_mfma_f32_16x16x32_bf16 v[108:111], v[124:127], v[198:201], v[108:111]
	v_mfma_f32_16x16x32_bf16 v[104:107], v[132:135], v[198:201], v[104:107]
	v_mfma_f32_16x16x32_bf16 v[92:95], v[124:127], v[206:209], v[92:95]
	v_mfma_f32_16x16x32_bf16 v[88:91], v[132:135], v[206:209], v[88:91]
	v_mfma_f32_16x16x32_bf16 v[76:79], v[124:127], v[214:217], v[76:79]
	v_mfma_f32_16x16x32_bf16 v[72:75], v[132:135], v[214:217], v[72:75]
	v_mfma_f32_16x16x32_bf16 v[120:123], v[160:163], v[186:189], v[120:123]
	v_mfma_f32_16x16x32_bf16 v[112:115], v[178:181], v[186:189], v[112:115]
	v_mfma_f32_16x16x32_bf16 v[100:103], v[160:163], v[194:197], v[100:103]
	v_mfma_f32_16x16x32_bf16 v[96:99], v[178:181], v[194:197], v[96:99]
	v_mfma_f32_16x16x32_bf16 v[84:87], v[160:163], v[202:205], v[84:87]
	v_mfma_f32_16x16x32_bf16 v[80:83], v[178:181], v[202:205], v[80:83]
	v_mfma_f32_16x16x32_bf16 v[68:71], v[160:163], v[210:213], v[68:71]
	v_mfma_f32_16x16x32_bf16 v[64:67], v[178:181], v[210:213], v[64:67]
	v_mfma_f32_16x16x32_bf16 v[120:123], v[164:167], v[190:193], v[120:123]
	v_mfma_f32_16x16x32_bf16 v[112:115], v[182:185], v[190:193], v[112:115]
	v_mfma_f32_16x16x32_bf16 v[100:103], v[164:167], v[198:201], v[100:103]
	v_mfma_f32_16x16x32_bf16 v[96:99], v[182:185], v[198:201], v[96:99]
	v_mfma_f32_16x16x32_bf16 v[84:87], v[164:167], v[206:209], v[84:87]
	v_mfma_f32_16x16x32_bf16 v[80:83], v[182:185], v[206:209], v[80:83]
	v_mfma_f32_16x16x32_bf16 v[68:71], v[164:167], v[214:217], v[68:71]
	v_mfma_f32_16x16x32_bf16 v[64:67], v[182:185], v[214:217], v[64:67]
	s_barrier
	s_add_i32 s90, s78, s21
	v_lshl_add_u64 v[168:169], s[76:77], 0, v[148:149]
	s_mov_b32 m0, s90
	ds_read_b128 v[186:189], v175 offset:16384
	ds_read_b128 v[190:193], v175 offset:17408
	ds_read_b128 v[194:197], v175 offset:18432
	ds_read_b128 v[198:201], v175 offset:19456
	ds_read_b128 v[202:205], v175 offset:20480
	ds_read_b128 v[206:209], v175 offset:21504
	ds_read_b128 v[210:213], v175 offset:22528
	ds_read_b128 v[214:217], v175 offset:23552
	global_load_lds_dwordx4 v[168:169], off
	s_add_i32 m0, s90, 0x2000
	s_add_u32 s90, s76, 0x40000
	v_lshl_add_u64 v[218:219], s[76:77], 0, v[144:145]
	s_addc_u32 s91, s77, 0
	s_add_i32 s92, s79, s21
	global_load_lds_dwordx4 v[218:219], off
	v_lshl_add_u64 v[220:221], s[90:91], 0, v[148:149]
	s_mov_b32 m0, s92
	v_lshl_add_u64 v[222:223], s[86:87], 0, v[146:147]
	global_load_lds_dwordx4 v[220:221], off
	v_lshl_add_u64 v[220:221], s[90:91], 0, v[144:145]
	s_add_i32 m0, s92, 0x2000
	s_nop 0
	global_load_lds_dwordx4 v[220:221], off
	v_lshl_add_u64 v[220:221], s[86:87], 0, v[150:151]
	s_mov_b32 m0, s59
	s_nop 0
	global_load_lds_dwordx4 v[220:221], off
	s_mov_b32 m0, s60
	s_nop 0
	global_load_lds_dwordx4 v[222:223], off
	s_waitcnt vmcnt(8)
	s_waitcnt lgkmcnt(0)
	s_barrier
	s_waitcnt lgkmcnt(0)
	v_mfma_f32_16x16x32_bf16 v[60:63], v[116:119], v[186:189], v[60:63]
	v_mfma_f32_16x16x32_bf16 v[56:59], v[128:131], v[186:189], v[56:59]
	v_mfma_f32_16x16x32_bf16 v[44:47], v[116:119], v[194:197], v[44:47]
	v_mfma_f32_16x16x32_bf16 v[40:43], v[128:131], v[194:197], v[40:43]
	v_mfma_f32_16x16x32_bf16 v[28:31], v[116:119], v[202:205], v[28:31]
	v_mfma_f32_16x16x32_bf16 v[24:27], v[128:131], v[202:205], v[24:27]
	v_mfma_f32_16x16x32_bf16 v[12:15], v[116:119], v[210:213], v[12:15]
	v_mfma_f32_16x16x32_bf16 v[8:11], v[128:131], v[210:213], v[8:11]
	v_mfma_f32_16x16x32_bf16 v[60:63], v[124:127], v[190:193], v[60:63]
	v_mfma_f32_16x16x32_bf16 v[56:59], v[132:135], v[190:193], v[56:59]
	v_mfma_f32_16x16x32_bf16 v[44:47], v[124:127], v[198:201], v[44:47]
	v_mfma_f32_16x16x32_bf16 v[40:43], v[132:135], v[198:201], v[40:43]
	v_mfma_f32_16x16x32_bf16 v[28:31], v[124:127], v[206:209], v[28:31]
	v_mfma_f32_16x16x32_bf16 v[24:27], v[132:135], v[206:209], v[24:27]
	v_mfma_f32_16x16x32_bf16 v[12:15], v[124:127], v[214:217], v[12:15]
	v_mfma_f32_16x16x32_bf16 v[8:11], v[132:135], v[214:217], v[8:11]
	v_mfma_f32_16x16x32_bf16 v[52:55], v[160:163], v[186:189], v[52:55]
	v_mfma_f32_16x16x32_bf16 v[48:51], v[178:181], v[186:189], v[48:51]
	v_mfma_f32_16x16x32_bf16 v[36:39], v[160:163], v[194:197], v[36:39]
	v_mfma_f32_16x16x32_bf16 v[32:35], v[178:181], v[194:197], v[32:35]
	v_mfma_f32_16x16x32_bf16 v[20:23], v[160:163], v[202:205], v[20:23]
	v_mfma_f32_16x16x32_bf16 v[16:19], v[178:181], v[202:205], v[16:19]
	v_mfma_f32_16x16x32_bf16 v[4:7], v[160:163], v[210:213], v[4:7]
	v_mfma_f32_16x16x32_bf16 v[0:3], v[178:181], v[210:213], v[0:3]
	v_mfma_f32_16x16x32_bf16 v[52:55], v[164:167], v[190:193], v[52:55]
	v_mfma_f32_16x16x32_bf16 v[48:51], v[182:185], v[190:193], v[48:51]
	v_mfma_f32_16x16x32_bf16 v[36:39], v[164:167], v[198:201], v[36:39]
	v_mfma_f32_16x16x32_bf16 v[32:35], v[182:185], v[198:201], v[32:35]
	v_mfma_f32_16x16x32_bf16 v[20:23], v[164:167], v[206:209], v[20:23]
	v_mfma_f32_16x16x32_bf16 v[16:19], v[182:185], v[206:209], v[16:19]
	v_mfma_f32_16x16x32_bf16 v[4:7], v[164:167], v[214:217], v[4:7]
	v_mfma_f32_16x16x32_bf16 v[0:3], v[182:185], v[214:217], v[0:3]
	s_barrier
	s_add_i32 s90, 0, 0x18000
	s_add_i32 s91, 0, 0x1c000
	v_add_u32_e32 v132, s90, v171
	v_add_u32_e32 v177, s91, v171
	ds_read_b128 v[116:119], v132
	ds_read_b128 v[124:127], v132 offset:1024
	ds_read_b128 v[128:131], v132 offset:2048
	ds_read_b128 v[132:135], v132 offset:3072
	ds_read_b128 v[160:163], v177
	ds_read_b128 v[164:167], v177 offset:1024
	ds_read_b128 v[178:181], v177 offset:2048
	ds_read_b128 v[182:185], v177 offset:3072
	s_add_u32 s86, s86, 0x40000
	s_addc_u32 s87, s87, 0
	s_mov_b32 m0, s61
	v_lshl_add_u64 v[224:225], s[86:87], 0, v[150:151]
	ds_read_b128 v[186:189], v175 offset:32768
	ds_read_b128 v[190:193], v175 offset:33792
	ds_read_b128 v[194:197], v175 offset:34816
	ds_read_b128 v[198:201], v175 offset:35840
	ds_read_b128 v[202:205], v175 offset:36864
	ds_read_b128 v[206:209], v175 offset:37888
	ds_read_b128 v[210:213], v175 offset:38912
	ds_read_b128 v[214:217], v175 offset:39936
	global_load_lds_dwordx4 v[224:225], off
	v_lshl_add_u64 v[224:225], s[86:87], 0, v[146:147]
	s_mov_b32 m0, s62
	s_nop 0
	global_load_lds_dwordx4 v[224:225], off
	s_waitcnt vmcnt(8)
	s_waitcnt lgkmcnt(0)
	s_barrier
	s_waitcnt lgkmcnt(0)
	v_mfma_f32_16x16x32_bf16 v[140:143], v[116:119], v[186:189], v[140:143]
	v_mfma_f32_16x16x32_bf16 v[136:139], v[128:131], v[186:189], v[136:139]
	v_mfma_f32_16x16x32_bf16 v[108:111], v[116:119], v[194:197], v[108:111]
	v_mfma_f32_16x16x32_bf16 v[104:107], v[128:131], v[194:197], v[104:107]
	v_mfma_f32_16x16x32_bf16 v[92:95], v[116:119], v[202:205], v[92:95]
	v_mfma_f32_16x16x32_bf16 v[88:91], v[128:131], v[202:205], v[88:91]
	v_mfma_f32_16x16x32_bf16 v[76:79], v[116:119], v[210:213], v[76:79]
	v_mfma_f32_16x16x32_bf16 v[72:75], v[128:131], v[210:213], v[72:75]
	v_mfma_f32_16x16x32_bf16 v[140:143], v[124:127], v[190:193], v[140:143]
	v_mfma_f32_16x16x32_bf16 v[136:139], v[132:135], v[190:193], v[136:139]
	v_mfma_f32_16x16x32_bf16 v[108:111], v[124:127], v[198:201], v[108:111]
	v_mfma_f32_16x16x32_bf16 v[104:107], v[132:135], v[198:201], v[104:107]
	v_mfma_f32_16x16x32_bf16 v[92:95], v[124:127], v[206:209], v[92:95]
	v_mfma_f32_16x16x32_bf16 v[88:91], v[132:135], v[206:209], v[88:91]
	v_mfma_f32_16x16x32_bf16 v[76:79], v[124:127], v[214:217], v[76:79]
	v_mfma_f32_16x16x32_bf16 v[72:75], v[132:135], v[214:217], v[72:75]
	v_mfma_f32_16x16x32_bf16 v[120:123], v[160:163], v[186:189], v[120:123]
	v_mfma_f32_16x16x32_bf16 v[112:115], v[178:181], v[186:189], v[112:115]
	v_mfma_f32_16x16x32_bf16 v[100:103], v[160:163], v[194:197], v[100:103]
	v_mfma_f32_16x16x32_bf16 v[96:99], v[178:181], v[194:197], v[96:99]
	v_mfma_f32_16x16x32_bf16 v[84:87], v[160:163], v[202:205], v[84:87]
	v_mfma_f32_16x16x32_bf16 v[80:83], v[178:181], v[202:205], v[80:83]
	v_mfma_f32_16x16x32_bf16 v[68:71], v[160:163], v[210:213], v[68:71]
	v_mfma_f32_16x16x32_bf16 v[64:67], v[178:181], v[210:213], v[64:67]
	v_mfma_f32_16x16x32_bf16 v[120:123], v[164:167], v[190:193], v[120:123]
	v_mfma_f32_16x16x32_bf16 v[112:115], v[182:185], v[190:193], v[112:115]
	v_mfma_f32_16x16x32_bf16 v[100:103], v[164:167], v[198:201], v[100:103]
	v_mfma_f32_16x16x32_bf16 v[96:99], v[182:185], v[198:201], v[96:99]
	v_mfma_f32_16x16x32_bf16 v[84:87], v[164:167], v[206:209], v[84:87]
	v_mfma_f32_16x16x32_bf16 v[80:83], v[182:185], v[206:209], v[80:83]
	v_mfma_f32_16x16x32_bf16 v[68:71], v[164:167], v[214:217], v[68:71]
	v_mfma_f32_16x16x32_bf16 v[64:67], v[182:185], v[214:217], v[64:67]
	s_barrier
	s_add_i32 s86, s90, s21
	v_lshl_add_u64 v[168:169], v[168:169], 0, s[16:17]
	s_mov_b32 m0, s86
	ds_read_b128 v[186:189], v175 offset:49152
	ds_read_b128 v[190:193], v175 offset:50176
	ds_read_b128 v[194:197], v175 offset:51200
	ds_read_b128 v[198:201], v175 offset:52224
	ds_read_b128 v[202:205], v175 offset:53248
	ds_read_b128 v[206:209], v175 offset:54272
	ds_read_b128 v[210:213], v175 offset:55296
	ds_read_b128 v[214:217], v175 offset:56320
	global_load_lds_dwordx4 v[168:169], off
	s_add_i32 m0, s86, 0x2000
	s_add_u32 s76, s76, 0x40080
	v_lshl_add_u64 v[168:169], v[218:219], 0, s[16:17]
	s_addc_u32 s77, s77, 0
	s_add_i32 s86, s91, s21
	global_load_lds_dwordx4 v[168:169], off
	v_lshl_add_u64 v[168:169], s[76:77], 0, v[148:149]
	s_mov_b32 m0, s86
	s_nop 0
	global_load_lds_dwordx4 v[168:169], off
	v_lshl_add_u64 v[168:169], s[76:77], 0, v[144:145]
	s_add_i32 m0, s86, 0x2000
	s_nop 0
	global_load_lds_dwordx4 v[168:169], off
	v_lshl_add_u64 v[168:169], v[220:221], 0, s[16:17]
	s_mov_b32 m0, s66
	s_nop 0
	global_load_lds_dwordx4 v[168:169], off
	v_lshl_add_u64 v[168:169], v[222:223], 0, s[16:17]
	s_mov_b32 m0, s67
	s_nop 0
	global_load_lds_dwordx4 v[168:169], off
	s_waitcnt vmcnt(8)
	s_waitcnt lgkmcnt(0)
	s_barrier
	s_waitcnt lgkmcnt(0)
	v_mfma_f32_16x16x32_bf16 v[60:63], v[116:119], v[186:189], v[60:63]
	v_mfma_f32_16x16x32_bf16 v[56:59], v[128:131], v[186:189], v[56:59]
	v_mfma_f32_16x16x32_bf16 v[44:47], v[116:119], v[194:197], v[44:47]
	v_mfma_f32_16x16x32_bf16 v[40:43], v[128:131], v[194:197], v[40:43]
	v_mfma_f32_16x16x32_bf16 v[28:31], v[116:119], v[202:205], v[28:31]
	v_mfma_f32_16x16x32_bf16 v[24:27], v[128:131], v[202:205], v[24:27]
	v_mfma_f32_16x16x32_bf16 v[12:15], v[116:119], v[210:213], v[12:15]
	v_mfma_f32_16x16x32_bf16 v[8:11], v[128:131], v[210:213], v[8:11]
	v_mfma_f32_16x16x32_bf16 v[60:63], v[124:127], v[190:193], v[60:63]
	v_mfma_f32_16x16x32_bf16 v[56:59], v[132:135], v[190:193], v[56:59]
	v_mfma_f32_16x16x32_bf16 v[44:47], v[124:127], v[198:201], v[44:47]
	v_mfma_f32_16x16x32_bf16 v[40:43], v[132:135], v[198:201], v[40:43]
	v_mfma_f32_16x16x32_bf16 v[28:31], v[124:127], v[206:209], v[28:31]
	v_mfma_f32_16x16x32_bf16 v[24:27], v[132:135], v[206:209], v[24:27]
	v_mfma_f32_16x16x32_bf16 v[12:15], v[124:127], v[214:217], v[12:15]
	v_mfma_f32_16x16x32_bf16 v[8:11], v[132:135], v[214:217], v[8:11]
	v_mfma_f32_16x16x32_bf16 v[52:55], v[160:163], v[186:189], v[52:55]
	v_mfma_f32_16x16x32_bf16 v[48:51], v[178:181], v[186:189], v[48:51]
	v_mfma_f32_16x16x32_bf16 v[36:39], v[160:163], v[194:197], v[36:39]
	v_mfma_f32_16x16x32_bf16 v[32:35], v[178:181], v[194:197], v[32:35]
	v_mfma_f32_16x16x32_bf16 v[20:23], v[160:163], v[202:205], v[20:23]
	v_mfma_f32_16x16x32_bf16 v[16:19], v[178:181], v[202:205], v[16:19]
	v_mfma_f32_16x16x32_bf16 v[4:7], v[160:163], v[210:213], v[4:7]
	v_mfma_f32_16x16x32_bf16 v[0:3], v[178:181], v[210:213], v[0:3]
	v_mfma_f32_16x16x32_bf16 v[52:55], v[164:167], v[190:193], v[52:55]
	v_mfma_f32_16x16x32_bf16 v[48:51], v[182:185], v[190:193], v[48:51]
	v_mfma_f32_16x16x32_bf16 v[36:39], v[164:167], v[198:201], v[36:39]
	v_mfma_f32_16x16x32_bf16 v[32:35], v[182:185], v[198:201], v[32:35]
	v_mfma_f32_16x16x32_bf16 v[20:23], v[164:167], v[206:209], v[20:23]
	v_mfma_f32_16x16x32_bf16 v[16:19], v[182:185], v[206:209], v[16:19]
	v_mfma_f32_16x16x32_bf16 v[4:7], v[164:167], v[214:217], v[4:7]
	v_mfma_f32_16x16x32_bf16 v[0:3], v[182:185], v[214:217], v[0:3]
	s_barrier
	s_add_i32 s89, s89, 2
	s_add_u32 s74, s74, 0x100
	s_addc_u32 s75, s75, 0
	s_add_u32 s83, s83, 0x100
	s_addc_u32 s88, s88, 0
	s_cmp_gt_u32 s89, 13
	s_cbranch_scc0 .LBB0_1209
	s_and_b64 vcc, exec, s[34:35]
	s_cbranch_vccz .LBB0_1212
	s_barrier

.LBB0_1665:
	v_add_u32_e32 v176, s63, v178
	ds_read_b128 v[172:175], v176
	ds_read_b128 v[182:185], v176 offset:1024
	ds_read_b128 v[186:189], v176 offset:2048
	ds_read_b128 v[190:193], v176 offset:3072
	v_add_u32_e32 v176, s64, v178
	ds_read_b128 v[194:197], v176
	ds_read_b128 v[198:201], v176 offset:1024
	ds_read_b128 v[202:205], v176 offset:2048
	ds_read_b128 v[206:209], v176 offset:3072
	s_add_u32 s41, s42, 0xfffc0080
	s_addc_u32 s44, s43, -1
	s_cmp_eq_u32 s35, 12
	s_cselect_b32 s47, s4, s44
	s_cselect_b32 s46, s5, s41
	s_cselect_b32 s45, s14, s29
	s_cselect_b32 s44, s20, s21
	v_lshl_add_u64 v[176:177], s[42:43], 0, v[164:165]
	s_add_i32 m0, s49, 0xc000
	ds_read_b128 v[210:213], v180
	ds_read_b128 v[214:217], v180 offset:1024
	ds_read_b128 v[218:221], v180 offset:2048
	ds_read_b128 v[222:225], v180 offset:3072
	ds_read_b128 v[226:229], v180 offset:4096
	ds_read_b128 v[232:235], v180 offset:5120
	ds_read_b128 v[236:239], v180 offset:6144
	ds_read_b128 v[240:243], v180 offset:7168
	global_load_lds_dwordx4 v[176:177], off
	v_lshl_add_u64 v[176:177], s[42:43], 0, v[166:167]
	s_add_i32 m0, s49, 0xe000
	s_nop 0
	global_load_lds_dwordx4 v[176:177], off
	s_waitcnt vmcnt(8)
	s_waitcnt lgkmcnt(0)
	s_barrier
	s_waitcnt lgkmcnt(0)
	v_mfma_f32_16x16x32_bf16 v[124:127], v[172:175], v[210:213], v[124:127]
	v_mfma_f32_16x16x32_bf16 v[120:123], v[186:189], v[210:213], v[120:123]
	v_mfma_f32_16x16x32_bf16 v[108:111], v[172:175], v[218:221], v[108:111]
	v_mfma_f32_16x16x32_bf16 v[104:107], v[186:189], v[218:221], v[104:107]
	v_mfma_f32_16x16x32_bf16 v[92:95], v[172:175], v[226:229], v[92:95]
	v_mfma_f32_16x16x32_bf16 v[88:91], v[186:189], v[226:229], v[88:91]
	v_mfma_f32_16x16x32_bf16 v[76:79], v[172:175], v[236:239], v[76:79]
	v_mfma_f32_16x16x32_bf16 v[72:75], v[186:189], v[236:239], v[72:75]
	v_mfma_f32_16x16x32_bf16 v[124:127], v[182:185], v[214:217], v[124:127]
	v_mfma_f32_16x16x32_bf16 v[120:123], v[190:193], v[214:217], v[120:123]
	v_mfma_f32_16x16x32_bf16 v[108:111], v[182:185], v[222:225], v[108:111]
	v_mfma_f32_16x16x32_bf16 v[104:107], v[190:193], v[222:225], v[104:107]
	v_mfma_f32_16x16x32_bf16 v[92:95], v[182:185], v[232:235], v[92:95]
	v_mfma_f32_16x16x32_bf16 v[88:91], v[190:193], v[232:235], v[88:91]
	v_mfma_f32_16x16x32_bf16 v[76:79], v[182:185], v[240:243], v[76:79]
	v_mfma_f32_16x16x32_bf16 v[72:75], v[190:193], v[240:243], v[72:75]
	v_mfma_f32_16x16x32_bf16 v[116:119], v[194:197], v[210:213], v[116:119]
	v_mfma_f32_16x16x32_bf16 v[112:115], v[202:205], v[210:213], v[112:115]
	v_mfma_f32_16x16x32_bf16 v[100:103], v[194:197], v[218:221], v[100:103]
	v_mfma_f32_16x16x32_bf16 v[96:99], v[202:205], v[218:221], v[96:99]
	v_mfma_f32_16x16x32_bf16 v[84:87], v[194:197], v[226:229], v[84:87]
	v_mfma_f32_16x16x32_bf16 v[80:83], v[202:205], v[226:229], v[80:83]
	v_mfma_f32_16x16x32_bf16 v[68:71], v[194:197], v[236:239], v[68:71]
	v_mfma_f32_16x16x32_bf16 v[64:67], v[202:205], v[236:239], v[64:67]
	v_mfma_f32_16x16x32_bf16 v[116:119], v[198:201], v[214:217], v[116:119]
	v_mfma_f32_16x16x32_bf16 v[112:115], v[206:209], v[214:217], v[112:115]
	v_mfma_f32_16x16x32_bf16 v[100:103], v[198:201], v[222:225], v[100:103]
	v_mfma_f32_16x16x32_bf16 v[96:99], v[206:209], v[222:225], v[96:99]
	v_mfma_f32_16x16x32_bf16 v[84:87], v[198:201], v[232:235], v[84:87]
	v_mfma_f32_16x16x32_bf16 v[80:83], v[206:209], v[232:235], v[80:83]
	v_mfma_f32_16x16x32_bf16 v[68:71], v[198:201], v[240:243], v[68:71]
	v_mfma_f32_16x16x32_bf16 v[64:67], v[206:209], v[240:243], v[64:67]
	s_barrier
	s_add_i32 s41, s63, s30
	v_lshl_add_u64 v[176:177], s[44:45], 0, v[128:129]
	s_mov_b32 m0, s41
	ds_read_b128 v[210:213], v180 offset:16384
	ds_read_b128 v[214:217], v180 offset:17408
	ds_read_b128 v[218:221], v180 offset:18432
	ds_read_b128 v[222:225], v180 offset:19456
	ds_read_b128 v[226:229], v180 offset:20480
	ds_read_b128 v[232:235], v180 offset:21504
	ds_read_b128 v[236:239], v180 offset:22528
	ds_read_b128 v[240:243], v180 offset:23552
	global_load_lds_dwordx4 v[176:177], off
	s_add_i32 m0, s41, 0x2000
	s_add_u32 s66, s44, 0x40000
	v_lshl_add_u64 v[244:245], s[44:45], 0, v[130:131]
	s_addc_u32 s67, s45, 0
	s_add_i32 s41, s64, s30
	global_load_lds_dwordx4 v[244:245], off
	v_lshl_add_u64 v[246:247], s[66:67], 0, v[128:129]
	s_mov_b32 m0, s41
	v_lshl_add_u64 v[248:249], s[46:47], 0, v[130:131]
	global_load_lds_dwordx4 v[246:247], off
	v_lshl_add_u64 v[246:247], s[66:67], 0, v[130:131]
	s_add_i32 m0, s41, 0x2000
	s_nop 0
	global_load_lds_dwordx4 v[246:247], off
	v_lshl_add_u64 v[246:247], s[46:47], 0, v[128:129]
	s_mov_b32 m0, s49
	s_nop 0
	global_load_lds_dwordx4 v[246:247], off
	s_mov_b32 m0, s52
	s_nop 0
	global_load_lds_dwordx4 v[248:249], off
	s_waitcnt vmcnt(8)
	s_waitcnt lgkmcnt(0)
	s_barrier
	s_waitcnt lgkmcnt(0)
	v_mfma_f32_16x16x32_bf16 v[60:63], v[172:175], v[210:213], v[60:63]
	v_mfma_f32_16x16x32_bf16 v[56:59], v[186:189], v[210:213], v[56:59]
	v_mfma_f32_16x16x32_bf16 v[44:47], v[172:175], v[218:221], v[44:47]
	v_mfma_f32_16x16x32_bf16 v[40:43], v[186:189], v[218:221], v[40:43]
	v_mfma_f32_16x16x32_bf16 v[28:31], v[172:175], v[226:229], v[28:31]
	v_mfma_f32_16x16x32_bf16 v[24:27], v[186:189], v[226:229], v[24:27]
	v_mfma_f32_16x16x32_bf16 v[12:15], v[172:175], v[236:239], v[12:15]
	v_mfma_f32_16x16x32_bf16 v[8:11], v[186:189], v[236:239], v[8:11]
	v_mfma_f32_16x16x32_bf16 v[60:63], v[182:185], v[214:217], v[60:63]
	v_mfma_f32_16x16x32_bf16 v[56:59], v[190:193], v[214:217], v[56:59]
	v_mfma_f32_16x16x32_bf16 v[44:47], v[182:185], v[222:225], v[44:47]
	v_mfma_f32_16x16x32_bf16 v[40:43], v[190:193], v[222:225], v[40:43]
	v_mfma_f32_16x16x32_bf16 v[28:31], v[182:185], v[232:235], v[28:31]
	v_mfma_f32_16x16x32_bf16 v[24:27], v[190:193], v[232:235], v[24:27]
	v_mfma_f32_16x16x32_bf16 v[12:15], v[182:185], v[240:243], v[12:15]
	v_mfma_f32_16x16x32_bf16 v[8:11], v[190:193], v[240:243], v[8:11]
	v_mfma_f32_16x16x32_bf16 v[52:55], v[194:197], v[210:213], v[52:55]
	v_mfma_f32_16x16x32_bf16 v[48:51], v[202:205], v[210:213], v[48:51]
	v_mfma_f32_16x16x32_bf16 v[36:39], v[194:197], v[218:221], v[36:39]
	v_mfma_f32_16x16x32_bf16 v[32:35], v[202:205], v[218:221], v[32:35]
	v_mfma_f32_16x16x32_bf16 v[20:23], v[194:197], v[226:229], v[20:23]
	v_mfma_f32_16x16x32_bf16 v[16:19], v[202:205], v[226:229], v[16:19]
	v_mfma_f32_16x16x32_bf16 v[4:7], v[194:197], v[236:239], v[4:7]
	v_mfma_f32_16x16x32_bf16 v[0:3], v[202:205], v[236:239], v[0:3]
	v_mfma_f32_16x16x32_bf16 v[52:55], v[198:201], v[214:217], v[52:55]
	v_mfma_f32_16x16x32_bf16 v[48:51], v[206:209], v[214:217], v[48:51]
	v_mfma_f32_16x16x32_bf16 v[36:39], v[198:201], v[222:225], v[36:39]
	v_mfma_f32_16x16x32_bf16 v[32:35], v[206:209], v[222:225], v[32:35]
	v_mfma_f32_16x16x32_bf16 v[20:23], v[198:201], v[232:235], v[20:23]
	v_mfma_f32_16x16x32_bf16 v[16:19], v[206:209], v[232:235], v[16:19]
	v_mfma_f32_16x16x32_bf16 v[4:7], v[198:201], v[240:243], v[4:7]
	v_mfma_f32_16x16x32_bf16 v[0:3], v[206:209], v[240:243], v[0:3]
	s_barrier
	s_add_i32 s41, 0, 0x18000
	s_add_i32 s66, 0, 0x1c000
	v_add_u32_e32 v190, s41, v178
	v_add_u32_e32 v206, s66, v178
	ds_read_b128 v[172:175], v190
	ds_read_b128 v[182:185], v190 offset:1024
	ds_read_b128 v[186:189], v190 offset:2048
	ds_read_b128 v[190:193], v190 offset:3072
	ds_read_b128 v[194:197], v206
	ds_read_b128 v[198:201], v206 offset:1024
	ds_read_b128 v[202:205], v206 offset:2048
	ds_read_b128 v[206:209], v206 offset:3072
	s_add_u32 s46, s46, 0x40000
	s_addc_u32 s47, s47, 0
	s_mov_b32 m0, s53
	v_lshl_add_u64 v[250:251], s[46:47], 0, v[128:129]
	ds_read_b128 v[210:213], v180 offset:32768
	ds_read_b128 v[214:217], v180 offset:33792
	ds_read_b128 v[218:221], v180 offset:34816
	ds_read_b128 v[222:225], v180 offset:35840
	ds_read_b128 v[226:229], v180 offset:36864
	ds_read_b128 v[232:235], v180 offset:37888
	ds_read_b128 v[236:239], v180 offset:38912
	ds_read_b128 v[240:243], v180 offset:39936
	global_load_lds_dwordx4 v[250:251], off
	v_lshl_add_u64 v[250:251], s[46:47], 0, v[130:131]
	s_mov_b32 m0, s54
	s_nop 0
	global_load_lds_dwordx4 v[250:251], off
	s_waitcnt vmcnt(8)
	s_waitcnt lgkmcnt(0)
	s_barrier
	s_waitcnt lgkmcnt(0)
	v_mfma_f32_16x16x32_bf16 v[124:127], v[172:175], v[210:213], v[124:127]
	v_mfma_f32_16x16x32_bf16 v[120:123], v[186:189], v[210:213], v[120:123]
	v_mfma_f32_16x16x32_bf16 v[108:111], v[172:175], v[218:221], v[108:111]
	v_mfma_f32_16x16x32_bf16 v[104:107], v[186:189], v[218:221], v[104:107]
	v_mfma_f32_16x16x32_bf16 v[92:95], v[172:175], v[226:229], v[92:95]
	v_mfma_f32_16x16x32_bf16 v[88:91], v[186:189], v[226:229], v[88:91]
	v_mfma_f32_16x16x32_bf16 v[76:79], v[172:175], v[236:239], v[76:79]
	v_mfma_f32_16x16x32_bf16 v[72:75], v[186:189], v[236:239], v[72:75]
	v_mfma_f32_16x16x32_bf16 v[124:127], v[182:185], v[214:217], v[124:127]
	v_mfma_f32_16x16x32_bf16 v[120:123], v[190:193], v[214:217], v[120:123]
	v_mfma_f32_16x16x32_bf16 v[108:111], v[182:185], v[222:225], v[108:111]
	v_mfma_f32_16x16x32_bf16 v[104:107], v[190:193], v[222:225], v[104:107]
	v_mfma_f32_16x16x32_bf16 v[92:95], v[182:185], v[232:235], v[92:95]
	v_mfma_f32_16x16x32_bf16 v[88:91], v[190:193], v[232:235], v[88:91]
	v_mfma_f32_16x16x32_bf16 v[76:79], v[182:185], v[240:243], v[76:79]
	v_mfma_f32_16x16x32_bf16 v[72:75], v[190:193], v[240:243], v[72:75]
	v_mfma_f32_16x16x32_bf16 v[116:119], v[194:197], v[210:213], v[116:119]
	v_mfma_f32_16x16x32_bf16 v[112:115], v[202:205], v[210:213], v[112:115]
	v_mfma_f32_16x16x32_bf16 v[100:103], v[194:197], v[218:221], v[100:103]
	v_mfma_f32_16x16x32_bf16 v[96:99], v[202:205], v[218:221], v[96:99]
	v_mfma_f32_16x16x32_bf16 v[84:87], v[194:197], v[226:229], v[84:87]
	v_mfma_f32_16x16x32_bf16 v[80:83], v[202:205], v[226:229], v[80:83]
	v_mfma_f32_16x16x32_bf16 v[68:71], v[194:197], v[236:239], v[68:71]
	v_mfma_f32_16x16x32_bf16 v[64:67], v[202:205], v[236:239], v[64:67]
	v_mfma_f32_16x16x32_bf16 v[116:119], v[198:201], v[214:217], v[116:119]
	v_mfma_f32_16x16x32_bf16 v[112:115], v[206:209], v[214:217], v[112:115]
	v_mfma_f32_16x16x32_bf16 v[100:103], v[198:201], v[222:225], v[100:103]
	v_mfma_f32_16x16x32_bf16 v[96:99], v[206:209], v[222:225], v[96:99]
	v_mfma_f32_16x16x32_bf16 v[84:87], v[198:201], v[232:235], v[84:87]
	v_mfma_f32_16x16x32_bf16 v[80:83], v[206:209], v[232:235], v[80:83]
	v_mfma_f32_16x16x32_bf16 v[68:71], v[198:201], v[240:243], v[68:71]
	v_mfma_f32_16x16x32_bf16 v[64:67], v[206:209], v[240:243], v[64:67]
	s_barrier
	s_add_i32 s41, s41, s30
	v_lshl_add_u64 v[176:177], v[176:177], 0, s[24:25]
	s_mov_b32 m0, s41
	ds_read_b128 v[210:213], v180 offset:49152
	ds_read_b128 v[214:217], v180 offset:50176
	ds_read_b128 v[218:221], v180 offset:51200
	ds_read_b128 v[222:225], v180 offset:52224
	ds_read_b128 v[226:229], v180 offset:53248
	ds_read_b128 v[232:235], v180 offset:54272
	ds_read_b128 v[236:239], v180 offset:55296
	ds_read_b128 v[240:243], v180 offset:56320
	global_load_lds_dwordx4 v[176:177], off
	s_add_i32 m0, s41, 0x2000
	s_add_u32 s44, s44, 0x40080
	v_lshl_add_u64 v[176:177], v[244:245], 0, s[24:25]
	s_addc_u32 s45, s45, 0
	s_add_i32 s41, s66, s30
	global_load_lds_dwordx4 v[176:177], off
	v_lshl_add_u64 v[176:177], s[44:45], 0, v[128:129]
	s_mov_b32 m0, s41
	s_nop 0
	global_load_lds_dwordx4 v[176:177], off
	v_lshl_add_u64 v[176:177], s[44:45], 0, v[130:131]
	s_add_i32 m0, s41, 0x2000
	s_nop 0
	global_load_lds_dwordx4 v[176:177], off
	v_lshl_add_u64 v[176:177], v[246:247], 0, s[24:25]
	s_mov_b32 m0, s61
	s_nop 0
	global_load_lds_dwordx4 v[176:177], off
	v_lshl_add_u64 v[176:177], v[248:249], 0, s[24:25]
	s_mov_b32 m0, s62
	s_nop 0
	global_load_lds_dwordx4 v[176:177], off
	s_waitcnt vmcnt(8)
	s_waitcnt lgkmcnt(0)
	s_barrier
	s_waitcnt lgkmcnt(0)
	v_mfma_f32_16x16x32_bf16 v[60:63], v[172:175], v[210:213], v[60:63]
	v_mfma_f32_16x16x32_bf16 v[56:59], v[186:189], v[210:213], v[56:59]
	v_mfma_f32_16x16x32_bf16 v[44:47], v[172:175], v[218:221], v[44:47]
	v_mfma_f32_16x16x32_bf16 v[40:43], v[186:189], v[218:221], v[40:43]
	v_mfma_f32_16x16x32_bf16 v[28:31], v[172:175], v[226:229], v[28:31]
	v_mfma_f32_16x16x32_bf16 v[24:27], v[186:189], v[226:229], v[24:27]
	v_mfma_f32_16x16x32_bf16 v[12:15], v[172:175], v[236:239], v[12:15]
	v_mfma_f32_16x16x32_bf16 v[8:11], v[186:189], v[236:239], v[8:11]
	v_mfma_f32_16x16x32_bf16 v[60:63], v[182:185], v[214:217], v[60:63]
	v_mfma_f32_16x16x32_bf16 v[56:59], v[190:193], v[214:217], v[56:59]
	v_mfma_f32_16x16x32_bf16 v[44:47], v[182:185], v[222:225], v[44:47]
	v_mfma_f32_16x16x32_bf16 v[40:43], v[190:193], v[222:225], v[40:43]
	v_mfma_f32_16x16x32_bf16 v[28:31], v[182:185], v[232:235], v[28:31]
	v_mfma_f32_16x16x32_bf16 v[24:27], v[190:193], v[232:235], v[24:27]
	v_mfma_f32_16x16x32_bf16 v[12:15], v[182:185], v[240:243], v[12:15]
	v_mfma_f32_16x16x32_bf16 v[8:11], v[190:193], v[240:243], v[8:11]
	v_mfma_f32_16x16x32_bf16 v[52:55], v[194:197], v[210:213], v[52:55]
	v_mfma_f32_16x16x32_bf16 v[48:51], v[202:205], v[210:213], v[48:51]
	v_mfma_f32_16x16x32_bf16 v[36:39], v[194:197], v[218:221], v[36:39]
	v_mfma_f32_16x16x32_bf16 v[32:35], v[202:205], v[218:221], v[32:35]
	v_mfma_f32_16x16x32_bf16 v[20:23], v[194:197], v[226:229], v[20:23]
	v_mfma_f32_16x16x32_bf16 v[16:19], v[202:205], v[226:229], v[16:19]
	v_mfma_f32_16x16x32_bf16 v[4:7], v[194:197], v[236:239], v[4:7]
	v_mfma_f32_16x16x32_bf16 v[0:3], v[202:205], v[236:239], v[0:3]
	v_mfma_f32_16x16x32_bf16 v[52:55], v[198:201], v[214:217], v[52:55]
	v_mfma_f32_16x16x32_bf16 v[48:51], v[206:209], v[214:217], v[48:51]
	v_mfma_f32_16x16x32_bf16 v[36:39], v[198:201], v[222:225], v[36:39]
	v_mfma_f32_16x16x32_bf16 v[32:35], v[206:209], v[222:225], v[32:35]
	v_mfma_f32_16x16x32_bf16 v[20:23], v[198:201], v[232:235], v[20:23]
	v_mfma_f32_16x16x32_bf16 v[16:19], v[206:209], v[232:235], v[16:19]
	v_mfma_f32_16x16x32_bf16 v[4:7], v[198:201], v[240:243], v[4:7]
	v_mfma_f32_16x16x32_bf16 v[0:3], v[206:209], v[240:243], v[0:3]
	s_barrier
	s_add_i32 s35, s35, 2
	s_add_u32 s42, s42, 0x100
	s_addc_u32 s43, s43, 0
	s_add_u32 s21, s21, 0x100
	s_addc_u32 s29, s29, 0
	s_cmp_gt_u32 s35, 13
	s_cbranch_scc0 .LBB0_1665
	s_and_b64 vcc, exec, s[26:27]
	s_cbranch_vccz .LBB0_1668
	s_barrier

.LBB0_1752:
	ds_read_b128 v[128:131], v167
	ds_read_b128 v[132:135], v167 offset:1024
	ds_read_b128 v[136:139], v167 offset:2048
	ds_read_b128 v[140:143], v167 offset:3072
	ds_read_b128 v[160:163], v168
	ds_read_b128 v[172:175], v168 offset:1024
	ds_read_b128 v[176:179], v168 offset:2048
	ds_read_b128 v[180:183], v168 offset:3072
	s_add_u32 s38, s36, 0xfffc0080
	s_addc_u32 s39, s37, -1
	s_cmp_eq_u32 s56, 12
	s_cselect_b32 s41, s4, s39
	s_cselect_b32 s40, s5, s38
	s_cselect_b32 s39, s25, s55
	s_cselect_b32 s38, s27, s54
	v_lshl_add_u64 v[216:217], s[36:37], 0, v[152:153]
	s_add_i32 m0, s42, 0xc000
	ds_read_b128 v[184:187], v169
	ds_read_b128 v[188:191], v169 offset:1024
	ds_read_b128 v[192:195], v169 offset:2048
	ds_read_b128 v[196:199], v169 offset:3072
	ds_read_b128 v[200:203], v169 offset:4096
	ds_read_b128 v[204:207], v169 offset:5120
	ds_read_b128 v[208:211], v169 offset:6144
	ds_read_b128 v[212:215], v169 offset:7168
	global_load_lds_dwordx4 v[216:217], off
	v_lshl_add_u64 v[216:217], s[36:37], 0, v[154:155]
	s_add_i32 m0, s42, 0xe000
	s_nop 0
	global_load_lds_dwordx4 v[216:217], off
	s_waitcnt vmcnt(8)
	s_waitcnt lgkmcnt(0)
	s_barrier
	s_waitcnt lgkmcnt(0)
	v_mfma_f32_16x16x32_bf16 v[124:127], v[128:131], v[184:187], v[124:127]
	v_mfma_f32_16x16x32_bf16 v[120:123], v[136:139], v[184:187], v[120:123]
	v_mfma_f32_16x16x32_bf16 v[116:119], v[128:131], v[192:195], v[116:119]
	v_mfma_f32_16x16x32_bf16 v[112:115], v[136:139], v[192:195], v[112:115]
	v_mfma_f32_16x16x32_bf16 v[96:99], v[128:131], v[200:203], v[96:99]
	v_mfma_f32_16x16x32_bf16 v[88:91], v[136:139], v[200:203], v[88:91]
	v_mfma_f32_16x16x32_bf16 v[80:83], v[128:131], v[208:211], v[80:83]
	v_mfma_f32_16x16x32_bf16 v[72:75], v[136:139], v[208:211], v[72:75]
	v_mfma_f32_16x16x32_bf16 v[124:127], v[132:135], v[188:191], v[124:127]
	v_mfma_f32_16x16x32_bf16 v[120:123], v[140:143], v[188:191], v[120:123]
	v_mfma_f32_16x16x32_bf16 v[116:119], v[132:135], v[196:199], v[116:119]
	v_mfma_f32_16x16x32_bf16 v[112:115], v[140:143], v[196:199], v[112:115]
	v_mfma_f32_16x16x32_bf16 v[96:99], v[132:135], v[204:207], v[96:99]
	v_mfma_f32_16x16x32_bf16 v[88:91], v[140:143], v[204:207], v[88:91]
	v_mfma_f32_16x16x32_bf16 v[80:83], v[132:135], v[212:215], v[80:83]
	v_mfma_f32_16x16x32_bf16 v[72:75], v[140:143], v[212:215], v[72:75]
	v_mfma_f32_16x16x32_bf16 v[108:111], v[160:163], v[184:187], v[108:111]
	v_mfma_f32_16x16x32_bf16 v[104:107], v[176:179], v[184:187], v[104:107]
	v_mfma_f32_16x16x32_bf16 v[100:103], v[160:163], v[192:195], v[100:103]
	v_mfma_f32_16x16x32_bf16 v[92:95], v[176:179], v[192:195], v[92:95]
	v_mfma_f32_16x16x32_bf16 v[84:87], v[160:163], v[200:203], v[84:87]
	v_mfma_f32_16x16x32_bf16 v[76:79], v[176:179], v[200:203], v[76:79]
	v_mfma_f32_16x16x32_bf16 v[68:71], v[160:163], v[208:211], v[68:71]
	v_mfma_f32_16x16x32_bf16 v[64:67], v[176:179], v[208:211], v[64:67]
	v_mfma_f32_16x16x32_bf16 v[108:111], v[172:175], v[188:191], v[108:111]
	v_mfma_f32_16x16x32_bf16 v[104:107], v[180:183], v[188:191], v[104:107]
	v_mfma_f32_16x16x32_bf16 v[100:103], v[172:175], v[196:199], v[100:103]
	v_mfma_f32_16x16x32_bf16 v[92:95], v[180:183], v[196:199], v[92:95]
	v_mfma_f32_16x16x32_bf16 v[84:87], v[172:175], v[204:207], v[84:87]
	v_mfma_f32_16x16x32_bf16 v[76:79], v[180:183], v[204:207], v[76:79]
	v_mfma_f32_16x16x32_bf16 v[68:71], v[172:175], v[212:215], v[68:71]
	v_mfma_f32_16x16x32_bf16 v[64:67], v[180:183], v[212:215], v[64:67]
	s_barrier
	s_add_i32 s57, s49, s30
	v_lshl_add_u64 v[216:217], s[38:39], 0, v[148:149]
	s_mov_b32 m0, s57
	ds_read_b128 v[184:187], v169 offset:16384
	ds_read_b128 v[188:191], v169 offset:17408
	ds_read_b128 v[192:195], v169 offset:18432
	ds_read_b128 v[196:199], v169 offset:19456
	ds_read_b128 v[200:203], v169 offset:20480
	ds_read_b128 v[204:207], v169 offset:21504
	ds_read_b128 v[208:211], v169 offset:22528
	ds_read_b128 v[212:215], v169 offset:23552
	global_load_lds_dwordx4 v[216:217], off
	s_add_i32 m0, s57, 0x2000
	s_add_u32 s58, s38, 0x580000
	v_lshl_add_u64 v[218:219], s[38:39], 0, v[144:145]
	s_addc_u32 s59, s39, 0
	s_add_i32 s57, s51, s30
	global_load_lds_dwordx4 v[218:219], off
	v_lshl_add_u64 v[220:221], s[58:59], 0, v[148:149]
	s_mov_b32 m0, s57
	v_lshl_add_u64 v[222:223], s[40:41], 0, v[146:147]
	global_load_lds_dwordx4 v[220:221], off
	v_lshl_add_u64 v[220:221], s[58:59], 0, v[144:145]
	s_add_i32 m0, s57, 0x2000
	s_nop 0
	global_load_lds_dwordx4 v[220:221], off
	v_lshl_add_u64 v[220:221], s[40:41], 0, v[150:151]
	s_mov_b32 m0, s42
	s_nop 0
	global_load_lds_dwordx4 v[220:221], off
	s_mov_b32 m0, s43
	s_nop 0
	global_load_lds_dwordx4 v[222:223], off
	s_waitcnt vmcnt(8)
	s_waitcnt lgkmcnt(0)
	s_barrier
	s_waitcnt lgkmcnt(0)
	v_mfma_f32_16x16x32_bf16 v[60:63], v[128:131], v[184:187], v[60:63]
	v_mfma_f32_16x16x32_bf16 v[56:59], v[136:139], v[184:187], v[56:59]
	v_mfma_f32_16x16x32_bf16 v[48:51], v[128:131], v[192:195], v[48:51]
	v_mfma_f32_16x16x32_bf16 v[40:43], v[136:139], v[192:195], v[40:43]
	v_mfma_f32_16x16x32_bf16 v[32:35], v[128:131], v[200:203], v[32:35]
	v_mfma_f32_16x16x32_bf16 v[24:27], v[136:139], v[200:203], v[24:27]
	v_mfma_f32_16x16x32_bf16 v[16:19], v[128:131], v[208:211], v[16:19]
	v_mfma_f32_16x16x32_bf16 v[8:11], v[136:139], v[208:211], v[8:11]
	v_mfma_f32_16x16x32_bf16 v[60:63], v[132:135], v[188:191], v[60:63]
	v_mfma_f32_16x16x32_bf16 v[56:59], v[140:143], v[188:191], v[56:59]
	v_mfma_f32_16x16x32_bf16 v[48:51], v[132:135], v[196:199], v[48:51]
	v_mfma_f32_16x16x32_bf16 v[40:43], v[140:143], v[196:199], v[40:43]
	v_mfma_f32_16x16x32_bf16 v[32:35], v[132:135], v[204:207], v[32:35]
	v_mfma_f32_16x16x32_bf16 v[24:27], v[140:143], v[204:207], v[24:27]
	v_mfma_f32_16x16x32_bf16 v[16:19], v[132:135], v[212:215], v[16:19]
	v_mfma_f32_16x16x32_bf16 v[8:11], v[140:143], v[212:215], v[8:11]
	v_mfma_f32_16x16x32_bf16 v[52:55], v[160:163], v[184:187], v[52:55]
	v_mfma_f32_16x16x32_bf16 v[44:47], v[176:179], v[184:187], v[44:47]
	v_mfma_f32_16x16x32_bf16 v[36:39], v[160:163], v[192:195], v[36:39]
	v_mfma_f32_16x16x32_bf16 v[28:31], v[176:179], v[192:195], v[28:31]
	v_mfma_f32_16x16x32_bf16 v[20:23], v[160:163], v[200:203], v[20:23]
	v_mfma_f32_16x16x32_bf16 v[12:15], v[176:179], v[200:203], v[12:15]
	v_mfma_f32_16x16x32_bf16 v[4:7], v[160:163], v[208:211], v[4:7]
	v_mfma_f32_16x16x32_bf16 v[0:3], v[176:179], v[208:211], v[0:3]
	v_mfma_f32_16x16x32_bf16 v[52:55], v[172:175], v[188:191], v[52:55]
	v_mfma_f32_16x16x32_bf16 v[44:47], v[180:183], v[188:191], v[44:47]
	v_mfma_f32_16x16x32_bf16 v[36:39], v[172:175], v[196:199], v[36:39]
	v_mfma_f32_16x16x32_bf16 v[28:31], v[180:183], v[196:199], v[28:31]
	v_mfma_f32_16x16x32_bf16 v[20:23], v[172:175], v[204:207], v[20:23]
	v_mfma_f32_16x16x32_bf16 v[12:15], v[180:183], v[204:207], v[12:15]
	v_mfma_f32_16x16x32_bf16 v[4:7], v[172:175], v[212:215], v[4:7]
	v_mfma_f32_16x16x32_bf16 v[0:3], v[180:183], v[212:215], v[0:3]
	s_barrier
	s_add_i32 s57, 0, 0x18000
	s_add_i32 s58, 0, 0x1c000
	v_add_u32_e32 v140, s57, v165
	v_add_u32_e32 v171, s58, v165
	ds_read_b128 v[128:131], v140
	ds_read_b128 v[132:135], v140 offset:1024
	ds_read_b128 v[136:139], v140 offset:2048
	ds_read_b128 v[140:143], v140 offset:3072
	ds_read_b128 v[160:163], v171
	ds_read_b128 v[172:175], v171 offset:1024
	ds_read_b128 v[176:179], v171 offset:2048
	ds_read_b128 v[180:183], v171 offset:3072
	s_add_u32 s40, s40, 0x40000
	s_addc_u32 s41, s41, 0
	s_mov_b32 m0, s44
	v_lshl_add_u64 v[224:225], s[40:41], 0, v[150:151]
	ds_read_b128 v[184:187], v169 offset:32768
	ds_read_b128 v[188:191], v169 offset:33792
	ds_read_b128 v[192:195], v169 offset:34816
	ds_read_b128 v[196:199], v169 offset:35840
	ds_read_b128 v[200:203], v169 offset:36864
	ds_read_b128 v[204:207], v169 offset:37888
	ds_read_b128 v[208:211], v169 offset:38912
	ds_read_b128 v[212:215], v169 offset:39936
	global_load_lds_dwordx4 v[224:225], off
	v_lshl_add_u64 v[224:225], s[40:41], 0, v[146:147]
	s_mov_b32 m0, s45
	s_nop 0
	global_load_lds_dwordx4 v[224:225], off
	s_waitcnt vmcnt(8)
	s_waitcnt lgkmcnt(0)
	s_barrier
	s_waitcnt lgkmcnt(0)
	v_mfma_f32_16x16x32_bf16 v[124:127], v[128:131], v[184:187], v[124:127]
	v_mfma_f32_16x16x32_bf16 v[120:123], v[136:139], v[184:187], v[120:123]
	v_mfma_f32_16x16x32_bf16 v[116:119], v[128:131], v[192:195], v[116:119]
	v_mfma_f32_16x16x32_bf16 v[112:115], v[136:139], v[192:195], v[112:115]
	v_mfma_f32_16x16x32_bf16 v[96:99], v[128:131], v[200:203], v[96:99]
	v_mfma_f32_16x16x32_bf16 v[88:91], v[136:139], v[200:203], v[88:91]
	v_mfma_f32_16x16x32_bf16 v[80:83], v[128:131], v[208:211], v[80:83]
	v_mfma_f32_16x16x32_bf16 v[72:75], v[136:139], v[208:211], v[72:75]
	v_mfma_f32_16x16x32_bf16 v[124:127], v[132:135], v[188:191], v[124:127]
	v_mfma_f32_16x16x32_bf16 v[120:123], v[140:143], v[188:191], v[120:123]
	v_mfma_f32_16x16x32_bf16 v[116:119], v[132:135], v[196:199], v[116:119]
	v_mfma_f32_16x16x32_bf16 v[112:115], v[140:143], v[196:199], v[112:115]
	v_mfma_f32_16x16x32_bf16 v[96:99], v[132:135], v[204:207], v[96:99]
	v_mfma_f32_16x16x32_bf16 v[88:91], v[140:143], v[204:207], v[88:91]
	v_mfma_f32_16x16x32_bf16 v[80:83], v[132:135], v[212:215], v[80:83]
	v_mfma_f32_16x16x32_bf16 v[72:75], v[140:143], v[212:215], v[72:75]
	v_mfma_f32_16x16x32_bf16 v[108:111], v[160:163], v[184:187], v[108:111]
	v_mfma_f32_16x16x32_bf16 v[104:107], v[176:179], v[184:187], v[104:107]
	v_mfma_f32_16x16x32_bf16 v[100:103], v[160:163], v[192:195], v[100:103]
	v_mfma_f32_16x16x32_bf16 v[92:95], v[176:179], v[192:195], v[92:95]
	v_mfma_f32_16x16x32_bf16 v[84:87], v[160:163], v[200:203], v[84:87]
	v_mfma_f32_16x16x32_bf16 v[76:79], v[176:179], v[200:203], v[76:79]
	v_mfma_f32_16x16x32_bf16 v[68:71], v[160:163], v[208:211], v[68:71]
	v_mfma_f32_16x16x32_bf16 v[64:67], v[176:179], v[208:211], v[64:67]
	v_mfma_f32_16x16x32_bf16 v[108:111], v[172:175], v[188:191], v[108:111]
	v_mfma_f32_16x16x32_bf16 v[104:107], v[180:183], v[188:191], v[104:107]
	v_mfma_f32_16x16x32_bf16 v[100:103], v[172:175], v[196:199], v[100:103]
	v_mfma_f32_16x16x32_bf16 v[92:95], v[180:183], v[196:199], v[92:95]
	v_mfma_f32_16x16x32_bf16 v[84:87], v[172:175], v[204:207], v[84:87]
	v_mfma_f32_16x16x32_bf16 v[76:79], v[180:183], v[204:207], v[76:79]
	v_mfma_f32_16x16x32_bf16 v[68:71], v[172:175], v[212:215], v[68:71]
	v_mfma_f32_16x16x32_bf16 v[64:67], v[180:183], v[212:215], v[64:67]
	s_barrier
	s_add_i32 s40, s57, s30
	v_lshl_add_u64 v[216:217], v[216:217], 0, s[16:17]
	s_mov_b32 m0, s40
	ds_read_b128 v[184:187], v169 offset:49152
	ds_read_b128 v[188:191], v169 offset:50176
	ds_read_b128 v[192:195], v169 offset:51200
	ds_read_b128 v[196:199], v169 offset:52224
	ds_read_b128 v[200:203], v169 offset:53248
	ds_read_b128 v[204:207], v169 offset:54272
	ds_read_b128 v[208:211], v169 offset:55296
	ds_read_b128 v[212:215], v169 offset:56320
	global_load_lds_dwordx4 v[216:217], off
	s_add_i32 m0, s40, 0x2000
	s_add_u32 s38, s38, 0x580080
	v_lshl_add_u64 v[216:217], v[218:219], 0, s[16:17]
	s_addc_u32 s39, s39, 0
	s_add_i32 s40, s58, s30
	global_load_lds_dwordx4 v[216:217], off
	v_lshl_add_u64 v[216:217], s[38:39], 0, v[148:149]
	s_mov_b32 m0, s40
	s_nop 0
	global_load_lds_dwordx4 v[216:217], off
	v_lshl_add_u64 v[216:217], s[38:39], 0, v[144:145]
	s_add_i32 m0, s40, 0x2000
	s_nop 0
	global_load_lds_dwordx4 v[216:217], off
	v_lshl_add_u64 v[216:217], v[220:221], 0, s[16:17]
	s_mov_b32 m0, s47
	s_nop 0
	global_load_lds_dwordx4 v[216:217], off
	v_lshl_add_u64 v[216:217], v[222:223], 0, s[16:17]
	s_mov_b32 m0, s48
	s_nop 0
	global_load_lds_dwordx4 v[216:217], off
	s_waitcnt vmcnt(8)
	s_waitcnt lgkmcnt(0)
	s_barrier
	s_waitcnt lgkmcnt(0)
	v_mfma_f32_16x16x32_bf16 v[60:63], v[128:131], v[184:187], v[60:63]
	v_mfma_f32_16x16x32_bf16 v[56:59], v[136:139], v[184:187], v[56:59]
	v_mfma_f32_16x16x32_bf16 v[48:51], v[128:131], v[192:195], v[48:51]
	v_mfma_f32_16x16x32_bf16 v[40:43], v[136:139], v[192:195], v[40:43]
	v_mfma_f32_16x16x32_bf16 v[32:35], v[128:131], v[200:203], v[32:35]
	v_mfma_f32_16x16x32_bf16 v[24:27], v[136:139], v[200:203], v[24:27]
	v_mfma_f32_16x16x32_bf16 v[16:19], v[128:131], v[208:211], v[16:19]
	v_mfma_f32_16x16x32_bf16 v[8:11], v[136:139], v[208:211], v[8:11]
	v_mfma_f32_16x16x32_bf16 v[60:63], v[132:135], v[188:191], v[60:63]
	v_mfma_f32_16x16x32_bf16 v[56:59], v[140:143], v[188:191], v[56:59]
	v_mfma_f32_16x16x32_bf16 v[48:51], v[132:135], v[196:199], v[48:51]
	v_mfma_f32_16x16x32_bf16 v[40:43], v[140:143], v[196:199], v[40:43]
	v_mfma_f32_16x16x32_bf16 v[32:35], v[132:135], v[204:207], v[32:35]
	v_mfma_f32_16x16x32_bf16 v[24:27], v[140:143], v[204:207], v[24:27]
	v_mfma_f32_16x16x32_bf16 v[16:19], v[132:135], v[212:215], v[16:19]
	v_mfma_f32_16x16x32_bf16 v[8:11], v[140:143], v[212:215], v[8:11]
	v_mfma_f32_16x16x32_bf16 v[52:55], v[160:163], v[184:187], v[52:55]
	v_mfma_f32_16x16x32_bf16 v[44:47], v[176:179], v[184:187], v[44:47]
	v_mfma_f32_16x16x32_bf16 v[36:39], v[160:163], v[192:195], v[36:39]
	v_mfma_f32_16x16x32_bf16 v[28:31], v[176:179], v[192:195], v[28:31]
	v_mfma_f32_16x16x32_bf16 v[20:23], v[160:163], v[200:203], v[20:23]
	v_mfma_f32_16x16x32_bf16 v[12:15], v[176:179], v[200:203], v[12:15]
	v_mfma_f32_16x16x32_bf16 v[4:7], v[160:163], v[208:211], v[4:7]
	v_mfma_f32_16x16x32_bf16 v[0:3], v[176:179], v[208:211], v[0:3]
	v_mfma_f32_16x16x32_bf16 v[52:55], v[172:175], v[188:191], v[52:55]
	v_mfma_f32_16x16x32_bf16 v[44:47], v[180:183], v[188:191], v[44:47]
	v_mfma_f32_16x16x32_bf16 v[36:39], v[172:175], v[196:199], v[36:39]
	v_mfma_f32_16x16x32_bf16 v[28:31], v[180:183], v[196:199], v[28:31]
	v_mfma_f32_16x16x32_bf16 v[20:23], v[172:175], v[204:207], v[20:23]
	v_mfma_f32_16x16x32_bf16 v[12:15], v[180:183], v[204:207], v[12:15]
	v_mfma_f32_16x16x32_bf16 v[4:7], v[172:175], v[212:215], v[4:7]
	v_mfma_f32_16x16x32_bf16 v[0:3], v[180:183], v[212:215], v[0:3]
	s_barrier
	s_add_i32 s56, s56, 2
	s_add_u32 s36, s36, 0x100
	s_addc_u32 s37, s37, 0
	s_add_u32 s54, s54, 0x100
	s_addc_u32 s55, s55, 0
	s_cmp_gt_u32 s56, 13
	s_cbranch_scc0 .LBB0_1752
	s_and_b64 vcc, exec, s[22:23]
	s_cbranch_vccz .LBB0_1755
	s_barrier

.LBB0_1877:
	ds_read_b128 v[128:131], v167
	ds_read_b128 v[132:135], v167 offset:1024
	ds_read_b128 v[136:139], v167 offset:2048
	ds_read_b128 v[140:143], v167 offset:3072
	ds_read_b128 v[160:163], v168
	ds_read_b128 v[172:175], v168 offset:1024
	ds_read_b128 v[176:179], v168 offset:2048
	ds_read_b128 v[180:183], v168 offset:3072
	s_add_u32 s34, s30, 0xfffc0080
	s_addc_u32 s35, s31, -1
	s_cmp_eq_u32 s56, 12
	s_cselect_b32 s37, s25, s35
	s_cselect_b32 s36, s52, s34
	s_cselect_b32 s35, s23, s55
	s_cselect_b32 s34, s53, s54
	v_lshl_add_u64 v[216:217], s[30:31], 0, v[152:153]
	s_add_i32 m0, s40, 0xc000
	ds_read_b128 v[184:187], v169
	ds_read_b128 v[188:191], v169 offset:1024
	ds_read_b128 v[192:195], v169 offset:2048
	ds_read_b128 v[196:199], v169 offset:3072
	ds_read_b128 v[200:203], v169 offset:4096
	ds_read_b128 v[204:207], v169 offset:5120
	ds_read_b128 v[208:211], v169 offset:6144
	ds_read_b128 v[212:215], v169 offset:7168
	global_load_lds_dwordx4 v[216:217], off
	v_lshl_add_u64 v[216:217], s[30:31], 0, v[154:155]
	s_add_i32 m0, s40, 0xe000
	s_nop 0
	global_load_lds_dwordx4 v[216:217], off
	s_waitcnt vmcnt(8)
	s_waitcnt lgkmcnt(0)
	s_barrier
	s_waitcnt lgkmcnt(0)
	v_mfma_f32_16x16x32_bf16 v[124:127], v[128:131], v[184:187], v[124:127]
	v_mfma_f32_16x16x32_bf16 v[120:123], v[136:139], v[184:187], v[120:123]
	v_mfma_f32_16x16x32_bf16 v[116:119], v[128:131], v[192:195], v[116:119]
	v_mfma_f32_16x16x32_bf16 v[112:115], v[136:139], v[192:195], v[112:115]
	v_mfma_f32_16x16x32_bf16 v[96:99], v[128:131], v[200:203], v[96:99]
	v_mfma_f32_16x16x32_bf16 v[88:91], v[136:139], v[200:203], v[88:91]
	v_mfma_f32_16x16x32_bf16 v[80:83], v[128:131], v[208:211], v[80:83]
	v_mfma_f32_16x16x32_bf16 v[72:75], v[136:139], v[208:211], v[72:75]
	v_mfma_f32_16x16x32_bf16 v[124:127], v[132:135], v[188:191], v[124:127]
	v_mfma_f32_16x16x32_bf16 v[120:123], v[140:143], v[188:191], v[120:123]
	v_mfma_f32_16x16x32_bf16 v[116:119], v[132:135], v[196:199], v[116:119]
	v_mfma_f32_16x16x32_bf16 v[112:115], v[140:143], v[196:199], v[112:115]
	v_mfma_f32_16x16x32_bf16 v[96:99], v[132:135], v[204:207], v[96:99]
	v_mfma_f32_16x16x32_bf16 v[88:91], v[140:143], v[204:207], v[88:91]
	v_mfma_f32_16x16x32_bf16 v[80:83], v[132:135], v[212:215], v[80:83]
	v_mfma_f32_16x16x32_bf16 v[72:75], v[140:143], v[212:215], v[72:75]
	v_mfma_f32_16x16x32_bf16 v[108:111], v[160:163], v[184:187], v[108:111]
	v_mfma_f32_16x16x32_bf16 v[104:107], v[176:179], v[184:187], v[104:107]
	v_mfma_f32_16x16x32_bf16 v[100:103], v[160:163], v[192:195], v[100:103]
	v_mfma_f32_16x16x32_bf16 v[92:95], v[176:179], v[192:195], v[92:95]
	v_mfma_f32_16x16x32_bf16 v[84:87], v[160:163], v[200:203], v[84:87]
	v_mfma_f32_16x16x32_bf16 v[76:79], v[176:179], v[200:203], v[76:79]
	v_mfma_f32_16x16x32_bf16 v[68:71], v[160:163], v[208:211], v[68:71]
	v_mfma_f32_16x16x32_bf16 v[64:67], v[176:179], v[208:211], v[64:67]
	v_mfma_f32_16x16x32_bf16 v[108:111], v[172:175], v[188:191], v[108:111]
	v_mfma_f32_16x16x32_bf16 v[104:107], v[180:183], v[188:191], v[104:107]
	v_mfma_f32_16x16x32_bf16 v[100:103], v[172:175], v[196:199], v[100:103]
	v_mfma_f32_16x16x32_bf16 v[92:95], v[180:183], v[196:199], v[92:95]
	v_mfma_f32_16x16x32_bf16 v[84:87], v[172:175], v[204:207], v[84:87]
	v_mfma_f32_16x16x32_bf16 v[76:79], v[180:183], v[204:207], v[76:79]
	v_mfma_f32_16x16x32_bf16 v[68:71], v[172:175], v[212:215], v[68:71]
	v_mfma_f32_16x16x32_bf16 v[64:67], v[180:183], v[212:215], v[64:67]
	s_barrier
	s_add_i32 s57, s47, s38
	v_lshl_add_u64 v[216:217], s[34:35], 0, v[148:149]
	s_mov_b32 m0, s57
	ds_read_b128 v[184:187], v169 offset:16384
	ds_read_b128 v[188:191], v169 offset:17408
	ds_read_b128 v[192:195], v169 offset:18432
	ds_read_b128 v[196:199], v169 offset:19456
	ds_read_b128 v[200:203], v169 offset:20480
	ds_read_b128 v[204:207], v169 offset:21504
	ds_read_b128 v[208:211], v169 offset:22528
	ds_read_b128 v[212:215], v169 offset:23552
	global_load_lds_dwordx4 v[216:217], off
	s_add_i32 m0, s57, 0x2000
	s_add_u32 s58, s34, 0x580000
	v_lshl_add_u64 v[218:219], s[34:35], 0, v[144:145]
	s_addc_u32 s59, s35, 0
	s_add_i32 s57, s48, s38
	global_load_lds_dwordx4 v[218:219], off
	v_lshl_add_u64 v[220:221], s[58:59], 0, v[148:149]
	s_mov_b32 m0, s57
	v_lshl_add_u64 v[222:223], s[36:37], 0, v[146:147]
	global_load_lds_dwordx4 v[220:221], off
	v_lshl_add_u64 v[220:221], s[58:59], 0, v[144:145]
	s_add_i32 m0, s57, 0x2000
	s_nop 0
	global_load_lds_dwordx4 v[220:221], off
	v_lshl_add_u64 v[220:221], s[36:37], 0, v[150:151]
	s_mov_b32 m0, s40
	s_nop 0
	global_load_lds_dwordx4 v[220:221], off
	s_mov_b32 m0, s41
	s_nop 0
	global_load_lds_dwordx4 v[222:223], off
	s_waitcnt vmcnt(8)
	s_waitcnt lgkmcnt(0)
	s_barrier
	s_waitcnt lgkmcnt(0)
	v_mfma_f32_16x16x32_bf16 v[60:63], v[128:131], v[184:187], v[60:63]
	v_mfma_f32_16x16x32_bf16 v[56:59], v[136:139], v[184:187], v[56:59]
	v_mfma_f32_16x16x32_bf16 v[48:51], v[128:131], v[192:195], v[48:51]
	v_mfma_f32_16x16x32_bf16 v[40:43], v[136:139], v[192:195], v[40:43]
	v_mfma_f32_16x16x32_bf16 v[32:35], v[128:131], v[200:203], v[32:35]
	v_mfma_f32_16x16x32_bf16 v[24:27], v[136:139], v[200:203], v[24:27]
	v_mfma_f32_16x16x32_bf16 v[16:19], v[128:131], v[208:211], v[16:19]
	v_mfma_f32_16x16x32_bf16 v[8:11], v[136:139], v[208:211], v[8:11]
	v_mfma_f32_16x16x32_bf16 v[60:63], v[132:135], v[188:191], v[60:63]
	v_mfma_f32_16x16x32_bf16 v[56:59], v[140:143], v[188:191], v[56:59]
	v_mfma_f32_16x16x32_bf16 v[48:51], v[132:135], v[196:199], v[48:51]
	v_mfma_f32_16x16x32_bf16 v[40:43], v[140:143], v[196:199], v[40:43]
	v_mfma_f32_16x16x32_bf16 v[32:35], v[132:135], v[204:207], v[32:35]
	v_mfma_f32_16x16x32_bf16 v[24:27], v[140:143], v[204:207], v[24:27]
	v_mfma_f32_16x16x32_bf16 v[16:19], v[132:135], v[212:215], v[16:19]
	v_mfma_f32_16x16x32_bf16 v[8:11], v[140:143], v[212:215], v[8:11]
	v_mfma_f32_16x16x32_bf16 v[52:55], v[160:163], v[184:187], v[52:55]
	v_mfma_f32_16x16x32_bf16 v[44:47], v[176:179], v[184:187], v[44:47]
	v_mfma_f32_16x16x32_bf16 v[36:39], v[160:163], v[192:195], v[36:39]
	v_mfma_f32_16x16x32_bf16 v[28:31], v[176:179], v[192:195], v[28:31]
	v_mfma_f32_16x16x32_bf16 v[20:23], v[160:163], v[200:203], v[20:23]
	v_mfma_f32_16x16x32_bf16 v[12:15], v[176:179], v[200:203], v[12:15]
	v_mfma_f32_16x16x32_bf16 v[4:7], v[160:163], v[208:211], v[4:7]
	v_mfma_f32_16x16x32_bf16 v[0:3], v[176:179], v[208:211], v[0:3]
	v_mfma_f32_16x16x32_bf16 v[52:55], v[172:175], v[188:191], v[52:55]
	v_mfma_f32_16x16x32_bf16 v[44:47], v[180:183], v[188:191], v[44:47]
	v_mfma_f32_16x16x32_bf16 v[36:39], v[172:175], v[196:199], v[36:39]
	v_mfma_f32_16x16x32_bf16 v[28:31], v[180:183], v[196:199], v[28:31]
	v_mfma_f32_16x16x32_bf16 v[20:23], v[172:175], v[204:207], v[20:23]
	v_mfma_f32_16x16x32_bf16 v[12:15], v[180:183], v[204:207], v[12:15]
	v_mfma_f32_16x16x32_bf16 v[4:7], v[172:175], v[212:215], v[4:7]
	v_mfma_f32_16x16x32_bf16 v[0:3], v[180:183], v[212:215], v[0:3]
	s_barrier
	s_add_i32 s57, 0, 0x18000
	s_add_i32 s58, 0, 0x1c000
	v_add_u32_e32 v140, s57, v165
	v_add_u32_e32 v171, s58, v165
	ds_read_b128 v[128:131], v140
	ds_read_b128 v[132:135], v140 offset:1024
	ds_read_b128 v[136:139], v140 offset:2048
	ds_read_b128 v[140:143], v140 offset:3072
	ds_read_b128 v[160:163], v171
	ds_read_b128 v[172:175], v171 offset:1024
	ds_read_b128 v[176:179], v171 offset:2048
	ds_read_b128 v[180:183], v171 offset:3072
	s_add_u32 s36, s36, 0x40000
	s_addc_u32 s37, s37, 0
	s_mov_b32 m0, s42
	v_lshl_add_u64 v[224:225], s[36:37], 0, v[150:151]
	ds_read_b128 v[184:187], v169 offset:32768
	ds_read_b128 v[188:191], v169 offset:33792
	ds_read_b128 v[192:195], v169 offset:34816
	ds_read_b128 v[196:199], v169 offset:35840
	ds_read_b128 v[200:203], v169 offset:36864
	ds_read_b128 v[204:207], v169 offset:37888
	ds_read_b128 v[208:211], v169 offset:38912
	ds_read_b128 v[212:215], v169 offset:39936
	global_load_lds_dwordx4 v[224:225], off
	v_lshl_add_u64 v[224:225], s[36:37], 0, v[146:147]
	s_mov_b32 m0, s43
	s_nop 0
	global_load_lds_dwordx4 v[224:225], off
	s_waitcnt vmcnt(8)
	s_waitcnt lgkmcnt(0)
	s_barrier
	s_waitcnt lgkmcnt(0)
	v_mfma_f32_16x16x32_bf16 v[124:127], v[128:131], v[184:187], v[124:127]
	v_mfma_f32_16x16x32_bf16 v[120:123], v[136:139], v[184:187], v[120:123]
	v_mfma_f32_16x16x32_bf16 v[116:119], v[128:131], v[192:195], v[116:119]
	v_mfma_f32_16x16x32_bf16 v[112:115], v[136:139], v[192:195], v[112:115]
	v_mfma_f32_16x16x32_bf16 v[96:99], v[128:131], v[200:203], v[96:99]
	v_mfma_f32_16x16x32_bf16 v[88:91], v[136:139], v[200:203], v[88:91]
	v_mfma_f32_16x16x32_bf16 v[80:83], v[128:131], v[208:211], v[80:83]
	v_mfma_f32_16x16x32_bf16 v[72:75], v[136:139], v[208:211], v[72:75]
	v_mfma_f32_16x16x32_bf16 v[124:127], v[132:135], v[188:191], v[124:127]
	v_mfma_f32_16x16x32_bf16 v[120:123], v[140:143], v[188:191], v[120:123]
	v_mfma_f32_16x16x32_bf16 v[116:119], v[132:135], v[196:199], v[116:119]
	v_mfma_f32_16x16x32_bf16 v[112:115], v[140:143], v[196:199], v[112:115]
	v_mfma_f32_16x16x32_bf16 v[96:99], v[132:135], v[204:207], v[96:99]
	v_mfma_f32_16x16x32_bf16 v[88:91], v[140:143], v[204:207], v[88:91]
	v_mfma_f32_16x16x32_bf16 v[80:83], v[132:135], v[212:215], v[80:83]
	v_mfma_f32_16x16x32_bf16 v[72:75], v[140:143], v[212:215], v[72:75]
	v_mfma_f32_16x16x32_bf16 v[108:111], v[160:163], v[184:187], v[108:111]
	v_mfma_f32_16x16x32_bf16 v[104:107], v[176:179], v[184:187], v[104:107]
	v_mfma_f32_16x16x32_bf16 v[100:103], v[160:163], v[192:195], v[100:103]
	v_mfma_f32_16x16x32_bf16 v[92:95], v[176:179], v[192:195], v[92:95]
	v_mfma_f32_16x16x32_bf16 v[84:87], v[160:163], v[200:203], v[84:87]
	v_mfma_f32_16x16x32_bf16 v[76:79], v[176:179], v[200:203], v[76:79]
	v_mfma_f32_16x16x32_bf16 v[68:71], v[160:163], v[208:211], v[68:71]
	v_mfma_f32_16x16x32_bf16 v[64:67], v[176:179], v[208:211], v[64:67]
	v_mfma_f32_16x16x32_bf16 v[108:111], v[172:175], v[188:191], v[108:111]
	v_mfma_f32_16x16x32_bf16 v[104:107], v[180:183], v[188:191], v[104:107]
	v_mfma_f32_16x16x32_bf16 v[100:103], v[172:175], v[196:199], v[100:103]
	v_mfma_f32_16x16x32_bf16 v[92:95], v[180:183], v[196:199], v[92:95]
	v_mfma_f32_16x16x32_bf16 v[84:87], v[172:175], v[204:207], v[84:87]
	v_mfma_f32_16x16x32_bf16 v[76:79], v[180:183], v[204:207], v[76:79]
	v_mfma_f32_16x16x32_bf16 v[68:71], v[172:175], v[212:215], v[68:71]
	v_mfma_f32_16x16x32_bf16 v[64:67], v[180:183], v[212:215], v[64:67]
	s_barrier
	s_add_i32 s36, s57, s38
	v_lshl_add_u64 v[216:217], v[216:217], 0, s[14:15]
	s_mov_b32 m0, s36
	ds_read_b128 v[184:187], v169 offset:49152
	ds_read_b128 v[188:191], v169 offset:50176
	ds_read_b128 v[192:195], v169 offset:51200
	ds_read_b128 v[196:199], v169 offset:52224
	ds_read_b128 v[200:203], v169 offset:53248
	ds_read_b128 v[204:207], v169 offset:54272
	ds_read_b128 v[208:211], v169 offset:55296
	ds_read_b128 v[212:215], v169 offset:56320
	global_load_lds_dwordx4 v[216:217], off
	s_add_i32 m0, s36, 0x2000
	s_add_u32 s34, s34, 0x580080
	v_lshl_add_u64 v[216:217], v[218:219], 0, s[14:15]
	s_addc_u32 s35, s35, 0
	s_add_i32 s36, s58, s38
	global_load_lds_dwordx4 v[216:217], off
	v_lshl_add_u64 v[216:217], s[34:35], 0, v[148:149]
	s_mov_b32 m0, s36
	s_nop 0
	global_load_lds_dwordx4 v[216:217], off
	v_lshl_add_u64 v[216:217], s[34:35], 0, v[144:145]
	s_add_i32 m0, s36, 0x2000
	s_nop 0
	global_load_lds_dwordx4 v[216:217], off
	v_lshl_add_u64 v[216:217], v[220:221], 0, s[14:15]
	s_mov_b32 m0, s45
	s_nop 0
	global_load_lds_dwordx4 v[216:217], off
	v_lshl_add_u64 v[216:217], v[222:223], 0, s[14:15]
	s_mov_b32 m0, s46
	s_nop 0
	global_load_lds_dwordx4 v[216:217], off
	s_waitcnt vmcnt(8)
	s_waitcnt lgkmcnt(0)
	s_barrier
	s_waitcnt lgkmcnt(0)
	v_mfma_f32_16x16x32_bf16 v[60:63], v[128:131], v[184:187], v[60:63]
	v_mfma_f32_16x16x32_bf16 v[56:59], v[136:139], v[184:187], v[56:59]
	v_mfma_f32_16x16x32_bf16 v[48:51], v[128:131], v[192:195], v[48:51]
	v_mfma_f32_16x16x32_bf16 v[40:43], v[136:139], v[192:195], v[40:43]
	v_mfma_f32_16x16x32_bf16 v[32:35], v[128:131], v[200:203], v[32:35]
	v_mfma_f32_16x16x32_bf16 v[24:27], v[136:139], v[200:203], v[24:27]
	v_mfma_f32_16x16x32_bf16 v[16:19], v[128:131], v[208:211], v[16:19]
	v_mfma_f32_16x16x32_bf16 v[8:11], v[136:139], v[208:211], v[8:11]
	v_mfma_f32_16x16x32_bf16 v[60:63], v[132:135], v[188:191], v[60:63]
	v_mfma_f32_16x16x32_bf16 v[56:59], v[140:143], v[188:191], v[56:59]
	v_mfma_f32_16x16x32_bf16 v[48:51], v[132:135], v[196:199], v[48:51]
	v_mfma_f32_16x16x32_bf16 v[40:43], v[140:143], v[196:199], v[40:43]
	v_mfma_f32_16x16x32_bf16 v[32:35], v[132:135], v[204:207], v[32:35]
	v_mfma_f32_16x16x32_bf16 v[24:27], v[140:143], v[204:207], v[24:27]
	v_mfma_f32_16x16x32_bf16 v[16:19], v[132:135], v[212:215], v[16:19]
	v_mfma_f32_16x16x32_bf16 v[8:11], v[140:143], v[212:215], v[8:11]
	v_mfma_f32_16x16x32_bf16 v[52:55], v[160:163], v[184:187], v[52:55]
	v_mfma_f32_16x16x32_bf16 v[44:47], v[176:179], v[184:187], v[44:47]
	v_mfma_f32_16x16x32_bf16 v[36:39], v[160:163], v[192:195], v[36:39]
	v_mfma_f32_16x16x32_bf16 v[28:31], v[176:179], v[192:195], v[28:31]
	v_mfma_f32_16x16x32_bf16 v[20:23], v[160:163], v[200:203], v[20:23]
	v_mfma_f32_16x16x32_bf16 v[12:15], v[176:179], v[200:203], v[12:15]
	v_mfma_f32_16x16x32_bf16 v[4:7], v[160:163], v[208:211], v[4:7]
	v_mfma_f32_16x16x32_bf16 v[0:3], v[176:179], v[208:211], v[0:3]
	v_mfma_f32_16x16x32_bf16 v[52:55], v[172:175], v[188:191], v[52:55]
	v_mfma_f32_16x16x32_bf16 v[44:47], v[180:183], v[188:191], v[44:47]
	v_mfma_f32_16x16x32_bf16 v[36:39], v[172:175], v[196:199], v[36:39]
	v_mfma_f32_16x16x32_bf16 v[28:31], v[180:183], v[196:199], v[28:31]
	v_mfma_f32_16x16x32_bf16 v[20:23], v[172:175], v[204:207], v[20:23]
	v_mfma_f32_16x16x32_bf16 v[12:15], v[180:183], v[204:207], v[12:15]
	v_mfma_f32_16x16x32_bf16 v[4:7], v[172:175], v[212:215], v[4:7]
	v_mfma_f32_16x16x32_bf16 v[0:3], v[180:183], v[212:215], v[0:3]
	s_barrier
	s_add_i32 s56, s56, 2
	s_add_u32 s30, s30, 0x100
	s_addc_u32 s31, s31, 0
	s_add_u32 s54, s54, 0x100
	s_addc_u32 s55, s55, 0
	s_cmp_lt_u32 s56, 14
	s_cbranch_scc1 .LBB0_1877
	s_andn2_b64 vcc, exec, s[16:17]
	s_cbranch_vccnz .LBB0_1880
	s_barrier

.LBB0_2014:
	ds_read_b128 v[128:131], v176
	ds_read_b128 v[132:135], v176 offset:1024
	ds_read_b128 v[136:139], v176 offset:2048
	ds_read_b128 v[140:143], v176 offset:3072
	ds_read_b128 v[180:183], v177
	ds_read_b128 v[184:187], v177 offset:1024
	ds_read_b128 v[188:191], v177 offset:2048
	ds_read_b128 v[192:195], v177 offset:3072
	s_add_u32 s22, s20, 0x100
	s_addc_u32 s23, s21, 0
	s_cmp_eq_u32 s50, 40
	s_cselect_b32 s27, s5, s23
	s_cselect_b32 s26, s4, s22
	s_cselect_b32 s25, s15, s17
	s_cselect_b32 s24, s14, s6
	v_lshl_add_u64 v[172:173], s[20:21], 0, v[164:165]
	s_add_i32 m0, s34, 0xc000
	ds_read_b128 v[196:199], v178
	ds_read_b128 v[200:203], v178 offset:1024
	ds_read_b128 v[204:207], v178 offset:2048
	ds_read_b128 v[208:211], v178 offset:3072
	ds_read_b128 v[212:215], v178 offset:4096
	ds_read_b128 v[216:219], v178 offset:5120
	ds_read_b128 v[220:223], v178 offset:6144
	ds_read_b128 v[224:227], v178 offset:7168
	global_load_lds_dwordx4 v[172:173], off
	v_lshl_add_u64 v[172:173], s[20:21], 0, v[166:167]
	s_add_i32 m0, s34, 0xe000
	s_nop 0
	global_load_lds_dwordx4 v[172:173], off
	s_waitcnt vmcnt(8)
	s_waitcnt lgkmcnt(0)
	s_barrier
	s_waitcnt lgkmcnt(0)
	v_mfma_f32_16x16x32_bf16 v[124:127], v[128:131], v[196:199], v[124:127]
	v_mfma_f32_16x16x32_bf16 v[120:123], v[136:139], v[196:199], v[120:123]
	v_mfma_f32_16x16x32_bf16 v[112:115], v[128:131], v[204:207], v[112:115]
	v_mfma_f32_16x16x32_bf16 v[108:111], v[136:139], v[204:207], v[108:111]
	v_mfma_f32_16x16x32_bf16 v[96:99], v[128:131], v[212:215], v[96:99]
	v_mfma_f32_16x16x32_bf16 v[92:95], v[136:139], v[212:215], v[92:95]
	v_mfma_f32_16x16x32_bf16 v[80:83], v[128:131], v[220:223], v[80:83]
	v_mfma_f32_16x16x32_bf16 v[76:79], v[136:139], v[220:223], v[76:79]
	v_mfma_f32_16x16x32_bf16 v[124:127], v[132:135], v[200:203], v[124:127]
	v_mfma_f32_16x16x32_bf16 v[120:123], v[140:143], v[200:203], v[120:123]
	v_mfma_f32_16x16x32_bf16 v[112:115], v[132:135], v[208:211], v[112:115]
	v_mfma_f32_16x16x32_bf16 v[108:111], v[140:143], v[208:211], v[108:111]
	v_mfma_f32_16x16x32_bf16 v[96:99], v[132:135], v[216:219], v[96:99]
	v_mfma_f32_16x16x32_bf16 v[92:95], v[140:143], v[216:219], v[92:95]
	v_mfma_f32_16x16x32_bf16 v[80:83], v[132:135], v[224:227], v[80:83]
	v_mfma_f32_16x16x32_bf16 v[76:79], v[140:143], v[224:227], v[76:79]
	v_mfma_f32_16x16x32_bf16 v[116:119], v[180:183], v[196:199], v[116:119]
	v_mfma_f32_16x16x32_bf16 v[104:107], v[188:191], v[196:199], v[104:107]
	v_mfma_f32_16x16x32_bf16 v[100:103], v[180:183], v[204:207], v[100:103]
	v_mfma_f32_16x16x32_bf16 v[88:91], v[188:191], v[204:207], v[88:91]
	v_mfma_f32_16x16x32_bf16 v[84:87], v[180:183], v[212:215], v[84:87]
	v_mfma_f32_16x16x32_bf16 v[72:75], v[188:191], v[212:215], v[72:75]
	v_mfma_f32_16x16x32_bf16 v[68:71], v[180:183], v[220:223], v[68:71]
	v_mfma_f32_16x16x32_bf16 v[64:67], v[188:191], v[220:223], v[64:67]
	v_mfma_f32_16x16x32_bf16 v[116:119], v[184:187], v[200:203], v[116:119]
	v_mfma_f32_16x16x32_bf16 v[104:107], v[192:195], v[200:203], v[104:107]
	v_mfma_f32_16x16x32_bf16 v[100:103], v[184:187], v[208:211], v[100:103]
	v_mfma_f32_16x16x32_bf16 v[88:91], v[192:195], v[208:211], v[88:91]
	v_mfma_f32_16x16x32_bf16 v[84:87], v[184:187], v[216:219], v[84:87]
	v_mfma_f32_16x16x32_bf16 v[72:75], v[192:195], v[216:219], v[72:75]
	v_mfma_f32_16x16x32_bf16 v[68:71], v[184:187], v[224:227], v[68:71]
	v_mfma_f32_16x16x32_bf16 v[64:67], v[192:195], v[224:227], v[64:67]
	s_barrier
	s_add_i32 s20, s44, s33
	v_lshl_add_u64 v[172:173], s[24:25], 0, v[144:145]
	s_mov_b32 m0, s20
	ds_read_b128 v[196:199], v178 offset:16384
	ds_read_b128 v[200:203], v178 offset:17408
	ds_read_b128 v[204:207], v178 offset:18432
	ds_read_b128 v[208:211], v178 offset:19456
	ds_read_b128 v[212:215], v178 offset:20480
	ds_read_b128 v[216:219], v178 offset:21504
	ds_read_b128 v[220:223], v178 offset:22528
	ds_read_b128 v[224:227], v178 offset:23552
	global_load_lds_dwordx4 v[172:173], off
	s_add_i32 m0, s20, 0x2000
	s_add_u32 s20, s24, 0xb0000
	v_lshl_add_u64 v[228:229], s[24:25], 0, v[146:147]
	s_addc_u32 s21, s25, 0
	s_add_i32 s51, s45, s33
	global_load_lds_dwordx4 v[228:229], off
	v_lshl_add_u64 v[230:231], s[20:21], 0, v[144:145]
	s_mov_b32 m0, s51
	v_lshl_add_u64 v[232:233], s[26:27], 0, v[146:147]
	global_load_lds_dwordx4 v[230:231], off
	v_lshl_add_u64 v[230:231], s[20:21], 0, v[146:147]
	s_add_i32 m0, s51, 0x2000
	s_nop 0
	global_load_lds_dwordx4 v[230:231], off
	v_lshl_add_u64 v[230:231], s[26:27], 0, v[144:145]
	s_mov_b32 m0, s34
	s_nop 0
	global_load_lds_dwordx4 v[230:231], off
	s_mov_b32 m0, s35
	s_nop 0
	global_load_lds_dwordx4 v[232:233], off
	s_waitcnt vmcnt(8)
	s_waitcnt lgkmcnt(0)
	s_barrier
	s_waitcnt lgkmcnt(0)
	v_mfma_f32_16x16x32_bf16 v[60:63], v[128:131], v[196:199], v[60:63]
	v_mfma_f32_16x16x32_bf16 v[56:59], v[136:139], v[196:199], v[56:59]
	v_mfma_f32_16x16x32_bf16 v[48:51], v[128:131], v[204:207], v[48:51]
	v_mfma_f32_16x16x32_bf16 v[44:47], v[136:139], v[204:207], v[44:47]
	v_mfma_f32_16x16x32_bf16 v[32:35], v[128:131], v[212:215], v[32:35]
	v_mfma_f32_16x16x32_bf16 v[28:31], v[136:139], v[212:215], v[28:31]
	v_mfma_f32_16x16x32_bf16 v[16:19], v[128:131], v[220:223], v[16:19]
	v_mfma_f32_16x16x32_bf16 v[12:15], v[136:139], v[220:223], v[12:15]
	v_mfma_f32_16x16x32_bf16 v[60:63], v[132:135], v[200:203], v[60:63]
	v_mfma_f32_16x16x32_bf16 v[56:59], v[140:143], v[200:203], v[56:59]
	v_mfma_f32_16x16x32_bf16 v[48:51], v[132:135], v[208:211], v[48:51]
	v_mfma_f32_16x16x32_bf16 v[44:47], v[140:143], v[208:211], v[44:47]
	v_mfma_f32_16x16x32_bf16 v[32:35], v[132:135], v[216:219], v[32:35]
	v_mfma_f32_16x16x32_bf16 v[28:31], v[140:143], v[216:219], v[28:31]
	v_mfma_f32_16x16x32_bf16 v[16:19], v[132:135], v[224:227], v[16:19]
	v_mfma_f32_16x16x32_bf16 v[12:15], v[140:143], v[224:227], v[12:15]
	v_mfma_f32_16x16x32_bf16 v[52:55], v[180:183], v[196:199], v[52:55]
	v_mfma_f32_16x16x32_bf16 v[40:43], v[188:191], v[196:199], v[40:43]
	v_mfma_f32_16x16x32_bf16 v[36:39], v[180:183], v[204:207], v[36:39]
	v_mfma_f32_16x16x32_bf16 v[24:27], v[188:191], v[204:207], v[24:27]
	v_mfma_f32_16x16x32_bf16 v[20:23], v[180:183], v[212:215], v[20:23]
	v_mfma_f32_16x16x32_bf16 v[8:11], v[188:191], v[212:215], v[8:11]
	v_mfma_f32_16x16x32_bf16 v[4:7], v[180:183], v[220:223], v[4:7]
	v_mfma_f32_16x16x32_bf16 v[0:3], v[188:191], v[220:223], v[0:3]
	v_mfma_f32_16x16x32_bf16 v[52:55], v[184:187], v[200:203], v[52:55]
	v_mfma_f32_16x16x32_bf16 v[40:43], v[192:195], v[200:203], v[40:43]
	v_mfma_f32_16x16x32_bf16 v[36:39], v[184:187], v[208:211], v[36:39]
	v_mfma_f32_16x16x32_bf16 v[24:27], v[192:195], v[208:211], v[24:27]
	v_mfma_f32_16x16x32_bf16 v[20:23], v[184:187], v[216:219], v[20:23]
	v_mfma_f32_16x16x32_bf16 v[8:11], v[192:195], v[216:219], v[8:11]
	v_mfma_f32_16x16x32_bf16 v[4:7], v[184:187], v[224:227], v[4:7]
	v_mfma_f32_16x16x32_bf16 v[0:3], v[192:195], v[224:227], v[0:3]
	s_barrier
	s_add_i32 s51, 0, 0x18000
	s_add_i32 s52, 0, 0x1c000
	v_add_u32_e32 v140, s51, v174
	v_add_u32_e32 v179, s52, v174
	ds_read_b128 v[128:131], v140
	ds_read_b128 v[132:135], v140 offset:1024
	ds_read_b128 v[136:139], v140 offset:2048
	ds_read_b128 v[140:143], v140 offset:3072
	ds_read_b128 v[180:183], v179
	ds_read_b128 v[184:187], v179 offset:1024
	ds_read_b128 v[188:191], v179 offset:2048
	ds_read_b128 v[192:195], v179 offset:3072
	s_add_u32 s20, s26, 0xb0000
	s_addc_u32 s21, s27, 0
	s_mov_b32 m0, s36
	v_lshl_add_u64 v[234:235], s[20:21], 0, v[144:145]
	ds_read_b128 v[196:199], v178 offset:32768
	ds_read_b128 v[200:203], v178 offset:33792
	ds_read_b128 v[204:207], v178 offset:34816
	ds_read_b128 v[208:211], v178 offset:35840
	ds_read_b128 v[212:215], v178 offset:36864
	ds_read_b128 v[216:219], v178 offset:37888
	ds_read_b128 v[220:223], v178 offset:38912
	ds_read_b128 v[224:227], v178 offset:39936
	global_load_lds_dwordx4 v[234:235], off
	v_lshl_add_u64 v[234:235], s[20:21], 0, v[146:147]
	s_mov_b32 m0, s37
	s_nop 0
	global_load_lds_dwordx4 v[234:235], off
	s_waitcnt vmcnt(8)
	s_waitcnt lgkmcnt(0)
	s_barrier
	s_waitcnt lgkmcnt(0)
	v_mfma_f32_16x16x32_bf16 v[124:127], v[128:131], v[196:199], v[124:127]
	v_mfma_f32_16x16x32_bf16 v[120:123], v[136:139], v[196:199], v[120:123]
	v_mfma_f32_16x16x32_bf16 v[112:115], v[128:131], v[204:207], v[112:115]
	v_mfma_f32_16x16x32_bf16 v[108:111], v[136:139], v[204:207], v[108:111]
	v_mfma_f32_16x16x32_bf16 v[96:99], v[128:131], v[212:215], v[96:99]
	v_mfma_f32_16x16x32_bf16 v[92:95], v[136:139], v[212:215], v[92:95]
	v_mfma_f32_16x16x32_bf16 v[80:83], v[128:131], v[220:223], v[80:83]
	v_mfma_f32_16x16x32_bf16 v[76:79], v[136:139], v[220:223], v[76:79]
	v_mfma_f32_16x16x32_bf16 v[124:127], v[132:135], v[200:203], v[124:127]
	v_mfma_f32_16x16x32_bf16 v[120:123], v[140:143], v[200:203], v[120:123]
	v_mfma_f32_16x16x32_bf16 v[112:115], v[132:135], v[208:211], v[112:115]
	v_mfma_f32_16x16x32_bf16 v[108:111], v[140:143], v[208:211], v[108:111]
	v_mfma_f32_16x16x32_bf16 v[96:99], v[132:135], v[216:219], v[96:99]
	v_mfma_f32_16x16x32_bf16 v[92:95], v[140:143], v[216:219], v[92:95]
	v_mfma_f32_16x16x32_bf16 v[80:83], v[132:135], v[224:227], v[80:83]
	v_mfma_f32_16x16x32_bf16 v[76:79], v[140:143], v[224:227], v[76:79]
	v_mfma_f32_16x16x32_bf16 v[116:119], v[180:183], v[196:199], v[116:119]
	v_mfma_f32_16x16x32_bf16 v[104:107], v[188:191], v[196:199], v[104:107]
	v_mfma_f32_16x16x32_bf16 v[100:103], v[180:183], v[204:207], v[100:103]
	v_mfma_f32_16x16x32_bf16 v[88:91], v[188:191], v[204:207], v[88:91]
	v_mfma_f32_16x16x32_bf16 v[84:87], v[180:183], v[212:215], v[84:87]
	v_mfma_f32_16x16x32_bf16 v[72:75], v[188:191], v[212:215], v[72:75]
	v_mfma_f32_16x16x32_bf16 v[68:71], v[180:183], v[220:223], v[68:71]
	v_mfma_f32_16x16x32_bf16 v[64:67], v[188:191], v[220:223], v[64:67]
	v_mfma_f32_16x16x32_bf16 v[116:119], v[184:187], v[200:203], v[116:119]
	v_mfma_f32_16x16x32_bf16 v[104:107], v[192:195], v[200:203], v[104:107]
	v_mfma_f32_16x16x32_bf16 v[100:103], v[184:187], v[208:211], v[100:103]
	v_mfma_f32_16x16x32_bf16 v[88:91], v[192:195], v[208:211], v[88:91]
	v_mfma_f32_16x16x32_bf16 v[84:87], v[184:187], v[216:219], v[84:87]
	v_mfma_f32_16x16x32_bf16 v[72:75], v[192:195], v[216:219], v[72:75]
	v_mfma_f32_16x16x32_bf16 v[68:71], v[184:187], v[224:227], v[68:71]
	v_mfma_f32_16x16x32_bf16 v[64:67], v[192:195], v[224:227], v[64:67]
	s_barrier
	s_add_i32 s20, s51, s33
	v_lshl_add_u64 v[172:173], v[172:173], 0, s[10:11]
	s_mov_b32 m0, s20
	ds_read_b128 v[196:199], v178 offset:49152
	ds_read_b128 v[200:203], v178 offset:50176
	ds_read_b128 v[204:207], v178 offset:51200
	ds_read_b128 v[208:211], v178 offset:52224
	ds_read_b128 v[212:215], v178 offset:53248
	ds_read_b128 v[216:219], v178 offset:54272
	ds_read_b128 v[220:223], v178 offset:55296
	ds_read_b128 v[224:227], v178 offset:56320
	global_load_lds_dwordx4 v[172:173], off
	s_add_i32 m0, s20, 0x2000
	s_add_u32 s20, s24, 0xb0080
	v_lshl_add_u64 v[172:173], v[228:229], 0, s[10:11]
	s_addc_u32 s21, s25, 0
	s_add_i32 s24, s52, s33
	global_load_lds_dwordx4 v[172:173], off
	v_lshl_add_u64 v[172:173], s[20:21], 0, v[144:145]
	s_mov_b32 m0, s24
	s_nop 0
	global_load_lds_dwordx4 v[172:173], off
	v_lshl_add_u64 v[172:173], s[20:21], 0, v[146:147]
	s_add_i32 m0, s24, 0x2000
	s_nop 0
	global_load_lds_dwordx4 v[172:173], off
	v_lshl_add_u64 v[172:173], v[230:231], 0, s[10:11]
	s_mov_b32 m0, s42
	s_nop 0
	global_load_lds_dwordx4 v[172:173], off
	v_lshl_add_u64 v[172:173], v[232:233], 0, s[10:11]
	s_mov_b32 m0, s43
	s_nop 0
	global_load_lds_dwordx4 v[172:173], off
	s_waitcnt vmcnt(8)
	s_waitcnt lgkmcnt(0)
	s_barrier
	s_waitcnt lgkmcnt(0)
	v_mfma_f32_16x16x32_bf16 v[60:63], v[128:131], v[196:199], v[60:63]
	v_mfma_f32_16x16x32_bf16 v[56:59], v[136:139], v[196:199], v[56:59]
	v_mfma_f32_16x16x32_bf16 v[48:51], v[128:131], v[204:207], v[48:51]
	v_mfma_f32_16x16x32_bf16 v[44:47], v[136:139], v[204:207], v[44:47]
	v_mfma_f32_16x16x32_bf16 v[32:35], v[128:131], v[212:215], v[32:35]
	v_mfma_f32_16x16x32_bf16 v[28:31], v[136:139], v[212:215], v[28:31]
	v_mfma_f32_16x16x32_bf16 v[16:19], v[128:131], v[220:223], v[16:19]
	v_mfma_f32_16x16x32_bf16 v[12:15], v[136:139], v[220:223], v[12:15]
	v_mfma_f32_16x16x32_bf16 v[60:63], v[132:135], v[200:203], v[60:63]
	v_mfma_f32_16x16x32_bf16 v[56:59], v[140:143], v[200:203], v[56:59]
	v_mfma_f32_16x16x32_bf16 v[48:51], v[132:135], v[208:211], v[48:51]
	v_mfma_f32_16x16x32_bf16 v[44:47], v[140:143], v[208:211], v[44:47]
	v_mfma_f32_16x16x32_bf16 v[32:35], v[132:135], v[216:219], v[32:35]
	v_mfma_f32_16x16x32_bf16 v[28:31], v[140:143], v[216:219], v[28:31]
	v_mfma_f32_16x16x32_bf16 v[16:19], v[132:135], v[224:227], v[16:19]
	v_mfma_f32_16x16x32_bf16 v[12:15], v[140:143], v[224:227], v[12:15]
	v_mfma_f32_16x16x32_bf16 v[52:55], v[180:183], v[196:199], v[52:55]
	v_mfma_f32_16x16x32_bf16 v[40:43], v[188:191], v[196:199], v[40:43]
	v_mfma_f32_16x16x32_bf16 v[36:39], v[180:183], v[204:207], v[36:39]
	v_mfma_f32_16x16x32_bf16 v[24:27], v[188:191], v[204:207], v[24:27]
	v_mfma_f32_16x16x32_bf16 v[20:23], v[180:183], v[212:215], v[20:23]
	v_mfma_f32_16x16x32_bf16 v[8:11], v[188:191], v[212:215], v[8:11]
	v_mfma_f32_16x16x32_bf16 v[4:7], v[180:183], v[220:223], v[4:7]
	v_mfma_f32_16x16x32_bf16 v[0:3], v[188:191], v[220:223], v[0:3]
	v_mfma_f32_16x16x32_bf16 v[52:55], v[184:187], v[200:203], v[52:55]
	v_mfma_f32_16x16x32_bf16 v[40:43], v[192:195], v[200:203], v[40:43]
	v_mfma_f32_16x16x32_bf16 v[36:39], v[184:187], v[208:211], v[36:39]
	v_mfma_f32_16x16x32_bf16 v[24:27], v[192:195], v[208:211], v[24:27]
	v_mfma_f32_16x16x32_bf16 v[20:23], v[184:187], v[216:219], v[20:23]
	v_mfma_f32_16x16x32_bf16 v[8:11], v[192:195], v[216:219], v[8:11]
	v_mfma_f32_16x16x32_bf16 v[4:7], v[184:187], v[224:227], v[4:7]
	v_mfma_f32_16x16x32_bf16 v[0:3], v[192:195], v[224:227], v[0:3]
	s_barrier
	s_add_i32 s50, s50, 2
	s_add_u32 s6, s6, 0x100
	s_addc_u32 s17, s17, 0
	s_cmp_gt_u32 s50, 41
	s_mov_b64 s[20:21], s[22:23]
	s_cbranch_scc0 .LBB0_2014
	s_and_b64 vcc, exec, s[12:13]
	s_cbranch_vccz .LBB0_2017
	s_barrier
